# v47 + sc1 (write-through) on all GEMM epilogue stores so the grid barrier's L2 write-back has nothing to flush
# baseline (speedup 1.0000x reference)
.LBB0_269:
	ds_read_b32 v174, v186
	s_lshl_b32 s0, s44, 7
	s_addk_i32 s0, 0xfc00
	s_waitcnt lgkmcnt(0)
	v_cvt_f32_u32_e32 v174, v174
	v_fmamk_f32 v174, v174, 0x35000000, v232
	v_rsq_f32_e32 v174, v174
	s_nop 0
	v_pk_fma_f32 v[188:189], v[126:127], v[174:175], v[144:145] op_sel_hi:[1,0,1]
	v_pk_fma_f32 v[190:191], v[128:129], v[174:175], v[142:143] op_sel_hi:[1,0,1]
	v_pk_fma_f32 v[192:193], v[118:119], v[174:175], v[154:155] op_sel_hi:[1,0,1]
	v_pk_fma_f32 v[204:205], v[120:121], v[174:175], v[152:153] op_sel_hi:[1,0,1]
	v_pk_fma_f32 v[206:207], v[122:123], v[174:175], v[148:149] op_sel_hi:[1,0,1]
	v_pk_fma_f32 v[208:209], v[124:125], v[174:175], v[146:147] op_sel_hi:[1,0,1]
	v_pk_fma_f32 v[210:211], v[114:115], v[174:175], v[156:157] op_sel_hi:[1,0,1]
	v_pk_fma_f32 v[174:175], v[116:117], v[174:175], v[150:151] op_sel_hi:[1,0,1]
	v_pk_mul_f32 v[190:191], v[190:191], v[204:205]
	v_pk_mul_f32 v[188:189], v[188:189], v[192:193]
	v_pk_mul_f32 v[174:175], v[208:209], v[174:175]
	v_pk_mul_f32 v[192:193], v[206:207], v[210:211]
	v_cvt_pk_bf16_f32 v188, v188, v189
	v_cvt_pk_bf16_f32 v189, v190, v191
	s_nop 0
	v_cvt_pk_bf16_f32 v190, v192, v193
	v_cvt_pk_bf16_f32 v191, v174, v175
	v_lshl_add_u32 v174, v185, 2, s59
	ds_read_b32 v174, v174
	v_lshl_or_b32 v175, v184, 3, s0
	v_or_b32_e32 v194, s33, v175
	s_waitcnt lgkmcnt(0)
	v_cvt_f32_u32_e32 v187, v174
	v_lshlrev_b64 v[174:175], 12, v[172:173]
	v_lshl_add_u64 v[192:193], s[12:13], 0, v[174:175]
	v_fmamk_f32 v174, v187, 0x35000000, v232
	v_rsq_f32_e32 v204, v174
	v_lshlrev_b64 v[174:175], 1, v[194:195]
	v_lshl_add_u64 v[192:193], v[192:193], 0, v[174:175]
	global_store_dwordx4 v[192:193], v[188:191], off sc1
	v_pk_fma_f32 v[192:193], v[102:103], v[204:205], v[154:155] op_sel_hi:[1,0,1]
	v_pk_fma_f32 v[206:207], v[104:105], v[204:205], v[152:153] op_sel_hi:[1,0,1]
	v_pk_fma_f32 v[188:189], v[110:111], v[204:205], v[144:145] op_sel_hi:[1,0,1]
	v_pk_fma_f32 v[190:191], v[112:113], v[204:205], v[142:143] op_sel_hi:[1,0,1]
	v_pk_mul_f32 v[188:189], v[188:189], v[192:193]
	v_pk_mul_f32 v[190:191], v[190:191], v[206:207]
	v_pk_fma_f32 v[192:193], v[106:107], v[204:205], v[148:149] op_sel_hi:[1,0,1]
	v_pk_fma_f32 v[206:207], v[108:109], v[204:205], v[146:147] op_sel_hi:[1,0,1]
	v_pk_fma_f32 v[208:209], v[98:99], v[204:205], v[156:157] op_sel_hi:[1,0,1]
	v_pk_fma_f32 v[204:205], v[100:101], v[204:205], v[150:151] op_sel_hi:[1,0,1]
	v_lshl_add_u32 v187, v183, 2, s59
	v_pk_mul_f32 v[204:205], v[206:207], v[204:205]
	v_pk_mul_f32 v[192:193], v[192:193], v[208:209]
	v_cvt_pk_bf16_f32 v188, v188, v189
	v_cvt_pk_bf16_f32 v189, v190, v191
	s_nop 0
	v_cvt_pk_bf16_f32 v190, v192, v193
	v_cvt_pk_bf16_f32 v191, v204, v205
	ds_read_b32 v187, v187
	v_lshlrev_b64 v[192:193], 12, v[170:171]
	v_lshl_add_u64 v[192:193], s[12:13], 0, v[192:193]
	v_lshl_add_u64 v[192:193], v[192:193], 0, v[174:175]
	global_store_dwordx4 v[192:193], v[188:191], off sc1
	s_waitcnt lgkmcnt(0)
	v_cvt_f32_u32_e32 v187, v187
	v_fmamk_f32 v187, v187, 0x35000000, v232
	v_rsq_f32_e32 v194, v187
	v_lshl_add_u32 v187, v182, 2, s59
	v_pk_fma_f32 v[188:189], v[94:95], v[194:195], v[144:145] op_sel_hi:[1,0,1]
	v_pk_fma_f32 v[190:191], v[96:97], v[194:195], v[142:143] op_sel_hi:[1,0,1]
	v_pk_fma_f32 v[192:193], v[86:87], v[194:195], v[154:155] op_sel_hi:[1,0,1]
	v_pk_fma_f32 v[204:205], v[88:89], v[194:195], v[152:153] op_sel_hi:[1,0,1]
	v_pk_mul_f32 v[188:189], v[188:189], v[192:193]
	v_pk_mul_f32 v[190:191], v[190:191], v[204:205]
	v_pk_fma_f32 v[192:193], v[90:91], v[194:195], v[148:149] op_sel_hi:[1,0,1]
	v_pk_fma_f32 v[204:205], v[92:93], v[194:195], v[146:147] op_sel_hi:[1,0,1]
	v_pk_fma_f32 v[206:207], v[82:83], v[194:195], v[156:157] op_sel_hi:[1,0,1]
	v_pk_fma_f32 v[208:209], v[84:85], v[194:195], v[150:151] op_sel_hi:[1,0,1]
	v_pk_mul_f32 v[192:193], v[192:193], v[206:207]
	v_pk_mul_f32 v[204:205], v[204:205], v[208:209]
	v_cvt_pk_bf16_f32 v188, v188, v189
	v_cvt_pk_bf16_f32 v189, v190, v191
	v_cvt_pk_bf16_f32 v190, v192, v193
	v_lshlrev_b64 v[192:193], 12, v[168:169]
	v_cvt_pk_bf16_f32 v191, v204, v205
	ds_read_b32 v187, v187
	v_lshl_add_u64 v[192:193], s[12:13], 0, v[192:193]
	v_lshl_add_u64 v[192:193], v[192:193], 0, v[174:175]
	global_store_dwordx4 v[192:193], v[188:191], off sc1
	s_waitcnt lgkmcnt(0)
	v_cvt_f32_u32_e32 v187, v187
	v_fmamk_f32 v187, v187, 0x35000000, v232
	v_rsq_f32_e32 v194, v187
	v_lshl_add_u32 v187, v181, 2, s59
	v_pk_fma_f32 v[188:189], v[78:79], v[194:195], v[144:145] op_sel_hi:[1,0,1]
	v_pk_fma_f32 v[190:191], v[80:81], v[194:195], v[142:143] op_sel_hi:[1,0,1]
	v_pk_fma_f32 v[192:193], v[70:71], v[194:195], v[154:155] op_sel_hi:[1,0,1]
	v_pk_fma_f32 v[204:205], v[72:73], v[194:195], v[152:153] op_sel_hi:[1,0,1]
	v_pk_mul_f32 v[188:189], v[188:189], v[192:193]
	v_pk_mul_f32 v[190:191], v[190:191], v[204:205]
	v_pk_fma_f32 v[192:193], v[74:75], v[194:195], v[148:149] op_sel_hi:[1,0,1]
	v_pk_fma_f32 v[204:205], v[76:77], v[194:195], v[146:147] op_sel_hi:[1,0,1]
	v_pk_fma_f32 v[206:207], v[66:67], v[194:195], v[156:157] op_sel_hi:[1,0,1]
	v_pk_fma_f32 v[208:209], v[68:69], v[194:195], v[150:151] op_sel_hi:[1,0,1]
	v_pk_mul_f32 v[192:193], v[192:193], v[206:207]
	v_pk_mul_f32 v[204:205], v[204:205], v[208:209]
	v_cvt_pk_bf16_f32 v188, v188, v189
	v_cvt_pk_bf16_f32 v189, v190, v191
	v_cvt_pk_bf16_f32 v190, v192, v193
	v_lshlrev_b64 v[192:193], 12, v[166:167]
	v_cvt_pk_bf16_f32 v191, v204, v205
	ds_read_b32 v187, v187
	v_lshl_add_u64 v[192:193], s[12:13], 0, v[192:193]
	v_lshl_add_u64 v[192:193], v[192:193], 0, v[174:175]
	global_store_dwordx4 v[192:193], v[188:191], off sc1
	s_waitcnt lgkmcnt(0)
	v_cvt_f32_u32_e32 v187, v187
	v_fmamk_f32 v187, v187, 0x35000000, v232
	v_rsq_f32_e32 v194, v187
	v_lshl_add_u32 v187, v180, 2, s59
	v_pk_fma_f32 v[188:189], v[62:63], v[194:195], v[144:145] op_sel_hi:[1,0,1]
	v_pk_fma_f32 v[190:191], v[64:65], v[194:195], v[142:143] op_sel_hi:[1,0,1]
	v_pk_fma_f32 v[192:193], v[54:55], v[194:195], v[154:155] op_sel_hi:[1,0,1]
	v_pk_fma_f32 v[204:205], v[56:57], v[194:195], v[152:153] op_sel_hi:[1,0,1]
	v_pk_mul_f32 v[188:189], v[188:189], v[192:193]
	v_pk_mul_f32 v[190:191], v[190:191], v[204:205]
	v_pk_fma_f32 v[192:193], v[58:59], v[194:195], v[148:149] op_sel_hi:[1,0,1]
	v_pk_fma_f32 v[204:205], v[60:61], v[194:195], v[146:147] op_sel_hi:[1,0,1]
	v_pk_fma_f32 v[206:207], v[50:51], v[194:195], v[156:157] op_sel_hi:[1,0,1]
	v_pk_fma_f32 v[208:209], v[52:53], v[194:195], v[150:151] op_sel_hi:[1,0,1]
	v_pk_mul_f32 v[192:193], v[192:193], v[206:207]
	v_pk_mul_f32 v[204:205], v[204:205], v[208:209]
	v_cvt_pk_bf16_f32 v188, v188, v189
	v_cvt_pk_bf16_f32 v189, v190, v191
	v_cvt_pk_bf16_f32 v190, v192, v193
	v_lshlrev_b64 v[192:193], 12, v[164:165]
	v_cvt_pk_bf16_f32 v191, v204, v205
	ds_read_b32 v187, v187
	v_lshl_add_u64 v[192:193], s[12:13], 0, v[192:193]
	v_lshl_add_u64 v[192:193], v[192:193], 0, v[174:175]
	global_store_dwordx4 v[192:193], v[188:191], off sc1
	s_waitcnt lgkmcnt(0)
	v_cvt_f32_u32_e32 v187, v187
	v_fmamk_f32 v187, v187, 0x35000000, v232
	v_rsq_f32_e32 v194, v187
	v_lshl_add_u32 v187, v179, 2, s59
	v_pk_fma_f32 v[188:189], v[46:47], v[194:195], v[144:145] op_sel_hi:[1,0,1]
	v_pk_fma_f32 v[190:191], v[48:49], v[194:195], v[142:143] op_sel_hi:[1,0,1]
	v_pk_fma_f32 v[192:193], v[38:39], v[194:195], v[154:155] op_sel_hi:[1,0,1]
	v_pk_fma_f32 v[204:205], v[40:41], v[194:195], v[152:153] op_sel_hi:[1,0,1]
	v_pk_mul_f32 v[188:189], v[188:189], v[192:193]
	v_pk_mul_f32 v[190:191], v[190:191], v[204:205]
	v_pk_fma_f32 v[192:193], v[42:43], v[194:195], v[148:149] op_sel_hi:[1,0,1]
	v_pk_fma_f32 v[204:205], v[44:45], v[194:195], v[146:147] op_sel_hi:[1,0,1]
	v_pk_fma_f32 v[206:207], v[34:35], v[194:195], v[156:157] op_sel_hi:[1,0,1]
	v_pk_fma_f32 v[208:209], v[36:37], v[194:195], v[150:151] op_sel_hi:[1,0,1]
	v_pk_mul_f32 v[192:193], v[192:193], v[206:207]
	v_pk_mul_f32 v[204:205], v[204:205], v[208:209]
	v_cvt_pk_bf16_f32 v188, v188, v189
	v_cvt_pk_bf16_f32 v189, v190, v191
	v_cvt_pk_bf16_f32 v190, v192, v193
	v_lshlrev_b64 v[192:193], 12, v[162:163]
	v_cvt_pk_bf16_f32 v191, v204, v205
	ds_read_b32 v187, v187
	v_lshl_add_u64 v[192:193], s[12:13], 0, v[192:193]
	v_lshl_add_u64 v[192:193], v[192:193], 0, v[174:175]
	global_store_dwordx4 v[192:193], v[188:191], off sc1
	s_waitcnt lgkmcnt(0)
	v_cvt_f32_u32_e32 v187, v187
	v_fmamk_f32 v187, v187, 0x35000000, v232
	v_rsq_f32_e32 v194, v187
	v_lshl_add_u32 v187, v178, 2, s59
	v_pk_fma_f32 v[188:189], v[30:31], v[194:195], v[144:145] op_sel_hi:[1,0,1]
	v_pk_fma_f32 v[190:191], v[32:33], v[194:195], v[142:143] op_sel_hi:[1,0,1]
	v_pk_fma_f32 v[192:193], v[22:23], v[194:195], v[154:155] op_sel_hi:[1,0,1]
	v_pk_fma_f32 v[204:205], v[24:25], v[194:195], v[152:153] op_sel_hi:[1,0,1]
	v_pk_mul_f32 v[188:189], v[188:189], v[192:193]
	v_pk_mul_f32 v[190:191], v[190:191], v[204:205]
	v_pk_fma_f32 v[192:193], v[26:27], v[194:195], v[148:149] op_sel_hi:[1,0,1]
	v_pk_fma_f32 v[204:205], v[28:29], v[194:195], v[146:147] op_sel_hi:[1,0,1]
	v_pk_fma_f32 v[206:207], v[18:19], v[194:195], v[156:157] op_sel_hi:[1,0,1]
	v_pk_fma_f32 v[208:209], v[20:21], v[194:195], v[150:151] op_sel_hi:[1,0,1]
	v_pk_mul_f32 v[192:193], v[192:193], v[206:207]
	v_pk_mul_f32 v[204:205], v[204:205], v[208:209]
	v_cvt_pk_bf16_f32 v188, v188, v189
	v_cvt_pk_bf16_f32 v189, v190, v191
	v_cvt_pk_bf16_f32 v190, v192, v193
	v_lshlrev_b64 v[192:193], 12, v[160:161]
	v_cvt_pk_bf16_f32 v191, v204, v205
	ds_read_b32 v187, v187
	v_lshl_add_u64 v[192:193], s[12:13], 0, v[192:193]
	v_lshl_add_u64 v[192:193], v[192:193], 0, v[174:175]
	global_store_dwordx4 v[192:193], v[188:191], off sc1
	s_waitcnt lgkmcnt(0)
	v_cvt_f32_u32_e32 v187, v187
	v_lshlrev_b64 v[190:191], 12, v[158:159]
	v_lshl_add_u64 v[190:191], s[12:13], 0, v[190:191]
	v_lshl_add_u64 v[174:175], v[190:191], 0, v[174:175]
	v_fmamk_f32 v187, v187, 0x35000000, v232
	v_rsq_f32_e32 v188, v187
	s_nop 0
	v_pk_fma_f32 v[190:191], v[14:15], v[188:189], v[144:145] op_sel_hi:[1,0,1]
	v_pk_fma_f32 v[192:193], v[16:17], v[188:189], v[142:143] op_sel_hi:[1,0,1]
	v_pk_fma_f32 v[204:205], v[6:7], v[188:189], v[154:155] op_sel_hi:[1,0,1]
	v_pk_fma_f32 v[206:207], v[8:9], v[188:189], v[152:153] op_sel_hi:[1,0,1]
	v_pk_mul_f32 v[190:191], v[190:191], v[204:205]
	v_pk_mul_f32 v[192:193], v[192:193], v[206:207]
	v_pk_fma_f32 v[204:205], v[10:11], v[188:189], v[148:149] op_sel_hi:[1,0,1]
	v_pk_fma_f32 v[206:207], v[12:13], v[188:189], v[146:147] op_sel_hi:[1,0,1]
	v_pk_fma_f32 v[208:209], v[2:3], v[188:189], v[156:157] op_sel_hi:[1,0,1]
	v_pk_fma_f32 v[188:189], v[4:5], v[188:189], v[150:151] op_sel_hi:[1,0,1]
	v_pk_mul_f32 v[204:205], v[204:205], v[208:209]
	v_pk_mul_f32 v[206:207], v[206:207], v[188:189]
	v_cvt_pk_bf16_f32 v188, v190, v191
	v_cvt_pk_bf16_f32 v189, v192, v193
	v_cvt_pk_bf16_f32 v190, v204, v205
	s_nop 0
	v_cvt_pk_bf16_f32 v191, v206, v207
	global_store_dwordx4 v[174:175], v[188:191], off sc1
	s_cbranch_execnz .LBB0_268
.LBB0_270:
	ds_read_b32 v174, v186
	v_lshl_or_b32 v175, v184, 3, s90
	v_lshlrev_b64 v[172:173], 12, v[172:173]
	v_lshl_add_u64 v[186:187], s[52:53], 0, v[172:173]
	s_waitcnt lgkmcnt(0)
	v_cvt_f32_u32_e32 v184, v174
	v_or_b32_e32 v174, s33, v175
	v_ashrrev_i32_e32 v175, 31, v174
	v_fmamk_f32 v172, v184, 0x35000000, v232
	v_rsq_f32_e32 v184, v172
	v_lshlrev_b64 v[172:173], 1, v[174:175]
	v_lshl_add_u64 v[174:175], v[186:187], 0, v[172:173]
	v_pk_fma_f32 v[128:129], v[128:129], v[184:185], v[142:143] op_sel_hi:[1,0,1]
	v_pk_fma_f32 v[126:127], v[126:127], v[184:185], v[144:145] op_sel_hi:[1,0,1]
	v_pk_fma_f32 v[186:187], v[124:125], v[184:185], v[146:147] op_sel_hi:[1,0,1]
	v_pk_fma_f32 v[124:125], v[122:123], v[184:185], v[148:149] op_sel_hi:[1,0,1]
	v_cvt_pk_bf16_f32 v122, v126, v127
	v_cvt_pk_bf16_f32 v123, v128, v129
	v_pk_fma_f32 v[118:119], v[118:119], v[184:185], v[154:155] op_sel_hi:[1,0,1]
	v_cvt_pk_bf16_f32 v124, v124, v125
	v_cvt_pk_bf16_f32 v125, v186, v187
	global_store_dwordx4 v[174:175], v[122:125], off sc1
	v_pk_fma_f32 v[120:121], v[120:121], v[184:185], v[152:153] op_sel_hi:[1,0,1]
	s_nop 0
	v_pk_fma_f32 v[122:123], v[116:117], v[184:185], v[150:151] op_sel_hi:[1,0,1]
	v_pk_fma_f32 v[116:117], v[114:115], v[184:185], v[156:157] op_sel_hi:[1,0,1]
	v_cvt_pk_bf16_f32 v114, v118, v119
	v_lshl_add_u32 v118, v185, 2, s59
	v_cvt_pk_bf16_f32 v115, v120, v121
	v_cvt_pk_bf16_f32 v116, v116, v117
	v_cvt_pk_bf16_f32 v117, v122, v123
	ds_read_b32 v118, v118
	global_store_dwordx4 v[174:175], v[114:117], off offset:256 sc1
	s_waitcnt lgkmcnt(0)
	v_cvt_f32_u32_e32 v118, v118
	v_lshlrev_b64 v[116:117], 12, v[170:171]
	v_lshl_add_u64 v[116:117], s[52:53], 0, v[116:117]
	v_lshl_add_u64 v[116:117], v[116:117], 0, v[172:173]
	v_fmamk_f32 v114, v118, 0x35000000, v232
	v_rsq_f32_e32 v114, v114
	s_nop 0
	v_pk_fma_f32 v[112:113], v[112:113], v[114:115], v[142:143] op_sel_hi:[1,0,1]
	v_pk_fma_f32 v[110:111], v[110:111], v[114:115], v[144:145] op_sel_hi:[1,0,1]
	v_pk_fma_f32 v[118:119], v[108:109], v[114:115], v[146:147] op_sel_hi:[1,0,1]
	v_pk_fma_f32 v[108:109], v[106:107], v[114:115], v[148:149] op_sel_hi:[1,0,1]
	v_cvt_pk_bf16_f32 v106, v110, v111
	v_cvt_pk_bf16_f32 v107, v112, v113
	v_pk_fma_f32 v[102:103], v[102:103], v[114:115], v[154:155] op_sel_hi:[1,0,1]
	v_cvt_pk_bf16_f32 v108, v108, v109
	v_cvt_pk_bf16_f32 v109, v118, v119
	global_store_dwordx4 v[116:117], v[106:109], off sc1
	v_pk_fma_f32 v[104:105], v[104:105], v[114:115], v[152:153] op_sel_hi:[1,0,1]
	s_nop 0
	v_pk_fma_f32 v[106:107], v[100:101], v[114:115], v[150:151] op_sel_hi:[1,0,1]
	v_pk_fma_f32 v[100:101], v[98:99], v[114:115], v[156:157] op_sel_hi:[1,0,1]
	v_cvt_pk_bf16_f32 v98, v102, v103
	v_lshl_add_u32 v102, v183, 2, s59
	v_cvt_pk_bf16_f32 v99, v104, v105
	v_cvt_pk_bf16_f32 v100, v100, v101
	v_cvt_pk_bf16_f32 v101, v106, v107
	ds_read_b32 v102, v102
	global_store_dwordx4 v[116:117], v[98:101], off offset:256 sc1
	s_waitcnt lgkmcnt(0)
	v_cvt_f32_u32_e32 v102, v102
	v_lshlrev_b64 v[100:101], 12, v[168:169]
	v_lshl_add_u64 v[100:101], s[52:53], 0, v[100:101]
	v_lshl_add_u64 v[100:101], v[100:101], 0, v[172:173]
	v_fmamk_f32 v98, v102, 0x35000000, v232
	v_rsq_f32_e32 v98, v98
	s_nop 0
	v_pk_fma_f32 v[96:97], v[96:97], v[98:99], v[142:143] op_sel_hi:[1,0,1]
	v_pk_fma_f32 v[94:95], v[94:95], v[98:99], v[144:145] op_sel_hi:[1,0,1]
	v_pk_fma_f32 v[102:103], v[92:93], v[98:99], v[146:147] op_sel_hi:[1,0,1]
	v_pk_fma_f32 v[92:93], v[90:91], v[98:99], v[148:149] op_sel_hi:[1,0,1]
	v_cvt_pk_bf16_f32 v90, v94, v95
	v_cvt_pk_bf16_f32 v91, v96, v97
	v_pk_fma_f32 v[86:87], v[86:87], v[98:99], v[154:155] op_sel_hi:[1,0,1]
	v_cvt_pk_bf16_f32 v92, v92, v93
	v_cvt_pk_bf16_f32 v93, v102, v103
	global_store_dwordx4 v[100:101], v[90:93], off sc1
	v_pk_fma_f32 v[88:89], v[88:89], v[98:99], v[152:153] op_sel_hi:[1,0,1]
	s_nop 0
	v_pk_fma_f32 v[90:91], v[84:85], v[98:99], v[150:151] op_sel_hi:[1,0,1]
	v_pk_fma_f32 v[84:85], v[82:83], v[98:99], v[156:157] op_sel_hi:[1,0,1]
	v_cvt_pk_bf16_f32 v82, v86, v87
	v_lshl_add_u32 v86, v182, 2, s59
	v_cvt_pk_bf16_f32 v83, v88, v89
	v_cvt_pk_bf16_f32 v84, v84, v85
	v_cvt_pk_bf16_f32 v85, v90, v91
	ds_read_b32 v86, v86
	global_store_dwordx4 v[100:101], v[82:85], off offset:256 sc1
	s_waitcnt lgkmcnt(0)
	v_cvt_f32_u32_e32 v86, v86
	v_lshlrev_b64 v[84:85], 12, v[166:167]
	v_lshl_add_u64 v[84:85], s[52:53], 0, v[84:85]
	v_lshl_add_u64 v[84:85], v[84:85], 0, v[172:173]
	v_fmamk_f32 v82, v86, 0x35000000, v232
	v_rsq_f32_e32 v82, v82
	s_nop 0
	v_pk_fma_f32 v[80:81], v[80:81], v[82:83], v[142:143] op_sel_hi:[1,0,1]
	v_pk_fma_f32 v[78:79], v[78:79], v[82:83], v[144:145] op_sel_hi:[1,0,1]
	v_pk_fma_f32 v[86:87], v[76:77], v[82:83], v[146:147] op_sel_hi:[1,0,1]
	v_pk_fma_f32 v[76:77], v[74:75], v[82:83], v[148:149] op_sel_hi:[1,0,1]
	v_cvt_pk_bf16_f32 v74, v78, v79
	v_cvt_pk_bf16_f32 v75, v80, v81
	v_pk_fma_f32 v[70:71], v[70:71], v[82:83], v[154:155] op_sel_hi:[1,0,1]
	v_cvt_pk_bf16_f32 v76, v76, v77
	v_cvt_pk_bf16_f32 v77, v86, v87
	global_store_dwordx4 v[84:85], v[74:77], off sc1
	v_pk_fma_f32 v[72:73], v[72:73], v[82:83], v[152:153] op_sel_hi:[1,0,1]
	s_nop 0
	v_pk_fma_f32 v[74:75], v[68:69], v[82:83], v[150:151] op_sel_hi:[1,0,1]
	v_pk_fma_f32 v[68:69], v[66:67], v[82:83], v[156:157] op_sel_hi:[1,0,1]
	v_cvt_pk_bf16_f32 v66, v70, v71
	v_lshl_add_u32 v70, v181, 2, s59
	v_cvt_pk_bf16_f32 v67, v72, v73
	v_cvt_pk_bf16_f32 v68, v68, v69
	v_cvt_pk_bf16_f32 v69, v74, v75
	ds_read_b32 v70, v70
	global_store_dwordx4 v[84:85], v[66:69], off offset:256 sc1
	s_waitcnt lgkmcnt(0)
	v_cvt_f32_u32_e32 v70, v70
	v_lshlrev_b64 v[68:69], 12, v[164:165]
	v_lshl_add_u64 v[68:69], s[52:53], 0, v[68:69]
	v_lshl_add_u64 v[68:69], v[68:69], 0, v[172:173]
	v_fmamk_f32 v66, v70, 0x35000000, v232
	v_rsq_f32_e32 v66, v66
	s_nop 0
	v_pk_fma_f32 v[64:65], v[64:65], v[66:67], v[142:143] op_sel_hi:[1,0,1]
	v_pk_fma_f32 v[62:63], v[62:63], v[66:67], v[144:145] op_sel_hi:[1,0,1]
	v_pk_fma_f32 v[70:71], v[60:61], v[66:67], v[146:147] op_sel_hi:[1,0,1]
	v_pk_fma_f32 v[60:61], v[58:59], v[66:67], v[148:149] op_sel_hi:[1,0,1]
	v_cvt_pk_bf16_f32 v58, v62, v63
	v_cvt_pk_bf16_f32 v59, v64, v65
	v_pk_fma_f32 v[54:55], v[54:55], v[66:67], v[154:155] op_sel_hi:[1,0,1]
	v_cvt_pk_bf16_f32 v60, v60, v61
	v_cvt_pk_bf16_f32 v61, v70, v71
	global_store_dwordx4 v[68:69], v[58:61], off sc1
	v_pk_fma_f32 v[56:57], v[56:57], v[66:67], v[152:153] op_sel_hi:[1,0,1]
	s_nop 0
	v_pk_fma_f32 v[58:59], v[52:53], v[66:67], v[150:151] op_sel_hi:[1,0,1]
	v_pk_fma_f32 v[52:53], v[50:51], v[66:67], v[156:157] op_sel_hi:[1,0,1]
	v_cvt_pk_bf16_f32 v50, v54, v55
	v_lshl_add_u32 v54, v180, 2, s59
	v_cvt_pk_bf16_f32 v51, v56, v57
	v_cvt_pk_bf16_f32 v52, v52, v53
	v_cvt_pk_bf16_f32 v53, v58, v59
	ds_read_b32 v54, v54
	global_store_dwordx4 v[68:69], v[50:53], off offset:256 sc1
	s_waitcnt lgkmcnt(0)
	v_cvt_f32_u32_e32 v54, v54
	v_lshlrev_b64 v[52:53], 12, v[162:163]
	v_lshl_add_u64 v[52:53], s[52:53], 0, v[52:53]
	v_lshl_add_u64 v[52:53], v[52:53], 0, v[172:173]
	v_fmamk_f32 v50, v54, 0x35000000, v232
	v_rsq_f32_e32 v50, v50
	s_nop 0
	v_pk_fma_f32 v[48:49], v[48:49], v[50:51], v[142:143] op_sel_hi:[1,0,1]
	v_pk_fma_f32 v[46:47], v[46:47], v[50:51], v[144:145] op_sel_hi:[1,0,1]
	v_pk_fma_f32 v[54:55], v[44:45], v[50:51], v[146:147] op_sel_hi:[1,0,1]
	v_pk_fma_f32 v[44:45], v[42:43], v[50:51], v[148:149] op_sel_hi:[1,0,1]
	v_cvt_pk_bf16_f32 v42, v46, v47
	v_cvt_pk_bf16_f32 v43, v48, v49
	v_pk_fma_f32 v[38:39], v[38:39], v[50:51], v[154:155] op_sel_hi:[1,0,1]
	v_cvt_pk_bf16_f32 v44, v44, v45
	v_cvt_pk_bf16_f32 v45, v54, v55
	global_store_dwordx4 v[52:53], v[42:45], off sc1
	v_pk_fma_f32 v[40:41], v[40:41], v[50:51], v[152:153] op_sel_hi:[1,0,1]
	s_nop 0
	v_pk_fma_f32 v[42:43], v[36:37], v[50:51], v[150:151] op_sel_hi:[1,0,1]
	v_pk_fma_f32 v[36:37], v[34:35], v[50:51], v[156:157] op_sel_hi:[1,0,1]
	v_cvt_pk_bf16_f32 v34, v38, v39
	v_lshl_add_u32 v38, v179, 2, s59
	v_cvt_pk_bf16_f32 v35, v40, v41
	v_cvt_pk_bf16_f32 v36, v36, v37
	v_cvt_pk_bf16_f32 v37, v42, v43
	ds_read_b32 v38, v38
	global_store_dwordx4 v[52:53], v[34:37], off offset:256 sc1
	s_waitcnt lgkmcnt(0)
	v_cvt_f32_u32_e32 v38, v38
	v_lshlrev_b64 v[36:37], 12, v[160:161]
	v_lshl_add_u64 v[36:37], s[52:53], 0, v[36:37]
	v_lshl_add_u64 v[36:37], v[36:37], 0, v[172:173]
	v_fmamk_f32 v34, v38, 0x35000000, v232
	v_rsq_f32_e32 v34, v34
	s_nop 0
	v_pk_fma_f32 v[32:33], v[32:33], v[34:35], v[142:143] op_sel_hi:[1,0,1]
	v_pk_fma_f32 v[30:31], v[30:31], v[34:35], v[144:145] op_sel_hi:[1,0,1]
	v_pk_fma_f32 v[38:39], v[28:29], v[34:35], v[146:147] op_sel_hi:[1,0,1]
	v_pk_fma_f32 v[28:29], v[26:27], v[34:35], v[148:149] op_sel_hi:[1,0,1]
	v_cvt_pk_bf16_f32 v26, v30, v31
	v_cvt_pk_bf16_f32 v27, v32, v33
	v_pk_fma_f32 v[22:23], v[22:23], v[34:35], v[154:155] op_sel_hi:[1,0,1]
	v_cvt_pk_bf16_f32 v28, v28, v29
	v_cvt_pk_bf16_f32 v29, v38, v39
	global_store_dwordx4 v[36:37], v[26:29], off sc1
	v_pk_fma_f32 v[24:25], v[24:25], v[34:35], v[152:153] op_sel_hi:[1,0,1]
	s_nop 0
	v_pk_fma_f32 v[26:27], v[20:21], v[34:35], v[150:151] op_sel_hi:[1,0,1]
	v_pk_fma_f32 v[20:21], v[18:19], v[34:35], v[156:157] op_sel_hi:[1,0,1]
	v_cvt_pk_bf16_f32 v18, v22, v23
	v_lshl_add_u32 v22, v178, 2, s59
	v_cvt_pk_bf16_f32 v19, v24, v25
	v_cvt_pk_bf16_f32 v20, v20, v21
	v_cvt_pk_bf16_f32 v21, v26, v27
	ds_read_b32 v22, v22
	global_store_dwordx4 v[36:37], v[18:21], off offset:256 sc1
	s_waitcnt lgkmcnt(0)
	v_cvt_f32_u32_e32 v22, v22
	v_lshlrev_b64 v[20:21], 12, v[158:159]
	v_lshl_add_u64 v[20:21], s[52:53], 0, v[20:21]
	v_lshl_add_u64 v[20:21], v[20:21], 0, v[172:173]
	v_fmamk_f32 v18, v22, 0x35000000, v232
	v_rsq_f32_e32 v18, v18
	s_nop 0
	v_pk_fma_f32 v[16:17], v[16:17], v[18:19], v[142:143] op_sel_hi:[1,0,1]
	v_pk_fma_f32 v[14:15], v[14:15], v[18:19], v[144:145] op_sel_hi:[1,0,1]
	v_pk_fma_f32 v[22:23], v[12:13], v[18:19], v[146:147] op_sel_hi:[1,0,1]
	v_pk_fma_f32 v[12:13], v[10:11], v[18:19], v[148:149] op_sel_hi:[1,0,1]
	v_cvt_pk_bf16_f32 v10, v14, v15
	v_cvt_pk_bf16_f32 v11, v16, v17
	v_pk_fma_f32 v[8:9], v[8:9], v[18:19], v[152:153] op_sel_hi:[1,0,1]
	v_cvt_pk_bf16_f32 v12, v12, v13
	v_cvt_pk_bf16_f32 v13, v22, v23
	global_store_dwordx4 v[20:21], v[10:13], off sc1
	v_pk_fma_f32 v[6:7], v[6:7], v[18:19], v[154:155] op_sel_hi:[1,0,1]
	s_nop 0
	v_pk_fma_f32 v[10:11], v[4:5], v[18:19], v[150:151] op_sel_hi:[1,0,1]
	v_pk_fma_f32 v[4:5], v[2:3], v[18:19], v[156:157] op_sel_hi:[1,0,1]
	v_cvt_pk_bf16_f32 v2, v6, v7
	v_cvt_pk_bf16_f32 v3, v8, v9
	s_nop 0
	v_cvt_pk_bf16_f32 v4, v4, v5
	v_cvt_pk_bf16_f32 v5, v10, v11
	global_store_dwordx4 v[20:21], v[2:5], off offset:256 sc1
	s_andn2_b64 vcc, exec, s[4:5]
	s_mov_b64 s[4:5], -1
	s_cbranch_vccnz .LBB0_257

.LBB0_293:
	v_mov_b64_e32 v[130:131], s[52:53]
	v_mov_b32_e32 v193, v195
	v_mad_i64_i32 v[130:131], s[6:7], v190, s66, v[130:131]
	v_lshl_add_u64 v[132:133], v[192:193], 1, v[130:131]
	v_lshl_add_u32 v130, v223, 2, 0
	v_add_u32_e32 v130, 0x24400, v130
	ds_read_b32 v130, v130
	s_cmp_lt_u32 s40, 18
	s_mov_b64 s[6:7], -1
	s_waitcnt lgkmcnt(0)
	v_cvt_f32_u32_e32 v130, v130
	v_fmamk_f32 v130, v130, 0x35000000, v232
	v_rsq_f32_e32 v134, v130
	v_lshlrev_b64 v[130:131], 1, v[192:193]
	v_mov_b32_e32 v135, v134
	v_pk_fma_f32 v[138:139], v[128:129], v[134:135], v[174:175] op_sel_hi:[1,0,1]
	v_pk_fma_f32 v[142:143], v[126:127], v[134:135], v[182:183] op_sel_hi:[1,0,1]
	v_pk_fma_f32 v[136:137], v[124:125], v[134:135], v[186:187] op_sel_hi:[1,0,1]
	v_pk_fma_f32 v[140:141], v[122:123], v[134:135], v[188:189] op_sel_hi:[1,0,1]
	v_pk_fma_f32 v[146:147], v[118:119], v[134:135], v[184:185]
	v_pk_fma_f32 v[144:145], v[114:115], v[134:135], v[180:181]
	s_cbranch_scc1 .LBB0_295
	v_mul_f32_e32 v148, 0x3d372713, v140
	v_mul_f32_e32 v149, 0x3d372713, v141
	v_fma_f32 v148, v140, v148, 1.0
	v_fma_f32 v149, v141, v149, 1.0
	v_mul_f32_e32 v148, v140, v148
	v_mul_f32_e32 v149, v141, v149
	v_mul_f32_e32 v148, 0xc0135761, v148
	v_mul_f32_e32 v149, 0xc0135761, v149
	v_exp_f32_e32 v148, v148
	v_exp_f32_e32 v149, v149
	v_mul_f32_e32 v135, 0x3d372713, v142
	v_fma_f32 v135, v142, v135, 1.0
	v_add_f32_e32 v148, 1.0, v148
	v_add_f32_e32 v149, 1.0, v149
	v_rcp_f32_e32 v148, v148
	v_rcp_f32_e32 v149, v149
	v_mul_f32_e32 v154, 0x3d372713, v139
	v_mul_f32_e32 v135, v142, v135
	v_mul_f32_e32 v150, v140, v148
	v_mul_f32_e32 v148, 0x3d372713, v143
	v_mul_f32_e32 v151, v141, v149
	v_mul_f32_e32 v149, 0x3d372713, v138
	v_fma_f32 v148, v143, v148, 1.0
	v_fma_f32 v149, v138, v149, 1.0
	v_mul_f32_e32 v148, v143, v148
	v_mul_f32_e32 v149, v138, v149
	v_mul_f32_e32 v153, 0x3d372713, v136
	v_fma_f32 v154, v139, v154, 1.0
	v_mul_f32_e32 v155, 0x3d372713, v137
	v_mul_f32_e32 v135, 0xc0135761, v135
	v_mul_f32_e32 v148, 0xc0135761, v148
	v_mul_f32_e32 v149, 0xc0135761, v149
	v_fma_f32 v153, v136, v153, 1.0
	v_mul_f32_e32 v154, v139, v154
	v_fma_f32 v155, v137, v155, 1.0
	v_exp_f32_e32 v135, v135
	v_exp_f32_e32 v148, v148
	v_exp_f32_e32 v149, v149
	v_mul_f32_e32 v153, v136, v153
	v_mul_f32_e32 v154, 0xc0135761, v154
	v_mul_f32_e32 v155, v137, v155
	v_mul_f32_e32 v153, 0xc0135761, v153
	v_exp_f32_e32 v154, v154
	v_mul_f32_e32 v155, 0xc0135761, v155
	v_exp_f32_e32 v153, v153
	v_exp_f32_e32 v155, v155
	v_add_f32_e32 v135, 1.0, v135
	v_add_f32_e32 v148, 1.0, v148
	v_add_f32_e32 v149, 1.0, v149
	v_rcp_f32_e32 v135, v135
	v_rcp_f32_e32 v148, v148
	v_rcp_f32_e32 v149, v149
	v_add_f32_e32 v154, 1.0, v154
	v_add_f32_e32 v153, 1.0, v153
	v_rcp_f32_e32 v154, v154
	v_add_f32_e32 v155, 1.0, v155
	v_rcp_f32_e32 v153, v153
	v_rcp_f32_e32 v155, v155
	v_mul_f32_e32 v135, v142, v135
	v_mul_f32_e32 v148, v143, v148
	v_mul_f32_e32 v149, v138, v149
	v_mul_f32_e32 v154, v139, v154
	v_cvt_pk_bf16_f32 v148, v135, v148
	v_cvt_pk_bf16_f32 v149, v149, v154
	v_mov_b32_e32 v135, v134
	v_mul_f32_e32 v153, v136, v153
	v_mul_f32_e32 v155, v137, v155
	v_cvt_pk_bf16_f32 v150, v150, v151
	v_cvt_pk_bf16_f32 v151, v153, v155
	global_store_dwordx4 v[132:133], v[148:151], off sc1
	v_mul_f32_e32 v154, 0x3d372713, v147
	v_mul_f32_e32 v153, 0x3d372713, v144
	v_pk_fma_f32 v[148:149], v[120:121], v[134:135], v[176:177]
	v_pk_fma_f32 v[150:151], v[116:117], v[134:135], v[178:179]
	v_mul_f32_e32 v156, 0x3d372713, v148
	v_fma_f32 v156, v148, v156, 1.0
	v_mul_f32_e32 v156, v148, v156
	v_mul_f32_e32 v156, 0xc0135761, v156
	v_exp_f32_e32 v156, v156
	v_mul_f32_e32 v135, 0x3d372713, v146
	v_fma_f32 v135, v146, v135, 1.0
	v_fma_f32 v154, v147, v154, 1.0
	v_add_f32_e32 v156, 1.0, v156
	v_rcp_f32_e32 v156, v156
	v_mul_f32_e32 v155, 0x3d372713, v145
	v_mul_f32_e32 v135, v146, v135
	v_fma_f32 v153, v144, v153, 1.0
	v_mul_f32_e32 v156, v148, v156
	v_mul_f32_e32 v148, 0x3d372713, v150
	v_fma_f32 v148, v150, v148, 1.0
	v_mul_f32_e32 v148, v150, v148
	v_mul_f32_e32 v148, 0xc0135761, v148
	v_exp_f32_e32 v148, v148
	v_mul_f32_e32 v154, v147, v154
	v_fma_f32 v155, v145, v155, 1.0
	v_mul_f32_e32 v135, 0xc0135761, v135
	v_add_f32_e32 v148, 1.0, v148
	v_rcp_f32_e32 v148, v148
	v_mul_f32_e32 v153, v144, v153
	v_mul_f32_e32 v154, 0xc0135761, v154
	v_mul_f32_e32 v155, v145, v155
	v_mul_f32_e32 v157, v150, v148
	v_mul_f32_e32 v148, 0x3d372713, v149
	v_fma_f32 v148, v149, v148, 1.0
	v_mul_f32_e32 v148, v149, v148
	v_mul_f32_e32 v148, 0xc0135761, v148
	v_exp_f32_e32 v148, v148
	v_exp_f32_e32 v135, v135
	v_mul_f32_e32 v153, 0xc0135761, v153
	v_exp_f32_e32 v154, v154
	v_add_f32_e32 v148, 1.0, v148
	v_rcp_f32_e32 v148, v148
	v_mul_f32_e32 v155, 0xc0135761, v155
	v_exp_f32_e32 v153, v153
	v_exp_f32_e32 v155, v155
	v_mul_f32_e32 v149, v149, v148
	v_mul_f32_e32 v148, 0x3d372713, v151
	v_fma_f32 v148, v151, v148, 1.0
	v_mul_f32_e32 v148, v151, v148
	v_mul_f32_e32 v148, 0xc0135761, v148
	v_exp_f32_e32 v148, v148
	v_add_f32_e32 v135, 1.0, v135
	v_add_f32_e32 v154, 1.0, v154
	v_rcp_f32_e32 v135, v135
	v_add_f32_e32 v148, 1.0, v148
	v_add_f32_e32 v153, 1.0, v153
	v_rcp_f32_e32 v154, v154
	v_add_f32_e32 v155, 1.0, v155
	v_rcp_f32_e32 v148, v148
	v_rcp_f32_e32 v153, v153
	v_rcp_f32_e32 v155, v155
	v_mul_f32_e32 v135, v146, v135
	v_mul_f32_e32 v154, v147, v154
	v_mul_f32_e32 v151, v151, v148
	v_cvt_pk_bf16_f32 v148, v135, v154
	v_cvt_pk_bf16_f32 v149, v156, v149
	v_mul_f32_e32 v153, v144, v153
	v_mul_f32_e32 v155, v145, v155
	v_cvt_pk_bf16_f32 v150, v153, v155
	v_cvt_pk_bf16_f32 v151, v157, v151
	global_store_dwordx4 v[132:133], v[148:151], off offset:256 sc1
	v_or_b32_e32 v135, 16, v190
	s_nop 0
	v_mov_b64_e32 v[148:149], s[52:53]
	v_mad_i64_i32 v[150:151], s[6:7], v135, s66, v[148:149]
	v_subrev_u32_e32 v135, s21, v135
	v_lshl_add_u32 v135, v135, 2, s59
	ds_read_b32 v135, v135
	v_lshl_add_u64 v[150:151], v[150:151], 0, v[130:131]
	s_waitcnt lgkmcnt(0)
	v_cvt_f32_u32_e32 v135, v135
	v_fmamk_f32 v135, v135, 0x35000000, v232
	v_rsq_f32_e32 v158, v135
	s_nop 0
	v_pk_fma_f32 v[154:155], v[112:113], v[158:159], v[174:175] op_sel_hi:[1,0,1]
	v_pk_fma_f32 v[156:157], v[110:111], v[158:159], v[182:183] op_sel_hi:[1,0,1]
	v_pk_fma_f32 v[160:161], v[108:109], v[158:159], v[186:187] op_sel_hi:[1,0,1]
	v_pk_fma_f32 v[204:205], v[106:107], v[158:159], v[188:189] op_sel_hi:[1,0,1]
	v_mul_f32_e32 v159, 0x3d372713, v154
	v_fma_f32 v159, v154, v159, 1.0
	v_mul_f32_e32 v159, v154, v159
	v_mul_f32_e32 v159, 0xc0135761, v159
	v_exp_f32_e32 v159, v159
	v_mul_f32_e32 v135, 0x3d372713, v156
	v_fma_f32 v135, v156, v135, 1.0
	v_mul_f32_e32 v135, v156, v135
	v_add_f32_e32 v159, 1.0, v159
	v_rcp_f32_e32 v159, v159
	v_mul_f32_e32 v135, 0xc0135761, v135
	v_exp_f32_e32 v135, v135
	v_mul_f32_e32 v153, 0x3d372713, v204
	v_mul_f32_e32 v159, v154, v159
	v_mul_f32_e32 v154, 0x3d372713, v160
	v_fma_f32 v154, v160, v154, 1.0
	v_mul_f32_e32 v154, v160, v154
	v_mul_f32_e32 v154, 0xc0135761, v154
	v_exp_f32_e32 v154, v154
	v_add_f32_e32 v135, 1.0, v135
	v_rcp_f32_e32 v135, v135
	v_fma_f32 v153, v204, v153, 1.0
	v_add_f32_e32 v154, 1.0, v154
	v_rcp_f32_e32 v154, v154
	v_mul_f32_e32 v135, v156, v135
	v_mul_f32_e32 v156, 0x3d372713, v157
	v_fma_f32 v156, v157, v156, 1.0
	v_mul_f32_e32 v160, v160, v154
	v_mul_f32_e32 v154, 0x3d372713, v155
	v_mul_f32_e32 v156, v157, v156
	v_fma_f32 v154, v155, v154, 1.0
	v_mul_f32_e32 v156, 0xc0135761, v156
	v_mul_f32_e32 v154, v155, v154
	v_exp_f32_e32 v156, v156
	v_mul_f32_e32 v154, 0xc0135761, v154
	v_exp_f32_e32 v154, v154
	v_mul_f32_e32 v153, v204, v153
	v_add_f32_e32 v156, 1.0, v156
	v_rcp_f32_e32 v156, v156
	v_add_f32_e32 v154, 1.0, v154
	v_rcp_f32_e32 v154, v154
	v_mul_f32_e32 v153, 0xc0135761, v153
	v_mul_f32_e32 v156, v157, v156
	v_mul_f32_e32 v157, 0x3d372713, v205
	v_fma_f32 v157, v205, v157, 1.0
	v_mul_f32_e32 v155, v155, v154
	v_mul_f32_e32 v154, 0x3d372713, v161
	v_mul_f32_e32 v157, v205, v157
	v_fma_f32 v154, v161, v154, 1.0
	v_mul_f32_e32 v157, 0xc0135761, v157
	v_mul_f32_e32 v154, v161, v154
	v_exp_f32_e32 v157, v157
	v_mul_f32_e32 v154, 0xc0135761, v154
	v_exp_f32_e32 v153, v153
	v_exp_f32_e32 v154, v154
	v_add_f32_e32 v157, 1.0, v157
	v_rcp_f32_e32 v157, v157
	v_add_f32_e32 v153, 1.0, v153
	v_add_f32_e32 v154, 1.0, v154
	v_rcp_f32_e32 v153, v153
	v_rcp_f32_e32 v154, v154
	v_mul_f32_e32 v157, v205, v157
	v_mul_f32_e32 v153, v204, v153
	v_mul_f32_e32 v161, v161, v154
	v_cvt_pk_bf16_f32 v154, v135, v156
	v_cvt_pk_bf16_f32 v155, v159, v155
	v_cvt_pk_bf16_f32 v156, v153, v157
	v_cvt_pk_bf16_f32 v157, v160, v161
	global_store_dwordx4 v[150:151], v[154:157], off sc1
	v_pk_fma_f32 v[160:161], v[100:101], v[158:159], v[178:179] op_sel_hi:[1,0,1]
	s_nop 0
	v_pk_fma_f32 v[154:155], v[104:105], v[158:159], v[176:177] op_sel_hi:[1,0,1]
	v_pk_fma_f32 v[156:157], v[102:103], v[158:159], v[184:185] op_sel_hi:[1,0,1]
	v_pk_fma_f32 v[158:159], v[98:99], v[158:159], v[180:181] op_sel_hi:[1,0,1]
	v_mul_f32_e32 v135, 0x3d372713, v156
	v_mul_f32_e32 v153, 0x3d372713, v158
	v_fma_f32 v135, v156, v135, 1.0
	v_fma_f32 v153, v158, v153, 1.0
	v_mul_f32_e32 v135, v156, v135
	v_mul_f32_e32 v153, v158, v153
	v_mul_f32_e32 v135, 0xc0135761, v135
	v_mul_f32_e32 v153, 0xc0135761, v153
	v_exp_f32_e32 v135, v135
	v_exp_f32_e32 v153, v153
	v_add_f32_e32 v135, 1.0, v135
	v_add_f32_e32 v153, 1.0, v153
	v_rcp_f32_e32 v135, v135
	v_rcp_f32_e32 v153, v153
	v_mul_f32_e32 v135, v156, v135
	v_mul_f32_e32 v153, v158, v153
	v_mul_f32_e32 v156, 0x3d372713, v157
	v_mul_f32_e32 v158, 0x3d372713, v154
	v_fma_f32 v156, v157, v156, 1.0
	v_fma_f32 v158, v154, v158, 1.0
	v_mul_f32_e32 v156, v157, v156
	v_mul_f32_e32 v158, v154, v158
	v_mul_f32_e32 v156, 0xc0135761, v156
	v_mul_f32_e32 v158, 0xc0135761, v158
	v_exp_f32_e32 v156, v156
	v_exp_f32_e32 v158, v158
	v_add_f32_e32 v156, 1.0, v156
	v_add_f32_e32 v158, 1.0, v158
	v_rcp_f32_e32 v156, v156
	v_rcp_f32_e32 v158, v158
	v_mul_f32_e32 v156, v157, v156
	v_mul_f32_e32 v157, 0x3d372713, v159
	v_mul_f32_e32 v158, v154, v158
	v_mul_f32_e32 v154, 0x3d372713, v160
	v_fma_f32 v157, v159, v157, 1.0
	v_fma_f32 v154, v160, v154, 1.0
	v_mul_f32_e32 v157, v159, v157
	v_mul_f32_e32 v154, v160, v154
	v_mul_f32_e32 v157, 0xc0135761, v157
	v_mul_f32_e32 v154, 0xc0135761, v154
	v_exp_f32_e32 v157, v157
	v_exp_f32_e32 v154, v154
	v_add_f32_e32 v157, 1.0, v157
	v_add_f32_e32 v154, 1.0, v154
	v_rcp_f32_e32 v157, v157
	v_rcp_f32_e32 v154, v154
	v_mul_f32_e32 v157, v159, v157
	v_mul_f32_e32 v159, v160, v154
	v_mul_f32_e32 v154, 0x3d372713, v155
	v_fma_f32 v154, v155, v154, 1.0
	v_mul_f32_e32 v154, v155, v154
	v_mul_f32_e32 v154, 0xc0135761, v154
	v_exp_f32_e32 v154, v154
	s_nop 0
	v_add_f32_e32 v154, 1.0, v154
	v_rcp_f32_e32 v154, v154
	s_nop 0
	v_mul_f32_e32 v155, v155, v154
	v_mul_f32_e32 v154, 0x3d372713, v161
	v_fma_f32 v154, v161, v154, 1.0
	v_mul_f32_e32 v154, v161, v154
	v_mul_f32_e32 v154, 0xc0135761, v154
	v_exp_f32_e32 v154, v154
	s_nop 0
	v_add_f32_e32 v154, 1.0, v154
	v_rcp_f32_e32 v154, v154
	s_nop 0
	v_mul_f32_e32 v160, v161, v154
	v_cvt_pk_bf16_f32 v154, v135, v156
	v_or_b32_e32 v135, 32, v190
	v_cvt_pk_bf16_f32 v155, v158, v155
	v_cvt_pk_bf16_f32 v156, v153, v157
	v_cvt_pk_bf16_f32 v157, v159, v160
	global_store_dwordx4 v[150:151], v[154:157], off offset:256 sc1
	v_mad_i64_i32 v[150:151], s[6:7], v135, s66, v[148:149]
	v_subrev_u32_e32 v135, s21, v135
	v_lshl_add_u32 v135, v135, 2, s59
	ds_read_b32 v135, v135
	v_lshl_add_u64 v[150:151], v[150:151], 0, v[130:131]
	s_waitcnt lgkmcnt(0)
	v_cvt_f32_u32_e32 v135, v135
	v_fmamk_f32 v135, v135, 0x35000000, v232
	v_rsq_f32_e32 v158, v135
	s_nop 0
	v_pk_fma_f32 v[154:155], v[96:97], v[158:159], v[174:175] op_sel_hi:[1,0,1]
	v_pk_fma_f32 v[156:157], v[94:95], v[158:159], v[182:183] op_sel_hi:[1,0,1]
	v_pk_fma_f32 v[160:161], v[92:93], v[158:159], v[186:187] op_sel_hi:[1,0,1]
	v_pk_fma_f32 v[204:205], v[90:91], v[158:159], v[188:189] op_sel_hi:[1,0,1]
	v_mul_f32_e32 v159, 0x3d372713, v154
	v_fma_f32 v159, v154, v159, 1.0
	v_mul_f32_e32 v159, v154, v159
	v_mul_f32_e32 v159, 0xc0135761, v159
	v_exp_f32_e32 v159, v159
	v_mul_f32_e32 v135, 0x3d372713, v156
	v_fma_f32 v135, v156, v135, 1.0
	v_mul_f32_e32 v135, v156, v135
	v_add_f32_e32 v159, 1.0, v159
	v_rcp_f32_e32 v159, v159
	v_mul_f32_e32 v135, 0xc0135761, v135
	v_exp_f32_e32 v135, v135
	v_mul_f32_e32 v153, 0x3d372713, v204
	v_mul_f32_e32 v159, v154, v159
	v_mul_f32_e32 v154, 0x3d372713, v160
	v_fma_f32 v154, v160, v154, 1.0
	v_mul_f32_e32 v154, v160, v154
	v_mul_f32_e32 v154, 0xc0135761, v154
	v_exp_f32_e32 v154, v154
	v_add_f32_e32 v135, 1.0, v135
	v_rcp_f32_e32 v135, v135
	v_fma_f32 v153, v204, v153, 1.0
	v_add_f32_e32 v154, 1.0, v154
	v_rcp_f32_e32 v154, v154
	v_mul_f32_e32 v135, v156, v135
	v_mul_f32_e32 v156, 0x3d372713, v157
	v_fma_f32 v156, v157, v156, 1.0
	v_mul_f32_e32 v160, v160, v154
	v_mul_f32_e32 v154, 0x3d372713, v155
	v_mul_f32_e32 v156, v157, v156
	v_fma_f32 v154, v155, v154, 1.0
	v_mul_f32_e32 v156, 0xc0135761, v156
	v_mul_f32_e32 v154, v155, v154
	v_exp_f32_e32 v156, v156
	v_mul_f32_e32 v154, 0xc0135761, v154
	v_exp_f32_e32 v154, v154
	v_mul_f32_e32 v153, v204, v153
	v_add_f32_e32 v156, 1.0, v156
	v_rcp_f32_e32 v156, v156
	v_add_f32_e32 v154, 1.0, v154
	v_rcp_f32_e32 v154, v154
	v_mul_f32_e32 v153, 0xc0135761, v153
	v_mul_f32_e32 v156, v157, v156
	v_mul_f32_e32 v157, 0x3d372713, v205
	v_fma_f32 v157, v205, v157, 1.0
	v_mul_f32_e32 v155, v155, v154
	v_mul_f32_e32 v154, 0x3d372713, v161
	v_mul_f32_e32 v157, v205, v157
	v_fma_f32 v154, v161, v154, 1.0
	v_mul_f32_e32 v157, 0xc0135761, v157
	v_mul_f32_e32 v154, v161, v154
	v_exp_f32_e32 v157, v157
	v_mul_f32_e32 v154, 0xc0135761, v154
	v_exp_f32_e32 v153, v153
	v_exp_f32_e32 v154, v154
	v_add_f32_e32 v157, 1.0, v157
	v_rcp_f32_e32 v157, v157
	v_add_f32_e32 v153, 1.0, v153
	v_add_f32_e32 v154, 1.0, v154
	v_rcp_f32_e32 v153, v153
	v_rcp_f32_e32 v154, v154
	v_mul_f32_e32 v157, v205, v157
	v_mul_f32_e32 v153, v204, v153
	v_mul_f32_e32 v161, v161, v154
	v_cvt_pk_bf16_f32 v154, v135, v156
	v_cvt_pk_bf16_f32 v155, v159, v155
	v_cvt_pk_bf16_f32 v156, v153, v157
	v_cvt_pk_bf16_f32 v157, v160, v161
	global_store_dwordx4 v[150:151], v[154:157], off sc1
	v_pk_fma_f32 v[160:161], v[84:85], v[158:159], v[178:179] op_sel_hi:[1,0,1]
	s_nop 0
	v_pk_fma_f32 v[154:155], v[88:89], v[158:159], v[176:177] op_sel_hi:[1,0,1]
	v_pk_fma_f32 v[156:157], v[86:87], v[158:159], v[184:185] op_sel_hi:[1,0,1]
	v_pk_fma_f32 v[158:159], v[82:83], v[158:159], v[180:181] op_sel_hi:[1,0,1]
	v_mul_f32_e32 v135, 0x3d372713, v156
	v_mul_f32_e32 v153, 0x3d372713, v158
	v_fma_f32 v135, v156, v135, 1.0
	v_fma_f32 v153, v158, v153, 1.0
	v_mul_f32_e32 v135, v156, v135
	v_mul_f32_e32 v153, v158, v153
	v_mul_f32_e32 v135, 0xc0135761, v135
	v_mul_f32_e32 v153, 0xc0135761, v153
	v_exp_f32_e32 v135, v135
	v_exp_f32_e32 v153, v153
	v_add_f32_e32 v135, 1.0, v135
	v_add_f32_e32 v153, 1.0, v153
	v_rcp_f32_e32 v135, v135
	v_rcp_f32_e32 v153, v153
	v_mul_f32_e32 v135, v156, v135
	v_mul_f32_e32 v153, v158, v153
	v_mul_f32_e32 v156, 0x3d372713, v157
	v_mul_f32_e32 v158, 0x3d372713, v154
	v_fma_f32 v156, v157, v156, 1.0
	v_fma_f32 v158, v154, v158, 1.0
	v_mul_f32_e32 v156, v157, v156
	v_mul_f32_e32 v158, v154, v158
	v_mul_f32_e32 v156, 0xc0135761, v156
	v_mul_f32_e32 v158, 0xc0135761, v158
	v_exp_f32_e32 v156, v156
	v_exp_f32_e32 v158, v158
	v_add_f32_e32 v156, 1.0, v156
	v_add_f32_e32 v158, 1.0, v158
	v_rcp_f32_e32 v156, v156
	v_rcp_f32_e32 v158, v158
	v_mul_f32_e32 v156, v157, v156
	v_mul_f32_e32 v157, 0x3d372713, v159
	v_mul_f32_e32 v158, v154, v158
	v_mul_f32_e32 v154, 0x3d372713, v160
	v_fma_f32 v157, v159, v157, 1.0
	v_fma_f32 v154, v160, v154, 1.0
	v_mul_f32_e32 v157, v159, v157
	v_mul_f32_e32 v154, v160, v154
	v_mul_f32_e32 v157, 0xc0135761, v157
	v_mul_f32_e32 v154, 0xc0135761, v154
	v_exp_f32_e32 v157, v157
	v_exp_f32_e32 v154, v154
	v_add_f32_e32 v157, 1.0, v157
	v_add_f32_e32 v154, 1.0, v154
	v_rcp_f32_e32 v157, v157
	v_rcp_f32_e32 v154, v154
	v_mul_f32_e32 v157, v159, v157
	v_mul_f32_e32 v159, v160, v154
	v_mul_f32_e32 v154, 0x3d372713, v155
	v_fma_f32 v154, v155, v154, 1.0
	v_mul_f32_e32 v154, v155, v154
	v_mul_f32_e32 v154, 0xc0135761, v154
	v_exp_f32_e32 v154, v154
	s_nop 0
	v_add_f32_e32 v154, 1.0, v154
	v_rcp_f32_e32 v154, v154
	s_nop 0
	v_mul_f32_e32 v155, v155, v154
	v_mul_f32_e32 v154, 0x3d372713, v161
	v_fma_f32 v154, v161, v154, 1.0
	v_mul_f32_e32 v154, v161, v154
	v_mul_f32_e32 v154, 0xc0135761, v154
	v_exp_f32_e32 v154, v154
	s_nop 0
	v_add_f32_e32 v154, 1.0, v154
	v_rcp_f32_e32 v154, v154
	s_nop 0
	v_mul_f32_e32 v160, v161, v154
	v_cvt_pk_bf16_f32 v154, v135, v156
	v_or_b32_e32 v135, 48, v190
	v_cvt_pk_bf16_f32 v155, v158, v155
	v_cvt_pk_bf16_f32 v156, v153, v157
	v_cvt_pk_bf16_f32 v157, v159, v160
	global_store_dwordx4 v[150:151], v[154:157], off offset:256 sc1
	v_mad_i64_i32 v[150:151], s[6:7], v135, s66, v[148:149]
	v_subrev_u32_e32 v135, s21, v135
	v_lshl_add_u32 v135, v135, 2, s59
	ds_read_b32 v135, v135
	v_lshl_add_u64 v[150:151], v[150:151], 0, v[130:131]
	s_waitcnt lgkmcnt(0)
	v_cvt_f32_u32_e32 v135, v135
	v_fmamk_f32 v135, v135, 0x35000000, v232
	v_rsq_f32_e32 v158, v135
	s_nop 0
	v_pk_fma_f32 v[154:155], v[80:81], v[158:159], v[174:175] op_sel_hi:[1,0,1]
	v_pk_fma_f32 v[156:157], v[78:79], v[158:159], v[182:183] op_sel_hi:[1,0,1]
	v_pk_fma_f32 v[160:161], v[76:77], v[158:159], v[186:187] op_sel_hi:[1,0,1]
	v_pk_fma_f32 v[204:205], v[74:75], v[158:159], v[188:189] op_sel_hi:[1,0,1]
	v_mul_f32_e32 v159, 0x3d372713, v154
	v_fma_f32 v159, v154, v159, 1.0
	v_mul_f32_e32 v159, v154, v159
	v_mul_f32_e32 v159, 0xc0135761, v159
	v_exp_f32_e32 v159, v159
	v_mul_f32_e32 v135, 0x3d372713, v156
	v_fma_f32 v135, v156, v135, 1.0
	v_mul_f32_e32 v135, v156, v135
	v_add_f32_e32 v159, 1.0, v159
	v_rcp_f32_e32 v159, v159
	v_mul_f32_e32 v135, 0xc0135761, v135
	v_exp_f32_e32 v135, v135
	v_mul_f32_e32 v153, 0x3d372713, v204
	v_mul_f32_e32 v159, v154, v159
	v_mul_f32_e32 v154, 0x3d372713, v160
	v_fma_f32 v154, v160, v154, 1.0
	v_mul_f32_e32 v154, v160, v154
	v_mul_f32_e32 v154, 0xc0135761, v154
	v_exp_f32_e32 v154, v154
	v_add_f32_e32 v135, 1.0, v135
	v_rcp_f32_e32 v135, v135
	v_fma_f32 v153, v204, v153, 1.0
	v_add_f32_e32 v154, 1.0, v154
	v_rcp_f32_e32 v154, v154
	v_mul_f32_e32 v135, v156, v135
	v_mul_f32_e32 v156, 0x3d372713, v157
	v_fma_f32 v156, v157, v156, 1.0
	v_mul_f32_e32 v160, v160, v154
	v_mul_f32_e32 v154, 0x3d372713, v155
	v_mul_f32_e32 v156, v157, v156
	v_fma_f32 v154, v155, v154, 1.0
	v_mul_f32_e32 v156, 0xc0135761, v156
	v_mul_f32_e32 v154, v155, v154
	v_exp_f32_e32 v156, v156
	v_mul_f32_e32 v154, 0xc0135761, v154
	v_exp_f32_e32 v154, v154
	v_mul_f32_e32 v153, v204, v153
	v_add_f32_e32 v156, 1.0, v156
	v_rcp_f32_e32 v156, v156
	v_add_f32_e32 v154, 1.0, v154
	v_rcp_f32_e32 v154, v154
	v_mul_f32_e32 v153, 0xc0135761, v153
	v_mul_f32_e32 v156, v157, v156
	v_mul_f32_e32 v157, 0x3d372713, v205
	v_fma_f32 v157, v205, v157, 1.0
	v_mul_f32_e32 v155, v155, v154
	v_mul_f32_e32 v154, 0x3d372713, v161
	v_mul_f32_e32 v157, v205, v157
	v_fma_f32 v154, v161, v154, 1.0
	v_mul_f32_e32 v157, 0xc0135761, v157
	v_mul_f32_e32 v154, v161, v154
	v_exp_f32_e32 v157, v157
	v_mul_f32_e32 v154, 0xc0135761, v154
	v_exp_f32_e32 v153, v153
	v_exp_f32_e32 v154, v154
	v_add_f32_e32 v157, 1.0, v157
	v_rcp_f32_e32 v157, v157
	v_add_f32_e32 v153, 1.0, v153
	v_add_f32_e32 v154, 1.0, v154
	v_rcp_f32_e32 v153, v153
	v_rcp_f32_e32 v154, v154
	v_mul_f32_e32 v157, v205, v157
	v_mul_f32_e32 v153, v204, v153
	v_mul_f32_e32 v161, v161, v154
	v_cvt_pk_bf16_f32 v154, v135, v156
	v_cvt_pk_bf16_f32 v155, v159, v155
	v_cvt_pk_bf16_f32 v156, v153, v157
	v_cvt_pk_bf16_f32 v157, v160, v161
	global_store_dwordx4 v[150:151], v[154:157], off sc1
	v_pk_fma_f32 v[160:161], v[68:69], v[158:159], v[178:179] op_sel_hi:[1,0,1]
	s_nop 0
	v_pk_fma_f32 v[154:155], v[72:73], v[158:159], v[176:177] op_sel_hi:[1,0,1]
	v_pk_fma_f32 v[156:157], v[70:71], v[158:159], v[184:185] op_sel_hi:[1,0,1]
	v_pk_fma_f32 v[158:159], v[66:67], v[158:159], v[180:181] op_sel_hi:[1,0,1]
	v_mul_f32_e32 v135, 0x3d372713, v156
	v_mul_f32_e32 v153, 0x3d372713, v158
	v_fma_f32 v135, v156, v135, 1.0
	v_fma_f32 v153, v158, v153, 1.0
	v_mul_f32_e32 v135, v156, v135
	v_mul_f32_e32 v153, v158, v153
	v_mul_f32_e32 v135, 0xc0135761, v135
	v_mul_f32_e32 v153, 0xc0135761, v153
	v_exp_f32_e32 v135, v135
	v_exp_f32_e32 v153, v153
	v_add_f32_e32 v135, 1.0, v135
	v_add_f32_e32 v153, 1.0, v153
	v_rcp_f32_e32 v135, v135
	v_rcp_f32_e32 v153, v153
	v_mul_f32_e32 v135, v156, v135
	v_mul_f32_e32 v153, v158, v153
	v_mul_f32_e32 v156, 0x3d372713, v157
	v_mul_f32_e32 v158, 0x3d372713, v154
	v_fma_f32 v156, v157, v156, 1.0
	v_fma_f32 v158, v154, v158, 1.0
	v_mul_f32_e32 v156, v157, v156
	v_mul_f32_e32 v158, v154, v158
	v_mul_f32_e32 v156, 0xc0135761, v156
	v_mul_f32_e32 v158, 0xc0135761, v158
	v_exp_f32_e32 v156, v156
	v_exp_f32_e32 v158, v158
	v_add_f32_e32 v156, 1.0, v156
	v_add_f32_e32 v158, 1.0, v158
	v_rcp_f32_e32 v156, v156
	v_rcp_f32_e32 v158, v158
	v_mul_f32_e32 v156, v157, v156
	v_mul_f32_e32 v157, 0x3d372713, v159
	v_mul_f32_e32 v158, v154, v158
	v_mul_f32_e32 v154, 0x3d372713, v160
	v_fma_f32 v157, v159, v157, 1.0
	v_fma_f32 v154, v160, v154, 1.0
	v_mul_f32_e32 v157, v159, v157
	v_mul_f32_e32 v154, v160, v154
	v_mul_f32_e32 v157, 0xc0135761, v157
	v_mul_f32_e32 v154, 0xc0135761, v154
	v_exp_f32_e32 v157, v157
	v_exp_f32_e32 v154, v154
	v_add_f32_e32 v157, 1.0, v157
	v_add_f32_e32 v154, 1.0, v154
	v_rcp_f32_e32 v157, v157
	v_rcp_f32_e32 v154, v154
	v_mul_f32_e32 v157, v159, v157
	v_mul_f32_e32 v159, v160, v154
	v_mul_f32_e32 v154, 0x3d372713, v155
	v_fma_f32 v154, v155, v154, 1.0
	v_mul_f32_e32 v154, v155, v154
	v_mul_f32_e32 v154, 0xc0135761, v154
	v_exp_f32_e32 v154, v154
	s_nop 0
	v_add_f32_e32 v154, 1.0, v154
	v_rcp_f32_e32 v154, v154
	s_nop 0
	v_mul_f32_e32 v155, v155, v154
	v_mul_f32_e32 v154, 0x3d372713, v161
	v_fma_f32 v154, v161, v154, 1.0
	v_mul_f32_e32 v154, v161, v154
	v_mul_f32_e32 v154, 0xc0135761, v154
	v_exp_f32_e32 v154, v154
	s_nop 0
	v_add_f32_e32 v154, 1.0, v154
	v_rcp_f32_e32 v154, v154
	s_nop 0
	v_mul_f32_e32 v160, v161, v154
	v_cvt_pk_bf16_f32 v154, v135, v156
	v_add_u32_e32 v135, 0x80, v190
	v_cvt_pk_bf16_f32 v155, v158, v155
	v_cvt_pk_bf16_f32 v156, v153, v157
	v_cvt_pk_bf16_f32 v157, v159, v160
	global_store_dwordx4 v[150:151], v[154:157], off offset:256 sc1
	v_mad_i64_i32 v[150:151], s[6:7], v135, s66, v[148:149]
	v_subrev_u32_e32 v135, s21, v135
	v_lshl_add_u32 v135, v135, 2, s59
	ds_read_b32 v135, v135
	v_lshl_add_u64 v[150:151], v[150:151], 0, v[130:131]
	s_waitcnt lgkmcnt(0)
	v_cvt_f32_u32_e32 v135, v135
	v_fmamk_f32 v135, v135, 0x35000000, v232
	v_rsq_f32_e32 v158, v135
	s_nop 0
	v_pk_fma_f32 v[154:155], v[64:65], v[158:159], v[174:175] op_sel_hi:[1,0,1]
	v_pk_fma_f32 v[156:157], v[62:63], v[158:159], v[182:183] op_sel_hi:[1,0,1]
	v_pk_fma_f32 v[160:161], v[60:61], v[158:159], v[186:187] op_sel_hi:[1,0,1]
	v_pk_fma_f32 v[204:205], v[58:59], v[158:159], v[188:189] op_sel_hi:[1,0,1]
	v_mul_f32_e32 v159, 0x3d372713, v154
	v_fma_f32 v159, v154, v159, 1.0
	v_mul_f32_e32 v159, v154, v159
	v_mul_f32_e32 v159, 0xc0135761, v159
	v_exp_f32_e32 v159, v159
	v_mul_f32_e32 v135, 0x3d372713, v156
	v_fma_f32 v135, v156, v135, 1.0
	v_mul_f32_e32 v135, v156, v135
	v_add_f32_e32 v159, 1.0, v159
	v_rcp_f32_e32 v159, v159
	v_mul_f32_e32 v135, 0xc0135761, v135
	v_exp_f32_e32 v135, v135
	v_mul_f32_e32 v153, 0x3d372713, v204
	v_mul_f32_e32 v159, v154, v159
	v_mul_f32_e32 v154, 0x3d372713, v160
	v_fma_f32 v154, v160, v154, 1.0
	v_mul_f32_e32 v154, v160, v154
	v_mul_f32_e32 v154, 0xc0135761, v154
	v_exp_f32_e32 v154, v154
	v_add_f32_e32 v135, 1.0, v135
	v_rcp_f32_e32 v135, v135
	v_fma_f32 v153, v204, v153, 1.0
	v_add_f32_e32 v154, 1.0, v154
	v_rcp_f32_e32 v154, v154
	v_mul_f32_e32 v135, v156, v135
	v_mul_f32_e32 v156, 0x3d372713, v157
	v_fma_f32 v156, v157, v156, 1.0
	v_mul_f32_e32 v160, v160, v154
	v_mul_f32_e32 v154, 0x3d372713, v155
	v_mul_f32_e32 v156, v157, v156
	v_fma_f32 v154, v155, v154, 1.0
	v_mul_f32_e32 v156, 0xc0135761, v156
	v_mul_f32_e32 v154, v155, v154
	v_exp_f32_e32 v156, v156
	v_mul_f32_e32 v154, 0xc0135761, v154
	v_exp_f32_e32 v154, v154
	v_mul_f32_e32 v153, v204, v153
	v_add_f32_e32 v156, 1.0, v156
	v_rcp_f32_e32 v156, v156
	v_add_f32_e32 v154, 1.0, v154
	v_rcp_f32_e32 v154, v154
	v_mul_f32_e32 v153, 0xc0135761, v153
	v_mul_f32_e32 v156, v157, v156
	v_mul_f32_e32 v157, 0x3d372713, v205
	v_fma_f32 v157, v205, v157, 1.0
	v_mul_f32_e32 v155, v155, v154
	v_mul_f32_e32 v154, 0x3d372713, v161
	v_mul_f32_e32 v157, v205, v157
	v_fma_f32 v154, v161, v154, 1.0
	v_mul_f32_e32 v157, 0xc0135761, v157
	v_mul_f32_e32 v154, v161, v154
	v_exp_f32_e32 v157, v157
	v_mul_f32_e32 v154, 0xc0135761, v154
	v_exp_f32_e32 v153, v153
	v_exp_f32_e32 v154, v154
	v_add_f32_e32 v157, 1.0, v157
	v_rcp_f32_e32 v157, v157
	v_add_f32_e32 v153, 1.0, v153
	v_add_f32_e32 v154, 1.0, v154
	v_rcp_f32_e32 v153, v153
	v_rcp_f32_e32 v154, v154
	v_mul_f32_e32 v157, v205, v157
	v_mul_f32_e32 v153, v204, v153
	v_mul_f32_e32 v161, v161, v154
	v_cvt_pk_bf16_f32 v154, v135, v156
	v_cvt_pk_bf16_f32 v155, v159, v155
	v_cvt_pk_bf16_f32 v156, v153, v157
	v_cvt_pk_bf16_f32 v157, v160, v161
	global_store_dwordx4 v[150:151], v[154:157], off sc1
	v_pk_fma_f32 v[160:161], v[52:53], v[158:159], v[178:179] op_sel_hi:[1,0,1]
	s_nop 0
	v_pk_fma_f32 v[154:155], v[56:57], v[158:159], v[176:177] op_sel_hi:[1,0,1]
	v_pk_fma_f32 v[156:157], v[54:55], v[158:159], v[184:185] op_sel_hi:[1,0,1]
	v_pk_fma_f32 v[158:159], v[50:51], v[158:159], v[180:181] op_sel_hi:[1,0,1]
	v_mul_f32_e32 v135, 0x3d372713, v156
	v_mul_f32_e32 v153, 0x3d372713, v158
	v_fma_f32 v135, v156, v135, 1.0
	v_fma_f32 v153, v158, v153, 1.0
	v_mul_f32_e32 v135, v156, v135
	v_mul_f32_e32 v153, v158, v153
	v_mul_f32_e32 v135, 0xc0135761, v135
	v_mul_f32_e32 v153, 0xc0135761, v153
	v_exp_f32_e32 v135, v135
	v_exp_f32_e32 v153, v153
	v_add_f32_e32 v135, 1.0, v135
	v_add_f32_e32 v153, 1.0, v153
	v_rcp_f32_e32 v135, v135
	v_rcp_f32_e32 v153, v153
	v_mul_f32_e32 v135, v156, v135
	v_mul_f32_e32 v153, v158, v153
	v_mul_f32_e32 v156, 0x3d372713, v157
	v_mul_f32_e32 v158, 0x3d372713, v154
	v_fma_f32 v156, v157, v156, 1.0
	v_fma_f32 v158, v154, v158, 1.0
	v_mul_f32_e32 v156, v157, v156
	v_mul_f32_e32 v158, v154, v158
	v_mul_f32_e32 v156, 0xc0135761, v156
	v_mul_f32_e32 v158, 0xc0135761, v158
	v_exp_f32_e32 v156, v156
	v_exp_f32_e32 v158, v158
	v_add_f32_e32 v156, 1.0, v156
	v_add_f32_e32 v158, 1.0, v158
	v_rcp_f32_e32 v156, v156
	v_rcp_f32_e32 v158, v158
	v_mul_f32_e32 v156, v157, v156
	v_mul_f32_e32 v157, 0x3d372713, v159
	v_mul_f32_e32 v158, v154, v158
	v_mul_f32_e32 v154, 0x3d372713, v160
	v_fma_f32 v157, v159, v157, 1.0
	v_fma_f32 v154, v160, v154, 1.0
	v_mul_f32_e32 v157, v159, v157
	v_mul_f32_e32 v154, v160, v154
	v_mul_f32_e32 v157, 0xc0135761, v157
	v_mul_f32_e32 v154, 0xc0135761, v154
	v_exp_f32_e32 v157, v157
	v_exp_f32_e32 v154, v154
	v_add_f32_e32 v157, 1.0, v157
	v_add_f32_e32 v154, 1.0, v154
	v_rcp_f32_e32 v157, v157
	v_rcp_f32_e32 v154, v154
	v_mul_f32_e32 v157, v159, v157
	v_mul_f32_e32 v159, v160, v154
	v_mul_f32_e32 v154, 0x3d372713, v155
	v_fma_f32 v154, v155, v154, 1.0
	v_mul_f32_e32 v154, v155, v154
	v_mul_f32_e32 v154, 0xc0135761, v154
	v_exp_f32_e32 v154, v154
	s_nop 0
	v_add_f32_e32 v154, 1.0, v154
	v_rcp_f32_e32 v154, v154
	s_nop 0
	v_mul_f32_e32 v155, v155, v154
	v_mul_f32_e32 v154, 0x3d372713, v161
	v_fma_f32 v154, v161, v154, 1.0
	v_mul_f32_e32 v154, v161, v154
	v_mul_f32_e32 v154, 0xc0135761, v154
	v_exp_f32_e32 v154, v154
	s_nop 0
	v_add_f32_e32 v154, 1.0, v154
	v_rcp_f32_e32 v154, v154
	s_nop 0
	v_mul_f32_e32 v160, v161, v154
	v_cvt_pk_bf16_f32 v154, v135, v156
	v_add_u32_e32 v135, 0x90, v190
	v_cvt_pk_bf16_f32 v155, v158, v155
	v_cvt_pk_bf16_f32 v156, v153, v157
	v_cvt_pk_bf16_f32 v157, v159, v160
	global_store_dwordx4 v[150:151], v[154:157], off offset:256 sc1
	v_mad_i64_i32 v[150:151], s[6:7], v135, s66, v[148:149]
	v_subrev_u32_e32 v135, s21, v135
	v_lshl_add_u32 v135, v135, 2, s59
	ds_read_b32 v135, v135
	v_lshl_add_u64 v[150:151], v[150:151], 0, v[130:131]
	s_waitcnt lgkmcnt(0)
	v_cvt_f32_u32_e32 v135, v135
	v_fmamk_f32 v135, v135, 0x35000000, v232
	v_rsq_f32_e32 v158, v135
	s_nop 0
	v_pk_fma_f32 v[154:155], v[48:49], v[158:159], v[174:175] op_sel_hi:[1,0,1]
	v_pk_fma_f32 v[156:157], v[46:47], v[158:159], v[182:183] op_sel_hi:[1,0,1]
	v_pk_fma_f32 v[160:161], v[44:45], v[158:159], v[186:187] op_sel_hi:[1,0,1]
	v_pk_fma_f32 v[204:205], v[42:43], v[158:159], v[188:189] op_sel_hi:[1,0,1]
	v_mul_f32_e32 v159, 0x3d372713, v154
	v_fma_f32 v159, v154, v159, 1.0
	v_mul_f32_e32 v159, v154, v159
	v_mul_f32_e32 v159, 0xc0135761, v159
	v_exp_f32_e32 v159, v159
	v_mul_f32_e32 v135, 0x3d372713, v156
	v_fma_f32 v135, v156, v135, 1.0
	v_mul_f32_e32 v135, v156, v135
	v_add_f32_e32 v159, 1.0, v159
	v_rcp_f32_e32 v159, v159
	v_mul_f32_e32 v135, 0xc0135761, v135
	v_exp_f32_e32 v135, v135
	v_mul_f32_e32 v153, 0x3d372713, v204
	v_mul_f32_e32 v159, v154, v159
	v_mul_f32_e32 v154, 0x3d372713, v160
	v_fma_f32 v154, v160, v154, 1.0
	v_mul_f32_e32 v154, v160, v154
	v_mul_f32_e32 v154, 0xc0135761, v154
	v_exp_f32_e32 v154, v154
	v_add_f32_e32 v135, 1.0, v135
	v_rcp_f32_e32 v135, v135
	v_fma_f32 v153, v204, v153, 1.0
	v_add_f32_e32 v154, 1.0, v154
	v_rcp_f32_e32 v154, v154
	v_mul_f32_e32 v135, v156, v135
	v_mul_f32_e32 v156, 0x3d372713, v157
	v_fma_f32 v156, v157, v156, 1.0
	v_mul_f32_e32 v160, v160, v154
	v_mul_f32_e32 v154, 0x3d372713, v155
	v_mul_f32_e32 v156, v157, v156
	v_fma_f32 v154, v155, v154, 1.0
	v_mul_f32_e32 v156, 0xc0135761, v156
	v_mul_f32_e32 v154, v155, v154
	v_exp_f32_e32 v156, v156
	v_mul_f32_e32 v154, 0xc0135761, v154
	v_exp_f32_e32 v154, v154
	v_mul_f32_e32 v153, v204, v153
	v_add_f32_e32 v156, 1.0, v156
	v_rcp_f32_e32 v156, v156
	v_add_f32_e32 v154, 1.0, v154
	v_rcp_f32_e32 v154, v154
	v_mul_f32_e32 v153, 0xc0135761, v153
	v_mul_f32_e32 v156, v157, v156
	v_mul_f32_e32 v157, 0x3d372713, v205
	v_fma_f32 v157, v205, v157, 1.0
	v_mul_f32_e32 v155, v155, v154
	v_mul_f32_e32 v154, 0x3d372713, v161
	v_mul_f32_e32 v157, v205, v157
	v_fma_f32 v154, v161, v154, 1.0
	v_mul_f32_e32 v157, 0xc0135761, v157
	v_mul_f32_e32 v154, v161, v154
	v_exp_f32_e32 v157, v157
	v_mul_f32_e32 v154, 0xc0135761, v154
	v_exp_f32_e32 v153, v153
	v_exp_f32_e32 v154, v154
	v_add_f32_e32 v157, 1.0, v157
	v_rcp_f32_e32 v157, v157
	v_add_f32_e32 v153, 1.0, v153
	v_add_f32_e32 v154, 1.0, v154
	v_rcp_f32_e32 v153, v153
	v_rcp_f32_e32 v154, v154
	v_mul_f32_e32 v157, v205, v157
	v_mul_f32_e32 v153, v204, v153
	v_mul_f32_e32 v161, v161, v154
	v_cvt_pk_bf16_f32 v154, v135, v156
	v_cvt_pk_bf16_f32 v155, v159, v155
	v_cvt_pk_bf16_f32 v156, v153, v157
	v_cvt_pk_bf16_f32 v157, v160, v161
	global_store_dwordx4 v[150:151], v[154:157], off sc1
	v_pk_fma_f32 v[160:161], v[36:37], v[158:159], v[178:179] op_sel_hi:[1,0,1]
	s_nop 0
	v_pk_fma_f32 v[154:155], v[40:41], v[158:159], v[176:177] op_sel_hi:[1,0,1]
	v_pk_fma_f32 v[156:157], v[38:39], v[158:159], v[184:185] op_sel_hi:[1,0,1]
	v_pk_fma_f32 v[158:159], v[34:35], v[158:159], v[180:181] op_sel_hi:[1,0,1]
	v_mul_f32_e32 v135, 0x3d372713, v156
	v_mul_f32_e32 v153, 0x3d372713, v158
	v_fma_f32 v135, v156, v135, 1.0
	v_fma_f32 v153, v158, v153, 1.0
	v_mul_f32_e32 v135, v156, v135
	v_mul_f32_e32 v153, v158, v153
	v_mul_f32_e32 v135, 0xc0135761, v135
	v_mul_f32_e32 v153, 0xc0135761, v153
	v_exp_f32_e32 v135, v135
	v_exp_f32_e32 v153, v153
	v_add_f32_e32 v135, 1.0, v135
	v_add_f32_e32 v153, 1.0, v153
	v_rcp_f32_e32 v135, v135
	v_rcp_f32_e32 v153, v153
	v_mul_f32_e32 v135, v156, v135
	v_mul_f32_e32 v153, v158, v153
	v_mul_f32_e32 v156, 0x3d372713, v157
	v_mul_f32_e32 v158, 0x3d372713, v154
	v_fma_f32 v156, v157, v156, 1.0
	v_fma_f32 v158, v154, v158, 1.0
	v_mul_f32_e32 v156, v157, v156
	v_mul_f32_e32 v158, v154, v158
	v_mul_f32_e32 v156, 0xc0135761, v156
	v_mul_f32_e32 v158, 0xc0135761, v158
	v_exp_f32_e32 v156, v156
	v_exp_f32_e32 v158, v158
	v_add_f32_e32 v156, 1.0, v156
	v_add_f32_e32 v158, 1.0, v158
	v_rcp_f32_e32 v156, v156
	v_rcp_f32_e32 v158, v158
	v_mul_f32_e32 v156, v157, v156
	v_mul_f32_e32 v157, 0x3d372713, v159
	v_mul_f32_e32 v158, v154, v158
	v_mul_f32_e32 v154, 0x3d372713, v160
	v_fma_f32 v157, v159, v157, 1.0
	v_fma_f32 v154, v160, v154, 1.0
	v_mul_f32_e32 v157, v159, v157
	v_mul_f32_e32 v154, v160, v154
	v_mul_f32_e32 v157, 0xc0135761, v157
	v_mul_f32_e32 v154, 0xc0135761, v154
	v_exp_f32_e32 v157, v157
	v_exp_f32_e32 v154, v154
	v_add_f32_e32 v157, 1.0, v157
	v_add_f32_e32 v154, 1.0, v154
	v_rcp_f32_e32 v157, v157
	v_rcp_f32_e32 v154, v154
	v_mul_f32_e32 v157, v159, v157
	v_mul_f32_e32 v159, v160, v154
	v_mul_f32_e32 v154, 0x3d372713, v155
	v_fma_f32 v154, v155, v154, 1.0
	v_mul_f32_e32 v154, v155, v154
	v_mul_f32_e32 v154, 0xc0135761, v154
	v_exp_f32_e32 v154, v154
	s_nop 0
	v_add_f32_e32 v154, 1.0, v154
	v_rcp_f32_e32 v154, v154
	s_nop 0
	v_mul_f32_e32 v155, v155, v154
	v_mul_f32_e32 v154, 0x3d372713, v161
	v_fma_f32 v154, v161, v154, 1.0
	v_mul_f32_e32 v154, v161, v154
	v_mul_f32_e32 v154, 0xc0135761, v154
	v_exp_f32_e32 v154, v154
	s_nop 0
	v_add_f32_e32 v154, 1.0, v154
	v_rcp_f32_e32 v154, v154
	s_nop 0
	v_mul_f32_e32 v160, v161, v154
	v_cvt_pk_bf16_f32 v154, v135, v156
	v_add_u32_e32 v135, 0xa0, v190
	v_cvt_pk_bf16_f32 v155, v158, v155
	v_cvt_pk_bf16_f32 v156, v153, v157
	v_cvt_pk_bf16_f32 v157, v159, v160
	global_store_dwordx4 v[150:151], v[154:157], off offset:256 sc1
	v_mad_i64_i32 v[150:151], s[6:7], v135, s66, v[148:149]
	v_subrev_u32_e32 v135, s21, v135
	v_lshl_add_u32 v135, v135, 2, s59
	ds_read_b32 v135, v135
	v_lshl_add_u64 v[150:151], v[150:151], 0, v[130:131]
	s_waitcnt lgkmcnt(0)
	v_cvt_f32_u32_e32 v135, v135
	v_fmamk_f32 v135, v135, 0x35000000, v232
	v_rsq_f32_e32 v158, v135
	s_nop 0
	v_pk_fma_f32 v[154:155], v[32:33], v[158:159], v[174:175] op_sel_hi:[1,0,1]
	v_pk_fma_f32 v[156:157], v[30:31], v[158:159], v[182:183] op_sel_hi:[1,0,1]
	v_pk_fma_f32 v[160:161], v[28:29], v[158:159], v[186:187] op_sel_hi:[1,0,1]
	v_pk_fma_f32 v[204:205], v[26:27], v[158:159], v[188:189] op_sel_hi:[1,0,1]
	v_mul_f32_e32 v159, 0x3d372713, v154
	v_fma_f32 v159, v154, v159, 1.0
	v_mul_f32_e32 v159, v154, v159
	v_mul_f32_e32 v159, 0xc0135761, v159
	v_exp_f32_e32 v159, v159
	v_mul_f32_e32 v135, 0x3d372713, v156
	v_fma_f32 v135, v156, v135, 1.0
	v_mul_f32_e32 v135, v156, v135
	v_add_f32_e32 v159, 1.0, v159
	v_rcp_f32_e32 v159, v159
	v_mul_f32_e32 v135, 0xc0135761, v135
	v_exp_f32_e32 v135, v135
	v_mul_f32_e32 v153, 0x3d372713, v204
	v_mul_f32_e32 v159, v154, v159
	v_mul_f32_e32 v154, 0x3d372713, v160
	v_fma_f32 v154, v160, v154, 1.0
	v_mul_f32_e32 v154, v160, v154
	v_mul_f32_e32 v154, 0xc0135761, v154
	v_exp_f32_e32 v154, v154
	v_add_f32_e32 v135, 1.0, v135
	v_rcp_f32_e32 v135, v135
	v_fma_f32 v153, v204, v153, 1.0
	v_add_f32_e32 v154, 1.0, v154
	v_rcp_f32_e32 v154, v154
	v_mul_f32_e32 v135, v156, v135
	v_mul_f32_e32 v156, 0x3d372713, v157
	v_fma_f32 v156, v157, v156, 1.0
	v_mul_f32_e32 v160, v160, v154
	v_mul_f32_e32 v154, 0x3d372713, v155
	v_mul_f32_e32 v156, v157, v156
	v_fma_f32 v154, v155, v154, 1.0
	v_mul_f32_e32 v156, 0xc0135761, v156
	v_mul_f32_e32 v154, v155, v154
	v_exp_f32_e32 v156, v156
	v_mul_f32_e32 v154, 0xc0135761, v154
	v_exp_f32_e32 v154, v154
	v_mul_f32_e32 v153, v204, v153
	v_add_f32_e32 v156, 1.0, v156
	v_rcp_f32_e32 v156, v156
	v_add_f32_e32 v154, 1.0, v154
	v_rcp_f32_e32 v154, v154
	v_mul_f32_e32 v153, 0xc0135761, v153
	v_mul_f32_e32 v156, v157, v156
	v_mul_f32_e32 v157, 0x3d372713, v205
	v_fma_f32 v157, v205, v157, 1.0
	v_mul_f32_e32 v155, v155, v154
	v_mul_f32_e32 v154, 0x3d372713, v161
	v_mul_f32_e32 v157, v205, v157
	v_fma_f32 v154, v161, v154, 1.0
	v_mul_f32_e32 v157, 0xc0135761, v157
	v_mul_f32_e32 v154, v161, v154
	v_exp_f32_e32 v157, v157
	v_mul_f32_e32 v154, 0xc0135761, v154
	v_exp_f32_e32 v153, v153
	v_exp_f32_e32 v154, v154
	v_add_f32_e32 v157, 1.0, v157
	v_rcp_f32_e32 v157, v157
	v_add_f32_e32 v153, 1.0, v153
	v_add_f32_e32 v154, 1.0, v154
	v_rcp_f32_e32 v153, v153
	v_rcp_f32_e32 v154, v154
	v_mul_f32_e32 v157, v205, v157
	v_mul_f32_e32 v153, v204, v153
	v_mul_f32_e32 v161, v161, v154
	v_cvt_pk_bf16_f32 v154, v135, v156
	v_cvt_pk_bf16_f32 v155, v159, v155
	v_cvt_pk_bf16_f32 v156, v153, v157
	v_cvt_pk_bf16_f32 v157, v160, v161
	global_store_dwordx4 v[150:151], v[154:157], off sc1
	v_pk_fma_f32 v[160:161], v[20:21], v[158:159], v[178:179] op_sel_hi:[1,0,1]
	s_nop 0
	v_pk_fma_f32 v[154:155], v[24:25], v[158:159], v[176:177] op_sel_hi:[1,0,1]
	v_pk_fma_f32 v[156:157], v[22:23], v[158:159], v[184:185] op_sel_hi:[1,0,1]
	v_pk_fma_f32 v[158:159], v[18:19], v[158:159], v[180:181] op_sel_hi:[1,0,1]
	v_mul_f32_e32 v135, 0x3d372713, v156
	v_mul_f32_e32 v153, 0x3d372713, v158
	v_fma_f32 v135, v156, v135, 1.0
	v_fma_f32 v153, v158, v153, 1.0
	v_mul_f32_e32 v135, v156, v135
	v_mul_f32_e32 v153, v158, v153
	v_mul_f32_e32 v135, 0xc0135761, v135
	v_mul_f32_e32 v153, 0xc0135761, v153
	v_exp_f32_e32 v135, v135
	v_exp_f32_e32 v153, v153
	v_add_f32_e32 v135, 1.0, v135
	v_add_f32_e32 v153, 1.0, v153
	v_rcp_f32_e32 v135, v135
	v_rcp_f32_e32 v153, v153
	v_mul_f32_e32 v135, v156, v135
	v_mul_f32_e32 v153, v158, v153
	v_mul_f32_e32 v156, 0x3d372713, v157
	v_mul_f32_e32 v158, 0x3d372713, v154
	v_fma_f32 v156, v157, v156, 1.0
	v_fma_f32 v158, v154, v158, 1.0
	v_mul_f32_e32 v156, v157, v156
	v_mul_f32_e32 v158, v154, v158
	v_mul_f32_e32 v156, 0xc0135761, v156
	v_mul_f32_e32 v158, 0xc0135761, v158
	v_exp_f32_e32 v156, v156
	v_exp_f32_e32 v158, v158
	v_add_f32_e32 v156, 1.0, v156
	v_add_f32_e32 v158, 1.0, v158
	v_rcp_f32_e32 v156, v156
	v_rcp_f32_e32 v158, v158
	v_mul_f32_e32 v156, v157, v156
	v_mul_f32_e32 v157, 0x3d372713, v159
	v_mul_f32_e32 v158, v154, v158
	v_mul_f32_e32 v154, 0x3d372713, v160
	v_fma_f32 v157, v159, v157, 1.0
	v_fma_f32 v154, v160, v154, 1.0
	v_mul_f32_e32 v157, v159, v157
	v_mul_f32_e32 v154, v160, v154
	v_mul_f32_e32 v157, 0xc0135761, v157
	v_mul_f32_e32 v154, 0xc0135761, v154
	v_exp_f32_e32 v157, v157
	v_exp_f32_e32 v154, v154
	v_add_f32_e32 v157, 1.0, v157
	v_add_f32_e32 v154, 1.0, v154
	v_rcp_f32_e32 v157, v157
	v_rcp_f32_e32 v154, v154
	v_mul_f32_e32 v157, v159, v157
	v_mul_f32_e32 v159, v160, v154
	v_mul_f32_e32 v154, 0x3d372713, v155
	v_fma_f32 v154, v155, v154, 1.0
	v_mul_f32_e32 v154, v155, v154
	v_mul_f32_e32 v154, 0xc0135761, v154
	v_exp_f32_e32 v154, v154
	s_nop 0
	v_add_f32_e32 v154, 1.0, v154
	v_rcp_f32_e32 v154, v154
	s_nop 0
	v_mul_f32_e32 v155, v155, v154
	v_mul_f32_e32 v154, 0x3d372713, v161
	v_fma_f32 v154, v161, v154, 1.0
	v_mul_f32_e32 v154, v161, v154
	v_mul_f32_e32 v154, 0xc0135761, v154
	v_exp_f32_e32 v154, v154
	s_nop 0
	v_add_f32_e32 v154, 1.0, v154
	v_rcp_f32_e32 v154, v154
	s_nop 0
	v_mul_f32_e32 v160, v161, v154
	v_cvt_pk_bf16_f32 v154, v135, v156
	v_add_u32_e32 v135, 0xb0, v190
	v_mad_i64_i32 v[148:149], s[6:7], v135, s66, v[148:149]
	v_subrev_u32_e32 v135, s21, v135
	v_lshl_add_u32 v135, v135, 2, s59
	v_cvt_pk_bf16_f32 v155, v158, v155
	v_cvt_pk_bf16_f32 v156, v153, v157
	v_cvt_pk_bf16_f32 v157, v159, v160
	ds_read_b32 v135, v135
	global_store_dwordx4 v[150:151], v[154:157], off offset:256 sc1
	v_lshl_add_u64 v[148:149], v[148:149], 0, v[130:131]
	s_mov_b64 s[6:7], 0
	s_waitcnt lgkmcnt(0)
	v_cvt_f32_u32_e32 v135, v135
	v_fmamk_f32 v135, v135, 0x35000000, v232
	v_rsq_f32_e32 v150, v135
	s_nop 0
	v_pk_fma_f32 v[156:157], v[14:15], v[150:151], v[182:183] op_sel_hi:[1,0,1]
	s_nop 0
	v_mul_f32_e32 v153, 0x3d372713, v157
	v_fma_f32 v153, v157, v153, 1.0
	v_mul_f32_e32 v153, v157, v153
	v_mul_f32_e32 v153, 0xc0135761, v153
	v_exp_f32_e32 v153, v153
	v_pk_fma_f32 v[154:155], v[16:17], v[150:151], v[174:175] op_sel_hi:[1,0,1]
	v_pk_fma_f32 v[158:159], v[12:13], v[150:151], v[186:187] op_sel_hi:[1,0,1]
	v_mul_f32_e32 v135, 0x3d372713, v156
	v_add_f32_e32 v153, 1.0, v153
	v_rcp_f32_e32 v153, v153
	v_fma_f32 v135, v156, v135, 1.0
	v_mul_f32_e32 v135, v156, v135
	v_mul_f32_e32 v135, 0xc0135761, v135
	v_mul_f32_e32 v153, v157, v153
	v_mul_f32_e32 v157, 0x3d372713, v154
	v_fma_f32 v157, v154, v157, 1.0
	v_mul_f32_e32 v157, v154, v157
	v_mul_f32_e32 v157, 0xc0135761, v157
	v_exp_f32_e32 v157, v157
	v_exp_f32_e32 v135, v135
	v_pk_fma_f32 v[160:161], v[10:11], v[150:151], v[188:189] op_sel_hi:[1,0,1]
	v_add_f32_e32 v157, 1.0, v157
	v_rcp_f32_e32 v157, v157
	v_add_f32_e32 v135, 1.0, v135
	v_rcp_f32_e32 v135, v135
	v_mul_f32_e32 v151, 0x3d372713, v160
	v_mul_f32_e32 v157, v154, v157
	v_mul_f32_e32 v154, 0x3d372713, v158
	v_fma_f32 v154, v158, v154, 1.0
	v_mul_f32_e32 v154, v158, v154
	v_mul_f32_e32 v154, 0xc0135761, v154
	v_exp_f32_e32 v154, v154
	v_mul_f32_e32 v135, v156, v135
	v_mul_f32_e32 v156, 0x3d372713, v161
	v_fma_f32 v156, v161, v156, 1.0
	v_add_f32_e32 v154, 1.0, v154
	v_rcp_f32_e32 v154, v154
	v_fma_f32 v151, v160, v151, 1.0
	v_mul_f32_e32 v156, v161, v156
	v_mul_f32_e32 v151, v160, v151
	v_mul_f32_e32 v158, v158, v154
	v_mul_f32_e32 v154, 0x3d372713, v155
	v_fma_f32 v154, v155, v154, 1.0
	v_mul_f32_e32 v154, v155, v154
	v_mul_f32_e32 v154, 0xc0135761, v154
	v_exp_f32_e32 v154, v154
	v_mul_f32_e32 v156, 0xc0135761, v156
	v_mul_f32_e32 v151, 0xc0135761, v151
	v_exp_f32_e32 v156, v156
	v_add_f32_e32 v154, 1.0, v154
	v_rcp_f32_e32 v154, v154
	v_exp_f32_e32 v151, v151
	v_add_f32_e32 v156, 1.0, v156
	v_rcp_f32_e32 v156, v156
	v_mul_f32_e32 v155, v155, v154
	v_mul_f32_e32 v154, 0x3d372713, v159
	v_fma_f32 v154, v159, v154, 1.0
	v_mul_f32_e32 v154, v159, v154
	v_mul_f32_e32 v154, 0xc0135761, v154
	v_exp_f32_e32 v154, v154
	v_add_f32_e32 v151, 1.0, v151
	v_rcp_f32_e32 v151, v151
	v_mul_f32_e32 v156, v161, v156
	v_add_f32_e32 v154, 1.0, v154
	v_rcp_f32_e32 v154, v154
	v_mul_f32_e32 v151, v160, v151
	v_mul_f32_e32 v159, v159, v154
	v_cvt_pk_bf16_f32 v154, v135, v153
	v_cvt_pk_bf16_f32 v155, v157, v155
	v_cvt_pk_bf16_f32 v156, v151, v156
	v_cvt_pk_bf16_f32 v157, v158, v159
	global_store_dwordx4 v[148:149], v[154:157], off sc1
	v_pk_fma_f32 v[158:159], v[4:5], v[150:151], v[178:179] op_sel_hi:[1,0,1]
	s_nop 0
	v_pk_fma_f32 v[156:157], v[6:7], v[150:151], v[184:185] op_sel_hi:[1,0,1]
	v_pk_fma_f32 v[154:155], v[8:9], v[150:151], v[176:177] op_sel_hi:[1,0,1]
	v_mul_f32_e32 v135, 0x3d372713, v156
	v_fma_f32 v135, v156, v135, 1.0
	v_mul_f32_e32 v135, v156, v135
	v_mul_f32_e32 v135, 0xc0135761, v135
	v_exp_f32_e32 v135, v135
	v_pk_fma_f32 v[150:151], v[2:3], v[150:151], v[180:181] op_sel_hi:[1,0,1]
	v_add_f32_e32 v135, 1.0, v135
	v_rcp_f32_e32 v135, v135
	v_mul_f32_e32 v153, 0x3d372713, v150
	v_fma_f32 v153, v150, v153, 1.0
	v_mul_f32_e32 v153, v150, v153
	v_mul_f32_e32 v135, v156, v135
	v_mul_f32_e32 v156, 0x3d372713, v151
	v_fma_f32 v156, v151, v156, 1.0
	v_mul_f32_e32 v156, v151, v156
	v_mul_f32_e32 v156, 0xc0135761, v156
	v_exp_f32_e32 v156, v156
	v_mul_f32_e32 v153, 0xc0135761, v153
	v_exp_f32_e32 v153, v153
	v_add_f32_e32 v156, 1.0, v156
	v_rcp_f32_e32 v156, v156
	v_add_f32_e32 v153, 1.0, v153
	v_rcp_f32_e32 v153, v153
	v_mul_f32_e32 v151, v151, v156
	v_mul_f32_e32 v156, 0x3d372713, v154
	v_fma_f32 v156, v154, v156, 1.0
	v_mul_f32_e32 v156, v154, v156
	v_mul_f32_e32 v156, 0xc0135761, v156
	v_exp_f32_e32 v156, v156
	v_mul_f32_e32 v150, v150, v153
	v_mul_f32_e32 v153, 0x3d372713, v157
	v_fma_f32 v153, v157, v153, 1.0
	v_add_f32_e32 v156, 1.0, v156
	v_rcp_f32_e32 v156, v156
	v_mul_f32_e32 v153, v157, v153
	v_mul_f32_e32 v153, 0xc0135761, v153
	v_exp_f32_e32 v153, v153
	v_mul_f32_e32 v156, v154, v156
	v_mul_f32_e32 v154, 0x3d372713, v158
	v_fma_f32 v154, v158, v154, 1.0
	v_mul_f32_e32 v154, v158, v154
	v_mul_f32_e32 v154, 0xc0135761, v154
	v_exp_f32_e32 v154, v154
	v_add_f32_e32 v153, 1.0, v153
	v_rcp_f32_e32 v153, v153
	v_add_f32_e32 v154, 1.0, v154
	v_rcp_f32_e32 v154, v154
	v_mul_f32_e32 v153, v157, v153
	v_mul_f32_e32 v157, v158, v154
	v_mul_f32_e32 v154, 0x3d372713, v155
	v_fma_f32 v154, v155, v154, 1.0
	v_mul_f32_e32 v154, v155, v154
	v_mul_f32_e32 v154, 0xc0135761, v154
	v_exp_f32_e32 v154, v154
	s_nop 0
	v_add_f32_e32 v154, 1.0, v154
	v_rcp_f32_e32 v154, v154
	s_nop 0
	v_mul_f32_e32 v155, v155, v154
	v_mul_f32_e32 v154, 0x3d372713, v159
	v_fma_f32 v154, v159, v154, 1.0
	v_mul_f32_e32 v154, v159, v154
	v_mul_f32_e32 v154, 0xc0135761, v154
	v_exp_f32_e32 v154, v154
	s_nop 0
	v_add_f32_e32 v154, 1.0, v154
	v_rcp_f32_e32 v154, v154
	s_nop 0
	v_mul_f32_e32 v158, v159, v154
	v_cvt_pk_bf16_f32 v154, v135, v153
	v_cvt_pk_bf16_f32 v155, v156, v155
	v_cvt_pk_bf16_f32 v156, v150, v151
	v_cvt_pk_bf16_f32 v157, v157, v158
	global_store_dwordx4 v[148:149], v[154:157], off offset:256 sc1
.LBB0_295:
	s_andn2_b64 vcc, exec, s[6:7]
	s_cbranch_vccnz .LBB0_297
	v_mov_b32_e32 v135, v134
	v_cvt_pk_bf16_f32 v148, v142, v143
	v_cvt_pk_bf16_f32 v149, v138, v139
	v_cvt_pk_bf16_f32 v150, v140, v141
	v_cvt_pk_bf16_f32 v151, v136, v137
	v_pk_fma_f32 v[136:137], v[120:121], v[134:135], v[176:177]
	v_pk_fma_f32 v[138:139], v[116:117], v[134:135], v[178:179]
	global_store_dwordx4 v[132:133], v[148:151], off sc1
	v_cvt_pk_bf16_f32 v134, v146, v147
	v_cvt_pk_bf16_f32 v135, v136, v137
	v_cvt_pk_bf16_f32 v136, v144, v145
	v_cvt_pk_bf16_f32 v137, v138, v139
	v_or_b32_e32 v139, 16, v190
	v_subrev_u32_e32 v138, s21, v139
	v_lshl_add_u32 v138, v138, 2, s59
	ds_read_b32 v138, v138
	global_store_dwordx4 v[132:133], v[134:137], off offset:256 sc1
	v_mov_b64_e32 v[132:133], s[52:53]
	s_waitcnt lgkmcnt(0)
	v_cvt_f32_u32_e32 v138, v138
	v_fmamk_f32 v134, v138, 0x35000000, v232
	v_rsq_f32_e32 v138, v134
	v_mad_i64_i32 v[134:135], s[6:7], v139, s66, v[132:133]
	v_lshl_add_u64 v[140:141], v[134:135], 0, v[130:131]
	v_pk_fma_f32 v[136:137], v[112:113], v[138:139], v[174:175] op_sel_hi:[1,0,1]
	v_pk_fma_f32 v[134:135], v[110:111], v[138:139], v[182:183] op_sel_hi:[1,0,1]
	v_pk_fma_f32 v[142:143], v[108:109], v[138:139], v[186:187] op_sel_hi:[1,0,1]
	v_pk_fma_f32 v[144:145], v[106:107], v[138:139], v[188:189] op_sel_hi:[1,0,1]
	v_cvt_pk_bf16_f32 v134, v134, v135
	v_cvt_pk_bf16_f32 v135, v136, v137
	s_nop 0
	v_cvt_pk_bf16_f32 v136, v144, v145
	v_cvt_pk_bf16_f32 v137, v142, v143
	global_store_dwordx4 v[140:141], v[134:137], off sc1
	v_pk_fma_f32 v[142:143], v[100:101], v[138:139], v[178:179] op_sel_hi:[1,0,1]
	s_nop 0
	v_pk_fma_f32 v[136:137], v[104:105], v[138:139], v[176:177] op_sel_hi:[1,0,1]
	v_pk_fma_f32 v[134:135], v[102:103], v[138:139], v[184:185] op_sel_hi:[1,0,1]
	v_pk_fma_f32 v[138:139], v[98:99], v[138:139], v[180:181] op_sel_hi:[1,0,1]
	v_cvt_pk_bf16_f32 v134, v134, v135
	v_cvt_pk_bf16_f32 v135, v136, v137
	s_nop 0
	v_cvt_pk_bf16_f32 v136, v138, v139
	v_or_b32_e32 v139, 32, v190
	v_subrev_u32_e32 v138, s21, v139
	v_lshl_add_u32 v138, v138, 2, s59
	v_cvt_pk_bf16_f32 v137, v142, v143
	ds_read_b32 v138, v138
	global_store_dwordx4 v[140:141], v[134:137], off offset:256 sc1
	s_waitcnt lgkmcnt(0)
	v_cvt_f32_u32_e32 v138, v138
	v_fmamk_f32 v134, v138, 0x35000000, v232
	v_rsq_f32_e32 v138, v134
	v_mad_i64_i32 v[134:135], s[6:7], v139, s66, v[132:133]
	v_lshl_add_u64 v[140:141], v[134:135], 0, v[130:131]
	v_pk_fma_f32 v[136:137], v[96:97], v[138:139], v[174:175] op_sel_hi:[1,0,1]
	v_pk_fma_f32 v[134:135], v[94:95], v[138:139], v[182:183] op_sel_hi:[1,0,1]
	v_pk_fma_f32 v[142:143], v[92:93], v[138:139], v[186:187] op_sel_hi:[1,0,1]
	v_pk_fma_f32 v[144:145], v[90:91], v[138:139], v[188:189] op_sel_hi:[1,0,1]
	v_cvt_pk_bf16_f32 v134, v134, v135
	v_cvt_pk_bf16_f32 v135, v136, v137
	s_nop 0
	v_cvt_pk_bf16_f32 v136, v144, v145
	v_cvt_pk_bf16_f32 v137, v142, v143
	global_store_dwordx4 v[140:141], v[134:137], off sc1
	v_pk_fma_f32 v[142:143], v[84:85], v[138:139], v[178:179] op_sel_hi:[1,0,1]
	s_nop 0
	v_pk_fma_f32 v[136:137], v[88:89], v[138:139], v[176:177] op_sel_hi:[1,0,1]
	v_pk_fma_f32 v[134:135], v[86:87], v[138:139], v[184:185] op_sel_hi:[1,0,1]
	v_pk_fma_f32 v[138:139], v[82:83], v[138:139], v[180:181] op_sel_hi:[1,0,1]
	v_cvt_pk_bf16_f32 v134, v134, v135
	v_cvt_pk_bf16_f32 v135, v136, v137
	s_nop 0
	v_cvt_pk_bf16_f32 v136, v138, v139
	v_or_b32_e32 v139, 48, v190
	v_subrev_u32_e32 v138, s21, v139
	v_lshl_add_u32 v138, v138, 2, s59
	v_cvt_pk_bf16_f32 v137, v142, v143
	ds_read_b32 v138, v138
	global_store_dwordx4 v[140:141], v[134:137], off offset:256 sc1
	s_waitcnt lgkmcnt(0)
	v_cvt_f32_u32_e32 v138, v138
	v_fmamk_f32 v134, v138, 0x35000000, v232
	v_rsq_f32_e32 v138, v134
	v_mad_i64_i32 v[134:135], s[6:7], v139, s66, v[132:133]
	v_lshl_add_u64 v[140:141], v[134:135], 0, v[130:131]
	v_pk_fma_f32 v[136:137], v[80:81], v[138:139], v[174:175] op_sel_hi:[1,0,1]
	v_pk_fma_f32 v[134:135], v[78:79], v[138:139], v[182:183] op_sel_hi:[1,0,1]
	v_pk_fma_f32 v[142:143], v[76:77], v[138:139], v[186:187] op_sel_hi:[1,0,1]
	v_pk_fma_f32 v[144:145], v[74:75], v[138:139], v[188:189] op_sel_hi:[1,0,1]
	v_cvt_pk_bf16_f32 v134, v134, v135
	v_cvt_pk_bf16_f32 v135, v136, v137
	s_nop 0
	v_cvt_pk_bf16_f32 v136, v144, v145
	v_cvt_pk_bf16_f32 v137, v142, v143
	global_store_dwordx4 v[140:141], v[134:137], off sc1
	v_pk_fma_f32 v[142:143], v[68:69], v[138:139], v[178:179] op_sel_hi:[1,0,1]
	s_nop 0
	v_pk_fma_f32 v[136:137], v[72:73], v[138:139], v[176:177] op_sel_hi:[1,0,1]
	v_pk_fma_f32 v[134:135], v[70:71], v[138:139], v[184:185] op_sel_hi:[1,0,1]
	v_pk_fma_f32 v[138:139], v[66:67], v[138:139], v[180:181] op_sel_hi:[1,0,1]
	v_cvt_pk_bf16_f32 v134, v134, v135
	v_cvt_pk_bf16_f32 v135, v136, v137
	s_nop 0
	v_cvt_pk_bf16_f32 v136, v138, v139
	v_add_u32_e32 v139, 0x80, v190
	v_subrev_u32_e32 v138, s21, v139
	v_lshl_add_u32 v138, v138, 2, s59
	v_cvt_pk_bf16_f32 v137, v142, v143
	ds_read_b32 v138, v138
	global_store_dwordx4 v[140:141], v[134:137], off offset:256 sc1
	s_waitcnt lgkmcnt(0)
	v_cvt_f32_u32_e32 v138, v138
	v_fmamk_f32 v134, v138, 0x35000000, v232
	v_rsq_f32_e32 v138, v134
	v_mad_i64_i32 v[134:135], s[6:7], v139, s66, v[132:133]
	v_lshl_add_u64 v[140:141], v[134:135], 0, v[130:131]
	v_pk_fma_f32 v[136:137], v[64:65], v[138:139], v[174:175] op_sel_hi:[1,0,1]
	v_pk_fma_f32 v[134:135], v[62:63], v[138:139], v[182:183] op_sel_hi:[1,0,1]
	v_pk_fma_f32 v[142:143], v[60:61], v[138:139], v[186:187] op_sel_hi:[1,0,1]
	v_pk_fma_f32 v[144:145], v[58:59], v[138:139], v[188:189] op_sel_hi:[1,0,1]
	v_cvt_pk_bf16_f32 v134, v134, v135
	v_cvt_pk_bf16_f32 v135, v136, v137
	s_nop 0
	v_cvt_pk_bf16_f32 v136, v144, v145
	v_cvt_pk_bf16_f32 v137, v142, v143
	global_store_dwordx4 v[140:141], v[134:137], off sc1
	v_pk_fma_f32 v[142:143], v[52:53], v[138:139], v[178:179] op_sel_hi:[1,0,1]
	s_nop 0
	v_pk_fma_f32 v[136:137], v[56:57], v[138:139], v[176:177] op_sel_hi:[1,0,1]
	v_pk_fma_f32 v[134:135], v[54:55], v[138:139], v[184:185] op_sel_hi:[1,0,1]
	v_pk_fma_f32 v[138:139], v[50:51], v[138:139], v[180:181] op_sel_hi:[1,0,1]
	v_cvt_pk_bf16_f32 v134, v134, v135
	v_cvt_pk_bf16_f32 v135, v136, v137
	s_nop 0
	v_cvt_pk_bf16_f32 v136, v138, v139
	v_add_u32_e32 v139, 0x90, v190
	v_subrev_u32_e32 v138, s21, v139
	v_lshl_add_u32 v138, v138, 2, s59
	v_cvt_pk_bf16_f32 v137, v142, v143
	ds_read_b32 v138, v138
	global_store_dwordx4 v[140:141], v[134:137], off offset:256 sc1
	s_waitcnt lgkmcnt(0)
	v_cvt_f32_u32_e32 v138, v138
	v_fmamk_f32 v134, v138, 0x35000000, v232
	v_rsq_f32_e32 v138, v134
	v_mad_i64_i32 v[134:135], s[6:7], v139, s66, v[132:133]
	v_lshl_add_u64 v[140:141], v[134:135], 0, v[130:131]
	v_pk_fma_f32 v[136:137], v[48:49], v[138:139], v[174:175] op_sel_hi:[1,0,1]
	v_pk_fma_f32 v[134:135], v[46:47], v[138:139], v[182:183] op_sel_hi:[1,0,1]
	v_pk_fma_f32 v[142:143], v[44:45], v[138:139], v[186:187] op_sel_hi:[1,0,1]
	v_pk_fma_f32 v[144:145], v[42:43], v[138:139], v[188:189] op_sel_hi:[1,0,1]
	v_cvt_pk_bf16_f32 v134, v134, v135
	v_cvt_pk_bf16_f32 v135, v136, v137
	s_nop 0
	v_cvt_pk_bf16_f32 v136, v144, v145
	v_cvt_pk_bf16_f32 v137, v142, v143
	global_store_dwordx4 v[140:141], v[134:137], off sc1
	v_pk_fma_f32 v[142:143], v[36:37], v[138:139], v[178:179] op_sel_hi:[1,0,1]
	s_nop 0
	v_pk_fma_f32 v[136:137], v[40:41], v[138:139], v[176:177] op_sel_hi:[1,0,1]
	v_pk_fma_f32 v[134:135], v[38:39], v[138:139], v[184:185] op_sel_hi:[1,0,1]
	v_pk_fma_f32 v[138:139], v[34:35], v[138:139], v[180:181] op_sel_hi:[1,0,1]
	v_cvt_pk_bf16_f32 v134, v134, v135
	v_cvt_pk_bf16_f32 v135, v136, v137
	s_nop 0
	v_cvt_pk_bf16_f32 v136, v138, v139
	v_add_u32_e32 v139, 0xa0, v190
	v_subrev_u32_e32 v138, s21, v139
	v_lshl_add_u32 v138, v138, 2, s59
	v_cvt_pk_bf16_f32 v137, v142, v143
	ds_read_b32 v138, v138
	global_store_dwordx4 v[140:141], v[134:137], off offset:256 sc1
	s_waitcnt lgkmcnt(0)
	v_cvt_f32_u32_e32 v138, v138
	v_fmamk_f32 v134, v138, 0x35000000, v232
	v_rsq_f32_e32 v138, v134
	v_mad_i64_i32 v[134:135], s[6:7], v139, s66, v[132:133]
	v_lshl_add_u64 v[140:141], v[134:135], 0, v[130:131]
	v_pk_fma_f32 v[136:137], v[32:33], v[138:139], v[174:175] op_sel_hi:[1,0,1]
	v_pk_fma_f32 v[134:135], v[30:31], v[138:139], v[182:183] op_sel_hi:[1,0,1]
	v_pk_fma_f32 v[142:143], v[28:29], v[138:139], v[186:187] op_sel_hi:[1,0,1]
	v_pk_fma_f32 v[144:145], v[26:27], v[138:139], v[188:189] op_sel_hi:[1,0,1]
	v_cvt_pk_bf16_f32 v134, v134, v135
	v_cvt_pk_bf16_f32 v135, v136, v137
	s_nop 0
	v_cvt_pk_bf16_f32 v136, v144, v145
	v_cvt_pk_bf16_f32 v137, v142, v143
	global_store_dwordx4 v[140:141], v[134:137], off sc1
	v_pk_fma_f32 v[142:143], v[20:21], v[138:139], v[178:179] op_sel_hi:[1,0,1]
	s_nop 0
	v_pk_fma_f32 v[136:137], v[24:25], v[138:139], v[176:177] op_sel_hi:[1,0,1]
	v_pk_fma_f32 v[134:135], v[22:23], v[138:139], v[184:185] op_sel_hi:[1,0,1]
	v_pk_fma_f32 v[138:139], v[18:19], v[138:139], v[180:181] op_sel_hi:[1,0,1]
	v_cvt_pk_bf16_f32 v134, v134, v135
	v_cvt_pk_bf16_f32 v135, v136, v137
	s_nop 0
	v_cvt_pk_bf16_f32 v136, v138, v139
	v_add_u32_e32 v138, 0xb0, v190
	v_subrev_u32_e32 v139, s21, v138
	v_lshl_add_u32 v139, v139, 2, s59
	v_cvt_pk_bf16_f32 v137, v142, v143
	ds_read_b32 v139, v139
	global_store_dwordx4 v[140:141], v[134:137], off offset:256 sc1
	v_mad_i64_i32 v[132:133], s[6:7], v138, s66, v[132:133]
	s_nop 0
	v_lshl_add_u64 v[136:137], v[132:133], 0, v[130:131]
	s_waitcnt lgkmcnt(0)
	v_cvt_f32_u32_e32 v139, v139
	v_fmamk_f32 v134, v139, 0x35000000, v232
	v_rsq_f32_e32 v134, v134
	s_nop 0
	v_pk_fma_f32 v[132:133], v[16:17], v[134:135], v[174:175] op_sel_hi:[1,0,1]
	v_pk_fma_f32 v[130:131], v[14:15], v[134:135], v[182:183] op_sel_hi:[1,0,1]
	v_pk_fma_f32 v[138:139], v[12:13], v[134:135], v[186:187] op_sel_hi:[1,0,1]
	v_pk_fma_f32 v[140:141], v[10:11], v[134:135], v[188:189] op_sel_hi:[1,0,1]
	v_cvt_pk_bf16_f32 v130, v130, v131
	v_cvt_pk_bf16_f32 v131, v132, v133
	s_nop 0
	v_cvt_pk_bf16_f32 v132, v140, v141
	v_cvt_pk_bf16_f32 v133, v138, v139
	global_store_dwordx4 v[136:137], v[130:133], off sc1
	v_pk_fma_f32 v[138:139], v[4:5], v[134:135], v[178:179] op_sel_hi:[1,0,1]
	s_nop 0
	v_pk_fma_f32 v[132:133], v[8:9], v[134:135], v[176:177] op_sel_hi:[1,0,1]
	v_pk_fma_f32 v[130:131], v[6:7], v[134:135], v[184:185] op_sel_hi:[1,0,1]
	v_pk_fma_f32 v[134:135], v[2:3], v[134:135], v[180:181] op_sel_hi:[1,0,1]
	v_cvt_pk_bf16_f32 v130, v130, v131
	v_cvt_pk_bf16_f32 v131, v132, v133
	s_nop 0
	v_cvt_pk_bf16_f32 v132, v134, v135
	v_cvt_pk_bf16_f32 v133, v138, v139
	global_store_dwordx4 v[136:137], v[130:133], off offset:256 sc1

.LBB0_303:
	v_lshl_add_u32 v191, v223, 2, s59
	ds_read_b32 v191, v191
	v_ashrrev_i32_e32 v193, 31, v192
	v_mov_b64_e32 v[212:213], s[52:53]
	v_mad_i64_i32 v[220:221], s[22:23], v190, s66, v[212:213]
	s_waitcnt lgkmcnt(0)
	v_cvt_f32_u32_e32 v191, v191
	v_lshlrev_b64 v[192:193], 1, v[192:193]
	v_lshl_add_u64 v[220:221], v[220:221], 0, v[192:193]
	s_and_b64 vcc, exec, s[6:7]
	v_fmamk_f32 v191, v191, 0x35000000, v232
	v_rsq_f32_e32 v218, v191
	s_nop 0
	v_pk_fma_f32 v[124:125], v[124:125], v[218:219], v[186:187] op_sel_hi:[1,0,1]
	v_pk_fma_f32 v[122:123], v[122:123], v[218:219], v[188:189] op_sel_hi:[1,0,1]
	v_pk_fma_f32 v[126:127], v[126:127], v[218:219], v[182:183] op_sel_hi:[1,0,1]
	v_pk_fma_f32 v[128:129], v[128:129], v[218:219], v[174:175] op_sel_hi:[1,0,1]
	s_waitcnt vmcnt(0)
	v_pk_mul_f32 v[224:225], v[154:155], v[122:123]
	v_pk_mul_f32 v[226:227], v[156:157], v[124:125]
	v_pk_mul_f32 v[122:123], v[158:159], v[122:123]
	v_pk_mul_f32 v[124:125], v[160:161], v[124:125]
	v_pk_fma_f32 v[226:227], v[160:161], v[128:129], v[226:227] neg_lo:[0,0,1] neg_hi:[0,0,1]
	v_pk_fma_f32 v[128:129], v[156:157], v[128:129], v[124:125]
	v_pk_fma_f32 v[124:125], v[154:155], v[126:127], v[122:123]
	v_pk_fma_f32 v[224:225], v[158:159], v[126:127], v[224:225] neg_lo:[0,0,1] neg_hi:[0,0,1]
	v_pk_fma_f32 v[116:117], v[116:117], v[218:219], v[178:179] op_sel_hi:[1,0,1]
	v_cvt_pk_bf16_f32 v122, v224, v225
	v_cvt_pk_bf16_f32 v123, v226, v227
	v_cvt_pk_bf16_f32 v124, v124, v125
	v_cvt_pk_bf16_f32 v125, v128, v129
	v_pk_fma_f32 v[114:115], v[114:115], v[218:219], v[180:181] op_sel_hi:[1,0,1]
	global_store_dwordx4 v[220:221], v[122:125], off sc1
	v_pk_fma_f32 v[118:119], v[118:119], v[218:219], v[184:185] op_sel_hi:[1,0,1]
	v_pk_fma_f32 v[120:121], v[120:121], v[218:219], v[176:177] op_sel_hi:[1,0,1]
	v_pk_mul_f32 v[122:123], v[154:155], v[114:115]
	v_pk_mul_f32 v[124:125], v[156:157], v[116:117]
	v_pk_mul_f32 v[114:115], v[158:159], v[114:115]
	v_pk_mul_f32 v[116:117], v[160:161], v[116:117]
	v_pk_fma_f32 v[124:125], v[160:161], v[120:121], v[124:125] neg_lo:[0,0,1] neg_hi:[0,0,1]
	v_pk_fma_f32 v[122:123], v[158:159], v[118:119], v[122:123] neg_lo:[0,0,1] neg_hi:[0,0,1]
	v_pk_fma_f32 v[120:121], v[156:157], v[120:121], v[116:117]
	v_pk_fma_f32 v[116:117], v[154:155], v[118:119], v[114:115]
	v_subrev_u32_e32 v118, s21, v214
	v_lshl_add_u32 v118, v118, 2, s59
	v_cvt_pk_bf16_f32 v114, v122, v123
	v_cvt_pk_bf16_f32 v115, v124, v125
	v_cvt_pk_bf16_f32 v116, v116, v117
	v_cvt_pk_bf16_f32 v117, v120, v121
	ds_read_b32 v118, v118
	global_store_dwordx4 v[220:221], v[114:117], off offset:256 sc1
	s_nop 1
	v_mad_u64_u32 v[114:115], s[22:23], v216, s66, v[212:213]
	s_waitcnt lgkmcnt(0)
	v_cvt_f32_u32_e32 v117, v118
	v_mov_b32_e32 v116, v115
	v_fmamk_f32 v115, v117, 0x35000000, v232
	v_rsq_f32_e32 v118, v115
	v_mad_u64_u32 v[116:117], s[22:23], v217, s66, v[116:117]
	v_mov_b32_e32 v115, v116
	v_pk_fma_f32 v[108:109], v[108:109], v[118:119], v[186:187] op_sel_hi:[1,0,1]
	v_pk_fma_f32 v[106:107], v[106:107], v[118:119], v[188:189] op_sel_hi:[1,0,1]
	v_pk_fma_f32 v[110:111], v[110:111], v[118:119], v[182:183] op_sel_hi:[1,0,1]
	v_pk_fma_f32 v[112:113], v[112:113], v[118:119], v[174:175] op_sel_hi:[1,0,1]
	v_pk_mul_f32 v[116:117], v[146:147], v[106:107]
	v_pk_mul_f32 v[120:121], v[148:149], v[108:109]
	v_pk_mul_f32 v[106:107], v[150:151], v[106:107]
	v_pk_mul_f32 v[108:109], v[152:153], v[108:109]
	v_pk_fma_f32 v[120:121], v[152:153], v[112:113], v[120:121] neg_lo:[0,0,1] neg_hi:[0,0,1]
	v_pk_fma_f32 v[112:113], v[148:149], v[112:113], v[108:109]
	v_pk_fma_f32 v[108:109], v[146:147], v[110:111], v[106:107]
	v_lshl_add_u64 v[114:115], v[114:115], 0, v[192:193]
	v_pk_fma_f32 v[116:117], v[150:151], v[110:111], v[116:117] neg_lo:[0,0,1] neg_hi:[0,0,1]
	v_pk_fma_f32 v[100:101], v[100:101], v[118:119], v[178:179] op_sel_hi:[1,0,1]
	v_cvt_pk_bf16_f32 v106, v116, v117
	v_cvt_pk_bf16_f32 v107, v120, v121
	v_cvt_pk_bf16_f32 v108, v108, v109
	v_cvt_pk_bf16_f32 v109, v112, v113
	v_pk_fma_f32 v[98:99], v[98:99], v[118:119], v[180:181] op_sel_hi:[1,0,1]
	global_store_dwordx4 v[114:115], v[106:109], off sc1
	v_pk_fma_f32 v[102:103], v[102:103], v[118:119], v[184:185] op_sel_hi:[1,0,1]
	v_pk_fma_f32 v[104:105], v[104:105], v[118:119], v[176:177] op_sel_hi:[1,0,1]
	v_pk_mul_f32 v[106:107], v[146:147], v[98:99]
	v_pk_mul_f32 v[108:109], v[148:149], v[100:101]
	v_pk_mul_f32 v[98:99], v[150:151], v[98:99]
	v_pk_mul_f32 v[100:101], v[152:153], v[100:101]
	v_pk_fma_f32 v[108:109], v[152:153], v[104:105], v[108:109] neg_lo:[0,0,1] neg_hi:[0,0,1]
	v_pk_fma_f32 v[106:107], v[150:151], v[102:103], v[106:107] neg_lo:[0,0,1] neg_hi:[0,0,1]
	v_pk_fma_f32 v[104:105], v[148:149], v[104:105], v[100:101]
	v_pk_fma_f32 v[100:101], v[146:147], v[102:103], v[98:99]
	v_subrev_u32_e32 v102, s21, v208
	v_lshl_add_u32 v102, v102, 2, s59
	v_cvt_pk_bf16_f32 v98, v106, v107
	v_cvt_pk_bf16_f32 v99, v108, v109
	v_cvt_pk_bf16_f32 v100, v100, v101
	v_cvt_pk_bf16_f32 v101, v104, v105
	ds_read_b32 v102, v102
	global_store_dwordx4 v[114:115], v[98:101], off offset:256 sc1
	v_add_u32_e32 v106, 0x90, v190
	v_add_u32_e32 v114, 0xa0, v190
	v_mad_u64_u32 v[98:99], s[22:23], v210, s66, v[212:213]
	s_waitcnt lgkmcnt(0)
	v_cvt_f32_u32_e32 v101, v102
	v_mov_b32_e32 v100, v99
	v_add_u32_e32 v116, 0xb0, v190
	v_fmamk_f32 v99, v101, 0x35000000, v232
	v_rsq_f32_e32 v102, v99
	v_mad_u64_u32 v[100:101], s[22:23], v211, s66, v[100:101]
	v_mov_b32_e32 v99, v100
	v_pk_fma_f32 v[92:93], v[92:93], v[102:103], v[186:187] op_sel_hi:[1,0,1]
	v_pk_fma_f32 v[90:91], v[90:91], v[102:103], v[188:189] op_sel_hi:[1,0,1]
	v_pk_fma_f32 v[94:95], v[94:95], v[102:103], v[182:183] op_sel_hi:[1,0,1]
	v_pk_fma_f32 v[96:97], v[96:97], v[102:103], v[174:175] op_sel_hi:[1,0,1]
	v_pk_mul_f32 v[100:101], v[138:139], v[90:91]
	v_pk_mul_f32 v[104:105], v[140:141], v[92:93]
	v_pk_mul_f32 v[90:91], v[142:143], v[90:91]
	v_pk_mul_f32 v[92:93], v[144:145], v[92:93]
	v_pk_fma_f32 v[104:105], v[144:145], v[96:97], v[104:105] neg_lo:[0,0,1] neg_hi:[0,0,1]
	v_pk_fma_f32 v[96:97], v[140:141], v[96:97], v[92:93]
	v_pk_fma_f32 v[92:93], v[138:139], v[94:95], v[90:91]
	v_lshl_add_u64 v[98:99], v[98:99], 0, v[192:193]
	v_pk_fma_f32 v[100:101], v[142:143], v[94:95], v[100:101] neg_lo:[0,0,1] neg_hi:[0,0,1]
	v_pk_fma_f32 v[84:85], v[84:85], v[102:103], v[178:179] op_sel_hi:[1,0,1]
	v_cvt_pk_bf16_f32 v90, v100, v101
	v_cvt_pk_bf16_f32 v91, v104, v105
	v_cvt_pk_bf16_f32 v92, v92, v93
	v_cvt_pk_bf16_f32 v93, v96, v97
	v_pk_fma_f32 v[82:83], v[82:83], v[102:103], v[180:181] op_sel_hi:[1,0,1]
	global_store_dwordx4 v[98:99], v[90:93], off sc1
	v_pk_fma_f32 v[86:87], v[86:87], v[102:103], v[184:185] op_sel_hi:[1,0,1]
	v_pk_fma_f32 v[88:89], v[88:89], v[102:103], v[176:177] op_sel_hi:[1,0,1]
	v_pk_mul_f32 v[90:91], v[138:139], v[82:83]
	v_pk_mul_f32 v[92:93], v[140:141], v[84:85]
	v_pk_mul_f32 v[82:83], v[142:143], v[82:83]
	v_pk_mul_f32 v[84:85], v[144:145], v[84:85]
	v_pk_fma_f32 v[92:93], v[144:145], v[88:89], v[92:93] neg_lo:[0,0,1] neg_hi:[0,0,1]
	v_pk_fma_f32 v[90:91], v[142:143], v[86:87], v[90:91] neg_lo:[0,0,1] neg_hi:[0,0,1]
	v_pk_fma_f32 v[88:89], v[140:141], v[88:89], v[84:85]
	v_pk_fma_f32 v[84:85], v[138:139], v[86:87], v[82:83]
	v_subrev_u32_e32 v86, s21, v204
	v_lshl_add_u32 v86, v86, 2, s59
	v_cvt_pk_bf16_f32 v82, v90, v91
	v_cvt_pk_bf16_f32 v83, v92, v93
	v_cvt_pk_bf16_f32 v84, v84, v85
	v_cvt_pk_bf16_f32 v85, v88, v89
	ds_read_b32 v86, v86
	global_store_dwordx4 v[98:99], v[82:85], off offset:256 sc1
	s_nop 1
	v_mad_u64_u32 v[82:83], s[22:23], v206, s66, v[212:213]
	s_waitcnt lgkmcnt(0)
	v_cvt_f32_u32_e32 v85, v86
	v_mov_b32_e32 v84, v83
	v_fmamk_f32 v83, v85, 0x35000000, v232
	v_rsq_f32_e32 v86, v83
	v_mad_u64_u32 v[84:85], s[22:23], v207, s66, v[84:85]
	v_mov_b32_e32 v83, v84
	v_pk_fma_f32 v[76:77], v[76:77], v[86:87], v[186:187] op_sel_hi:[1,0,1]
	v_pk_fma_f32 v[74:75], v[74:75], v[86:87], v[188:189] op_sel_hi:[1,0,1]
	v_pk_fma_f32 v[78:79], v[78:79], v[86:87], v[182:183] op_sel_hi:[1,0,1]
	v_pk_fma_f32 v[80:81], v[80:81], v[86:87], v[174:175] op_sel_hi:[1,0,1]
	v_pk_mul_f32 v[84:85], v[134:135], v[74:75]
	v_pk_mul_f32 v[88:89], v[136:137], v[76:77]
	v_pk_mul_f32 v[74:75], v[130:131], v[74:75]
	v_pk_mul_f32 v[76:77], v[132:133], v[76:77]
	v_pk_fma_f32 v[88:89], v[132:133], v[80:81], v[88:89] neg_lo:[0,0,1] neg_hi:[0,0,1]
	v_pk_fma_f32 v[80:81], v[136:137], v[80:81], v[76:77]
	v_pk_fma_f32 v[76:77], v[134:135], v[78:79], v[74:75]
	v_lshl_add_u64 v[82:83], v[82:83], 0, v[192:193]
	v_pk_fma_f32 v[84:85], v[130:131], v[78:79], v[84:85] neg_lo:[0,0,1] neg_hi:[0,0,1]
	v_pk_fma_f32 v[68:69], v[68:69], v[86:87], v[178:179] op_sel_hi:[1,0,1]
	v_cvt_pk_bf16_f32 v74, v84, v85
	v_cvt_pk_bf16_f32 v75, v88, v89
	v_cvt_pk_bf16_f32 v76, v76, v77
	v_cvt_pk_bf16_f32 v77, v80, v81
	v_pk_fma_f32 v[66:67], v[66:67], v[86:87], v[180:181] op_sel_hi:[1,0,1]
	global_store_dwordx4 v[82:83], v[74:77], off sc1
	v_pk_fma_f32 v[70:71], v[70:71], v[86:87], v[184:185] op_sel_hi:[1,0,1]
	v_pk_fma_f32 v[72:73], v[72:73], v[86:87], v[176:177] op_sel_hi:[1,0,1]
	v_pk_mul_f32 v[74:75], v[134:135], v[66:67]
	v_pk_mul_f32 v[76:77], v[136:137], v[68:69]
	v_pk_mul_f32 v[66:67], v[130:131], v[66:67]
	v_pk_mul_f32 v[68:69], v[132:133], v[68:69]
	v_pk_fma_f32 v[76:77], v[132:133], v[72:73], v[76:77] neg_lo:[0,0,1] neg_hi:[0,0,1]
	v_pk_fma_f32 v[72:73], v[136:137], v[72:73], v[68:69]
	v_pk_fma_f32 v[68:69], v[134:135], v[70:71], v[66:67]
	v_pk_fma_f32 v[74:75], v[130:131], v[70:71], v[74:75] neg_lo:[0,0,1] neg_hi:[0,0,1]
	s_nop 0
	v_cvt_pk_bf16_f32 v66, v74, v75
	v_cvt_pk_bf16_f32 v67, v76, v77
	v_cvt_pk_bf16_f32 v68, v68, v69
	v_cvt_pk_bf16_f32 v69, v72, v73
	global_store_dwordx4 v[82:83], v[66:69], off offset:256 sc1
	s_cbranch_vccnz .LBB0_306
	v_add_u32_e32 v108, 0x90, v190
	v_add_u32_e32 v102, 0xa0, v190
	v_add_u32_e32 v98, 0xb0, v190
	v_ashrrev_i32_e32 v109, 31, v108
	v_ashrrev_i32_e32 v103, 31, v102
	v_ashrrev_i32_e32 v99, 31, v98
	v_mov_b64_e32 v[110:111], v[108:109]
	v_mov_b64_e32 v[104:105], v[102:103]
	v_mov_b64_e32 v[100:101], v[98:99]
	v_add_u32_e32 v112, 0x80, v190
	v_ashrrev_i32_e32 v113, 31, v112
	s_cbranch_execnz .LBB0_307

.LBB0_308:
	v_subrev_u32_e32 v99, s21, v112
	v_lshl_add_u32 v99, v99, 2, s59
	ds_read_b32 v99, v99
	v_mov_b64_e32 v[106:107], s[52:53]
	v_mad_i64_i32 v[112:113], s[6:7], v112, s66, v[106:107]
	v_lshl_add_u64 v[112:113], v[112:113], 0, v[192:193]
	s_waitcnt lgkmcnt(0)
	v_cvt_f32_u32_e32 v99, v99
	v_fmamk_f32 v99, v99, 0x35000000, v232
	v_rsq_f32_e32 v114, v99
	s_nop 0
	v_pk_fma_f32 v[60:61], v[60:61], v[114:115], v[186:187] op_sel_hi:[1,0,1]
	v_pk_fma_f32 v[58:59], v[58:59], v[114:115], v[188:189] op_sel_hi:[1,0,1]
	v_pk_fma_f32 v[62:63], v[62:63], v[114:115], v[182:183] op_sel_hi:[1,0,1]
	v_pk_fma_f32 v[64:65], v[64:65], v[114:115], v[174:175] op_sel_hi:[1,0,1]
	s_waitcnt vmcnt(6)
	v_pk_mul_f32 v[116:117], v[90:91], v[58:59]
	v_pk_mul_f32 v[118:119], v[92:93], v[60:61]
	v_pk_mul_f32 v[58:59], v[94:95], v[58:59]
	v_pk_mul_f32 v[60:61], v[96:97], v[60:61]
	v_pk_fma_f32 v[118:119], v[96:97], v[64:65], v[118:119] neg_lo:[0,0,1] neg_hi:[0,0,1]
	v_pk_fma_f32 v[64:65], v[92:93], v[64:65], v[60:61]
	v_pk_fma_f32 v[60:61], v[90:91], v[62:63], v[58:59]
	v_pk_fma_f32 v[116:117], v[94:95], v[62:63], v[116:117] neg_lo:[0,0,1] neg_hi:[0,0,1]
	v_pk_fma_f32 v[52:53], v[52:53], v[114:115], v[178:179] op_sel_hi:[1,0,1]
	v_cvt_pk_bf16_f32 v58, v116, v117
	v_cvt_pk_bf16_f32 v59, v118, v119
	v_cvt_pk_bf16_f32 v60, v60, v61
	v_cvt_pk_bf16_f32 v61, v64, v65
	v_pk_fma_f32 v[50:51], v[50:51], v[114:115], v[180:181] op_sel_hi:[1,0,1]
	global_store_dwordx4 v[112:113], v[58:61], off sc1
	v_pk_fma_f32 v[54:55], v[54:55], v[114:115], v[184:185] op_sel_hi:[1,0,1]
	v_pk_fma_f32 v[56:57], v[56:57], v[114:115], v[176:177] op_sel_hi:[1,0,1]
	v_pk_mul_f32 v[58:59], v[90:91], v[50:51]
	v_pk_mul_f32 v[60:61], v[92:93], v[52:53]
	v_pk_mul_f32 v[50:51], v[94:95], v[50:51]
	v_pk_mul_f32 v[52:53], v[96:97], v[52:53]
	v_pk_fma_f32 v[60:61], v[96:97], v[56:57], v[60:61] neg_lo:[0,0,1] neg_hi:[0,0,1]
	v_pk_fma_f32 v[58:59], v[94:95], v[54:55], v[58:59] neg_lo:[0,0,1] neg_hi:[0,0,1]
	v_pk_fma_f32 v[56:57], v[92:93], v[56:57], v[52:53]
	v_pk_fma_f32 v[52:53], v[90:91], v[54:55], v[50:51]
	v_subrev_u32_e32 v54, s21, v108
	v_lshl_add_u32 v54, v54, 2, s59
	v_cvt_pk_bf16_f32 v50, v58, v59
	v_cvt_pk_bf16_f32 v51, v60, v61
	v_cvt_pk_bf16_f32 v52, v52, v53
	v_cvt_pk_bf16_f32 v53, v56, v57
	ds_read_b32 v54, v54
	global_store_dwordx4 v[112:113], v[50:53], off offset:256 sc1
	s_nop 1
	v_mad_u64_u32 v[50:51], s[6:7], v110, s66, v[106:107]
	s_waitcnt lgkmcnt(0)
	v_cvt_f32_u32_e32 v53, v54
	v_mov_b32_e32 v52, v51
	v_fmamk_f32 v51, v53, 0x35000000, v232
	v_rsq_f32_e32 v54, v51
	v_mad_u64_u32 v[52:53], s[6:7], v111, s66, v[52:53]
	v_mov_b32_e32 v51, v52
	v_pk_fma_f32 v[44:45], v[44:45], v[54:55], v[186:187] op_sel_hi:[1,0,1]
	v_pk_fma_f32 v[42:43], v[42:43], v[54:55], v[188:189] op_sel_hi:[1,0,1]
	v_pk_fma_f32 v[46:47], v[46:47], v[54:55], v[182:183] op_sel_hi:[1,0,1]
	v_pk_fma_f32 v[48:49], v[48:49], v[54:55], v[174:175] op_sel_hi:[1,0,1]
	s_waitcnt vmcnt(6)
	v_pk_mul_f32 v[52:53], v[82:83], v[42:43]
	v_pk_mul_f32 v[56:57], v[84:85], v[44:45]
	v_pk_mul_f32 v[42:43], v[86:87], v[42:43]
	v_pk_mul_f32 v[44:45], v[88:89], v[44:45]
	v_pk_fma_f32 v[56:57], v[88:89], v[48:49], v[56:57] neg_lo:[0,0,1] neg_hi:[0,0,1]
	v_pk_fma_f32 v[48:49], v[84:85], v[48:49], v[44:45]
	v_pk_fma_f32 v[44:45], v[82:83], v[46:47], v[42:43]
	v_lshl_add_u64 v[50:51], v[50:51], 0, v[192:193]
	v_pk_fma_f32 v[52:53], v[86:87], v[46:47], v[52:53] neg_lo:[0,0,1] neg_hi:[0,0,1]
	v_pk_fma_f32 v[36:37], v[36:37], v[54:55], v[178:179] op_sel_hi:[1,0,1]
	v_cvt_pk_bf16_f32 v42, v52, v53
	v_cvt_pk_bf16_f32 v43, v56, v57
	v_cvt_pk_bf16_f32 v44, v44, v45
	v_cvt_pk_bf16_f32 v45, v48, v49
	v_pk_fma_f32 v[34:35], v[34:35], v[54:55], v[180:181] op_sel_hi:[1,0,1]
	global_store_dwordx4 v[50:51], v[42:45], off sc1
	v_pk_fma_f32 v[38:39], v[38:39], v[54:55], v[184:185] op_sel_hi:[1,0,1]
	v_pk_fma_f32 v[40:41], v[40:41], v[54:55], v[176:177] op_sel_hi:[1,0,1]
	v_pk_mul_f32 v[42:43], v[82:83], v[34:35]
	v_pk_mul_f32 v[44:45], v[84:85], v[36:37]
	v_pk_mul_f32 v[34:35], v[86:87], v[34:35]
	v_pk_mul_f32 v[36:37], v[88:89], v[36:37]
	v_pk_fma_f32 v[44:45], v[88:89], v[40:41], v[44:45] neg_lo:[0,0,1] neg_hi:[0,0,1]
	v_pk_fma_f32 v[42:43], v[86:87], v[38:39], v[42:43] neg_lo:[0,0,1] neg_hi:[0,0,1]
	v_pk_fma_f32 v[40:41], v[84:85], v[40:41], v[36:37]
	v_pk_fma_f32 v[36:37], v[82:83], v[38:39], v[34:35]
	v_subrev_u32_e32 v38, s21, v102
	v_lshl_add_u32 v38, v38, 2, s59
	v_cvt_pk_bf16_f32 v34, v42, v43
	v_cvt_pk_bf16_f32 v35, v44, v45
	v_cvt_pk_bf16_f32 v36, v36, v37
	v_cvt_pk_bf16_f32 v37, v40, v41
	ds_read_b32 v38, v38
	global_store_dwordx4 v[50:51], v[34:37], off offset:256 sc1
	s_nop 1
	v_mad_u64_u32 v[34:35], s[6:7], v104, s66, v[106:107]
	s_waitcnt lgkmcnt(0)
	v_cvt_f32_u32_e32 v37, v38
	v_mov_b32_e32 v36, v35
	v_fmamk_f32 v35, v37, 0x35000000, v232
	v_rsq_f32_e32 v38, v35
	v_mad_u64_u32 v[36:37], s[6:7], v105, s66, v[36:37]
	v_mov_b32_e32 v35, v36
	v_pk_fma_f32 v[28:29], v[28:29], v[38:39], v[186:187] op_sel_hi:[1,0,1]
	v_pk_fma_f32 v[26:27], v[26:27], v[38:39], v[188:189] op_sel_hi:[1,0,1]
	v_pk_fma_f32 v[30:31], v[30:31], v[38:39], v[182:183] op_sel_hi:[1,0,1]
	v_pk_fma_f32 v[32:33], v[32:33], v[38:39], v[174:175] op_sel_hi:[1,0,1]
	s_waitcnt vmcnt(6)
	v_pk_mul_f32 v[36:37], v[74:75], v[26:27]
	v_pk_mul_f32 v[40:41], v[76:77], v[28:29]
	v_pk_mul_f32 v[26:27], v[78:79], v[26:27]
	v_pk_mul_f32 v[28:29], v[80:81], v[28:29]
	v_pk_fma_f32 v[40:41], v[80:81], v[32:33], v[40:41] neg_lo:[0,0,1] neg_hi:[0,0,1]
	v_pk_fma_f32 v[32:33], v[76:77], v[32:33], v[28:29]
	v_pk_fma_f32 v[28:29], v[74:75], v[30:31], v[26:27]
	v_lshl_add_u64 v[34:35], v[34:35], 0, v[192:193]
	v_pk_fma_f32 v[36:37], v[78:79], v[30:31], v[36:37] neg_lo:[0,0,1] neg_hi:[0,0,1]
	v_pk_fma_f32 v[20:21], v[20:21], v[38:39], v[178:179] op_sel_hi:[1,0,1]
	v_cvt_pk_bf16_f32 v26, v36, v37
	v_cvt_pk_bf16_f32 v27, v40, v41
	v_cvt_pk_bf16_f32 v28, v28, v29
	v_cvt_pk_bf16_f32 v29, v32, v33
	v_pk_fma_f32 v[18:19], v[18:19], v[38:39], v[180:181] op_sel_hi:[1,0,1]
	global_store_dwordx4 v[34:35], v[26:29], off sc1
	v_pk_fma_f32 v[22:23], v[22:23], v[38:39], v[184:185] op_sel_hi:[1,0,1]
	v_pk_fma_f32 v[24:25], v[24:25], v[38:39], v[176:177] op_sel_hi:[1,0,1]
	v_pk_mul_f32 v[26:27], v[74:75], v[18:19]
	v_pk_mul_f32 v[28:29], v[76:77], v[20:21]
	v_pk_mul_f32 v[18:19], v[78:79], v[18:19]
	v_pk_mul_f32 v[20:21], v[80:81], v[20:21]
	v_pk_fma_f32 v[28:29], v[80:81], v[24:25], v[28:29] neg_lo:[0,0,1] neg_hi:[0,0,1]
	v_pk_fma_f32 v[26:27], v[78:79], v[22:23], v[26:27] neg_lo:[0,0,1] neg_hi:[0,0,1]
	v_pk_fma_f32 v[24:25], v[76:77], v[24:25], v[20:21]
	v_pk_fma_f32 v[20:21], v[74:75], v[22:23], v[18:19]
	v_subrev_u32_e32 v22, s21, v98
	v_lshl_add_u32 v22, v22, 2, s59
	v_cvt_pk_bf16_f32 v18, v26, v27
	v_cvt_pk_bf16_f32 v19, v28, v29
	v_cvt_pk_bf16_f32 v20, v20, v21
	v_cvt_pk_bf16_f32 v21, v24, v25
	ds_read_b32 v22, v22
	global_store_dwordx4 v[34:35], v[18:21], off offset:256 sc1
	s_nop 1
	v_mad_u64_u32 v[18:19], s[6:7], v100, s66, v[106:107]
	s_waitcnt lgkmcnt(0)
	v_cvt_f32_u32_e32 v21, v22
	v_mov_b32_e32 v20, v19
	v_fmamk_f32 v19, v21, 0x35000000, v232
	v_rsq_f32_e32 v22, v19
	v_mad_u64_u32 v[20:21], s[6:7], v101, s66, v[20:21]
	v_mov_b32_e32 v19, v20
	v_pk_fma_f32 v[12:13], v[12:13], v[22:23], v[186:187] op_sel_hi:[1,0,1]
	v_pk_fma_f32 v[10:11], v[10:11], v[22:23], v[188:189] op_sel_hi:[1,0,1]
	v_pk_fma_f32 v[14:15], v[14:15], v[22:23], v[182:183] op_sel_hi:[1,0,1]
	v_pk_fma_f32 v[16:17], v[16:17], v[22:23], v[174:175] op_sel_hi:[1,0,1]
	s_waitcnt vmcnt(6)
	v_pk_mul_f32 v[20:21], v[70:71], v[10:11]
	v_pk_mul_f32 v[24:25], v[72:73], v[12:13]
	v_pk_mul_f32 v[10:11], v[66:67], v[10:11]
	v_pk_mul_f32 v[12:13], v[68:69], v[12:13]
	v_pk_fma_f32 v[24:25], v[68:69], v[16:17], v[24:25] neg_lo:[0,0,1] neg_hi:[0,0,1]
	v_pk_fma_f32 v[16:17], v[72:73], v[16:17], v[12:13]
	v_pk_fma_f32 v[12:13], v[70:71], v[14:15], v[10:11]
	v_lshl_add_u64 v[18:19], v[18:19], 0, v[192:193]
	v_pk_fma_f32 v[20:21], v[66:67], v[14:15], v[20:21] neg_lo:[0,0,1] neg_hi:[0,0,1]
	v_pk_fma_f32 v[4:5], v[4:5], v[22:23], v[178:179] op_sel_hi:[1,0,1]
	v_cvt_pk_bf16_f32 v10, v20, v21
	v_cvt_pk_bf16_f32 v11, v24, v25
	v_cvt_pk_bf16_f32 v12, v12, v13
	v_cvt_pk_bf16_f32 v13, v16, v17
	v_pk_fma_f32 v[2:3], v[2:3], v[22:23], v[180:181] op_sel_hi:[1,0,1]
	global_store_dwordx4 v[18:19], v[10:13], off sc1
	v_pk_fma_f32 v[6:7], v[6:7], v[22:23], v[184:185] op_sel_hi:[1,0,1]
	v_pk_fma_f32 v[8:9], v[8:9], v[22:23], v[176:177] op_sel_hi:[1,0,1]
	v_pk_mul_f32 v[10:11], v[70:71], v[2:3]
	v_pk_mul_f32 v[12:13], v[72:73], v[4:5]
	v_pk_mul_f32 v[2:3], v[66:67], v[2:3]
	v_pk_mul_f32 v[4:5], v[68:69], v[4:5]
	v_pk_fma_f32 v[12:13], v[68:69], v[8:9], v[12:13] neg_lo:[0,0,1] neg_hi:[0,0,1]
	v_pk_fma_f32 v[8:9], v[72:73], v[8:9], v[4:5]
	v_pk_fma_f32 v[4:5], v[70:71], v[6:7], v[2:3]
	v_pk_fma_f32 v[10:11], v[66:67], v[6:7], v[10:11] neg_lo:[0,0,1] neg_hi:[0,0,1]
	s_nop 0
	v_cvt_pk_bf16_f32 v2, v10, v11
	v_cvt_pk_bf16_f32 v3, v12, v13
	v_cvt_pk_bf16_f32 v4, v4, v5
	v_cvt_pk_bf16_f32 v5, v8, v9
	global_store_dwordx4 v[18:19], v[2:5], off offset:256 sc1
	s_andn2_b64 vcc, exec, s[4:5]
	s_mov_b64 s[4:5], -1
	s_cbranch_vccnz .LBB0_281

.LBB0_514:
	v_mov_b32_e32 v70, v0
	s_lshl_b32 s0, s40, 8
	s_add_i32 s0, s0, s54
	v_bfe_u32 v239, v70, 4, 2
	v_and_or_b32 v228, v70, 15, s0
	s_or_b32 s0, s64, s67
	v_lshlrev_b32_e32 v70, 3, v239
	v_or_b32_e32 v214, s0, v70
	v_or_b32_e32 v70, s67, v70
	v_ashrrev_i32_e32 v215, 31, v214
	v_ashrrev_i32_e32 v229, 31, v228
	v_lshlrev_b32_e32 v238, 2, v70
	v_lshl_add_u64 v[70:71], v[214:215], 1, s[10:11]
	v_lshlrev_b64 v[72:73], 12, v[228:229]
	v_lshl_add_u64 v[72:73], v[70:71], 0, v[72:73]
	global_load_dwordx4 v[190:193], v[72:73], off
	global_load_dwordx4 v[186:189], v[72:73], off offset:256
	v_or_b32_e32 v230, 16, v228
	v_ashrrev_i32_e32 v231, 31, v230
	v_lshlrev_b64 v[72:73], 12, v[230:231]
	v_or_b32_e32 v226, 32, v228
	v_lshl_add_u64 v[72:73], v[70:71], 0, v[72:73]
	v_ashrrev_i32_e32 v227, 31, v226
	global_load_dwordx4 v[182:185], v[72:73], off
	global_load_dwordx4 v[178:181], v[72:73], off offset:256
	v_lshlrev_b64 v[72:73], 12, v[226:227]
	v_or_b32_e32 v224, 48, v228
	v_lshl_add_u64 v[72:73], v[70:71], 0, v[72:73]
	v_ashrrev_i32_e32 v225, 31, v224
	global_load_dwordx4 v[166:169], v[72:73], off
	global_load_dwordx4 v[162:165], v[72:73], off offset:256
	v_lshlrev_b64 v[72:73], 12, v[224:225]
	v_add_u32_e32 v222, 0x80, v228
	v_lshl_add_u64 v[72:73], v[70:71], 0, v[72:73]
	v_ashrrev_i32_e32 v223, 31, v222
	global_load_dwordx4 v[158:161], v[72:73], off
	global_load_dwordx4 v[154:157], v[72:73], off offset:256
	v_lshlrev_b64 v[72:73], 12, v[222:223]
	v_add_u32_e32 v220, 0x90, v228
	v_lshl_add_u64 v[72:73], v[70:71], 0, v[72:73]
	v_ashrrev_i32_e32 v221, 31, v220
	global_load_dwordx4 v[142:145], v[72:73], off
	global_load_dwordx4 v[134:137], v[72:73], off offset:256
	v_lshlrev_b64 v[72:73], 12, v[220:221]
	v_add_u32_e32 v218, 0xa0, v228
	v_lshl_add_u64 v[72:73], v[70:71], 0, v[72:73]
	v_ashrrev_i32_e32 v219, 31, v218
	global_load_dwordx4 v[126:129], v[72:73], off
	global_load_dwordx4 v[114:117], v[72:73], off offset:256
	v_lshlrev_b64 v[72:73], 12, v[218:219]
	v_add_u32_e32 v216, 0xb0, v228
	v_lshl_add_u64 v[72:73], v[70:71], 0, v[72:73]
	v_ashrrev_i32_e32 v217, 31, v216
	global_load_dwordx4 v[102:105], v[72:73], off
	global_load_dwordx4 v[90:93], v[72:73], off offset:256
	v_lshlrev_b64 v[72:73], 12, v[216:217]
	v_lshl_add_u64 v[70:71], v[70:71], 0, v[72:73]
	global_load_dwordx4 v[78:81], v[70:71], off
	s_nop 0
	global_load_dwordx4 v[70:73], v[70:71], off offset:256
	v_add_u32_e32 v238, 0, v238
	v_add_u32_e32 v238, 0x24400, v238
	v_lshlrev_b64 v[240:241], 11, v[228:229]
	v_lshl_add_u64 v[248:249], v[240:241], 0, v[214:215]
	ds_read_b128 v[240:243], v238
	ds_read_b128 v[244:247], v238 offset:16
	v_cmp_eq_u32_e32 vcc, 0, v239
	s_waitcnt vmcnt(0)
	v_lshlrev_b32_e32 v250, 16, v190
	v_and_b32_e32 v251, 0xffff0000, v190
	v_lshlrev_b32_e32 v190, 16, v191
	v_and_b32_e32 v191, 0xffff0000, v191
	s_waitcnt lgkmcnt(1)
	v_pk_fma_f32 v[176:177], v[176:177], v[242:243], v[190:191]
	v_lshlrev_b32_e32 v190, 16, v192
	v_and_b32_e32 v191, 0xffff0000, v192
	v_lshlrev_b32_e32 v192, 16, v193
	v_and_b32_e32 v193, 0xffff0000, v193
	s_waitcnt lgkmcnt(0)
	v_pk_fma_f32 v[192:193], v[172:173], v[246:247], v[192:193]
	v_pk_fma_f32 v[172:173], v[170:171], v[244:245], v[190:191]
	v_lshlrev_b64 v[190:191], 1, v[248:249]
	v_pk_fma_f32 v[174:175], v[174:175], v[240:241], v[250:251]
	s_nop 0
	v_cvt_pk_bf16_f32 v170, v174, v175
	v_cvt_pk_bf16_f32 v171, v176, v177
	v_cvt_pk_bf16_f32 v172, v172, v173
	v_cvt_pk_bf16_f32 v173, v192, v193
	v_lshl_add_u64 v[192:193], s[12:13], 0, v[190:191]
	v_and_b32_e32 v241, 0xffff0000, v170
	v_and_b32_e32 v243, 0xffff0000, v171
	global_store_dwordx4 v[192:193], v[170:173], off sc1
	v_lshlrev_b32_e32 v240, 16, v170
	v_lshlrev_b32_e32 v242, 16, v171
	v_mul_f32_e32 v170, v241, v241
	v_mul_f32_e32 v171, v243, v243
	v_and_b32_e32 v245, 0xffff0000, v172
	v_and_b32_e32 v247, 0xffff0000, v173
	v_fmac_f32_e32 v170, v240, v240
	v_fmac_f32_e32 v171, v242, v242
	v_lshlrev_b32_e32 v244, 16, v172
	v_lshlrev_b32_e32 v246, 16, v173
	v_add_f32_e32 v170, v170, v171
	v_mul_f32_e32 v171, v245, v245
	v_mul_f32_e32 v172, v247, v247
	v_fmac_f32_e32 v171, v244, v244
	v_fmac_f32_e32 v172, v246, v246
	v_add_f32_e32 v171, v171, v172
	v_add_f32_e32 v239, v170, v171
	ds_read_b128 v[170:173], v238 offset:1024
	ds_read_b128 v[174:177], v238 offset:1040
	v_lshl_add_u64 v[190:191], s[36:37], 0, v[190:191]
	s_waitcnt lgkmcnt(1)
	v_pk_mul_f32 v[172:173], v[172:173], v[242:243]
	v_pk_mul_f32 v[170:171], v[170:171], v[240:241]
	s_waitcnt lgkmcnt(0)
	v_pk_mul_f32 v[176:177], v[176:177], v[246:247]
	v_pk_mul_f32 v[174:175], v[174:175], v[244:245]
	v_cvt_pk_bf16_f32 v170, v170, v171
	v_cvt_pk_bf16_f32 v171, v172, v173
	v_lshlrev_b32_e32 v240, 16, v186
	v_cvt_pk_bf16_f32 v172, v174, v175
	v_cvt_pk_bf16_f32 v173, v176, v177
	global_store_dwordx4 v[190:191], v[170:173], off sc1
	ds_read_b128 v[170:173], v238 offset:512
	ds_read_b128 v[174:177], v238 offset:528
	v_and_b32_e32 v241, 0xffff0000, v186
	v_lshlrev_b32_e32 v186, 16, v187
	v_and_b32_e32 v187, 0xffff0000, v187
	s_waitcnt lgkmcnt(1)
	v_pk_fma_f32 v[152:153], v[152:153], v[172:173], v[186:187]
	v_pk_fma_f32 v[150:151], v[150:151], v[170:171], v[240:241]
	v_lshlrev_b32_e32 v170, 16, v188
	v_and_b32_e32 v171, 0xffff0000, v188
	v_lshlrev_b32_e32 v172, 16, v189
	v_and_b32_e32 v173, 0xffff0000, v189
	s_waitcnt lgkmcnt(0)
	v_pk_fma_f32 v[172:173], v[148:149], v[176:177], v[172:173]
	v_pk_fma_f32 v[148:149], v[146:147], v[174:175], v[170:171]
	v_cvt_pk_bf16_f32 v146, v150, v151
	v_cvt_pk_bf16_f32 v147, v152, v153
	s_nop 0
	v_cvt_pk_bf16_f32 v148, v148, v149
	v_cvt_pk_bf16_f32 v149, v172, v173
	v_and_b32_e32 v171, 0xffff0000, v146
	v_and_b32_e32 v173, 0xffff0000, v147
	global_store_dwordx4 v[192:193], v[146:149], off offset:256 sc1
	v_lshlrev_b32_e32 v170, 16, v146
	v_lshlrev_b32_e32 v172, 16, v147
	v_mul_f32_e32 v146, v171, v171
	v_mul_f32_e32 v147, v173, v173
	v_and_b32_e32 v175, 0xffff0000, v148
	v_and_b32_e32 v177, 0xffff0000, v149
	v_fmac_f32_e32 v146, v170, v170
	v_fmac_f32_e32 v147, v172, v172
	v_lshlrev_b32_e32 v174, 16, v148
	v_lshlrev_b32_e32 v176, 16, v149
	v_add_f32_e32 v146, v146, v147
	v_mul_f32_e32 v147, v175, v175
	v_mul_f32_e32 v148, v177, v177
	v_fmac_f32_e32 v147, v174, v174
	v_fmac_f32_e32 v148, v176, v176
	v_add_f32_e32 v147, v147, v148
	v_add_f32_e32 v146, v146, v147
	v_add_f32_e32 v186, v239, v146
	ds_read_b128 v[146:149], v238 offset:1536
	ds_read_b128 v[150:153], v238 offset:1552
	s_waitcnt lgkmcnt(1)
	v_pk_mul_f32 v[146:147], v[146:147], v[170:171]
	v_pk_mul_f32 v[148:149], v[148:149], v[172:173]
	v_cvt_pk_bf16_f32 v146, v146, v147
	s_waitcnt lgkmcnt(0)
	v_pk_mul_f32 v[152:153], v[152:153], v[176:177]
	v_pk_mul_f32 v[150:151], v[150:151], v[174:175]
	v_cvt_pk_bf16_f32 v147, v148, v149
	s_nop 0
	v_cvt_pk_bf16_f32 v148, v150, v151
	v_cvt_pk_bf16_f32 v149, v152, v153
	global_store_dwordx4 v[190:191], v[146:149], off offset:256 sc1
	ds_swizzle_b32 v146, v186 offset:swizzle(SWAP,16)
	s_waitcnt lgkmcnt(0)
	v_add_f32_e32 v148, v186, v146
	v_mov_b32_e32 v149, v148
	s_nop 1
	v_permlane32_swap_b32_e32 v148, v149
	v_lshl_add_u64 v[146:147], v[228:229], 2, s[38:39]
	s_and_saveexec_b64 s[22:23], vcc
	s_cbranch_execz .LBB0_516
	v_add_f32_e32 v148, v148, v149
	v_fma_f32 v148, v148, s74, 0.5
	v_cvt_u32_f32_e32 v148, v148
	global_atomic_add v[146:147], v148, off
.LBB0_516:
	s_or_b64 exec, exec, s[22:23]
	v_lshlrev_b64 v[148:149], 11, v[230:231]
	v_lshl_add_u64 v[152:153], v[148:149], 0, v[214:215]
	ds_read_b128 v[148:151], v238
	ds_read_b128 v[170:173], v238 offset:16
	v_lshlrev_b32_e32 v174, 16, v182
	v_and_b32_e32 v175, 0xffff0000, v182
	v_lshlrev_b32_e32 v176, 16, v183
	v_and_b32_e32 v177, 0xffff0000, v183
	s_waitcnt lgkmcnt(1)
	v_pk_fma_f32 v[140:141], v[140:141], v[150:151], v[176:177]
	v_pk_fma_f32 v[138:139], v[138:139], v[148:149], v[174:175]
	v_lshlrev_b32_e32 v148, 16, v184
	v_and_b32_e32 v149, 0xffff0000, v184
	v_lshlrev_b32_e32 v150, 16, v185
	v_and_b32_e32 v151, 0xffff0000, v185
	s_waitcnt lgkmcnt(0)
	v_pk_fma_f32 v[150:151], v[132:133], v[172:173], v[150:151]
	v_pk_fma_f32 v[132:133], v[130:131], v[170:171], v[148:149]
	v_lshlrev_b64 v[148:149], 1, v[152:153]
	v_cvt_pk_bf16_f32 v130, v138, v139
	v_cvt_pk_bf16_f32 v131, v140, v141
	v_cvt_pk_bf16_f32 v132, v132, v133
	v_cvt_pk_bf16_f32 v133, v150, v151
	v_lshl_add_u64 v[150:151], s[12:13], 0, v[148:149]
	v_and_b32_e32 v153, 0xffff0000, v130
	v_and_b32_e32 v171, 0xffff0000, v131
	global_store_dwordx4 v[150:151], v[130:133], off sc1
	v_lshlrev_b32_e32 v152, 16, v130
	v_lshlrev_b32_e32 v170, 16, v131
	v_and_b32_e32 v173, 0xffff0000, v132
	v_and_b32_e32 v175, 0xffff0000, v133
	v_mul_f32_e32 v130, v153, v153
	v_mul_f32_e32 v131, v171, v171
	v_lshlrev_b32_e32 v172, 16, v132
	v_lshlrev_b32_e32 v174, 16, v133
	v_fmac_f32_e32 v130, v152, v152
	v_fmac_f32_e32 v131, v170, v170
	v_mul_f32_e32 v138, v173, v173
	v_mul_f32_e32 v139, v175, v175
	v_add_f32_e32 v176, v130, v131
	v_fmac_f32_e32 v138, v172, v172
	v_fmac_f32_e32 v139, v174, v174
	ds_read_b128 v[130:133], v238 offset:1024
	v_add_f32_e32 v177, v138, v139
	ds_read_b128 v[138:141], v238 offset:1040
	v_lshl_add_u64 v[148:149], s[36:37], 0, v[148:149]
	v_add_f32_e32 v176, v176, v177
	s_waitcnt lgkmcnt(1)
	v_pk_mul_f32 v[132:133], v[132:133], v[170:171]
	v_pk_mul_f32 v[130:131], v[130:131], v[152:153]
	s_waitcnt lgkmcnt(0)
	v_pk_mul_f32 v[140:141], v[140:141], v[174:175]
	v_pk_mul_f32 v[138:139], v[138:139], v[172:173]
	v_cvt_pk_bf16_f32 v130, v130, v131
	v_cvt_pk_bf16_f32 v131, v132, v133
	v_lshlrev_b32_e32 v152, 16, v178
	v_cvt_pk_bf16_f32 v132, v138, v139
	v_cvt_pk_bf16_f32 v133, v140, v141
	global_store_dwordx4 v[148:149], v[130:133], off sc1
	ds_read_b128 v[130:133], v238 offset:512
	ds_read_b128 v[138:141], v238 offset:528
	v_and_b32_e32 v153, 0xffff0000, v178
	v_lshlrev_b32_e32 v170, 16, v179
	v_and_b32_e32 v171, 0xffff0000, v179
	s_waitcnt lgkmcnt(1)
	v_pk_fma_f32 v[124:125], v[124:125], v[132:133], v[170:171]
	v_pk_fma_f32 v[122:123], v[122:123], v[130:131], v[152:153]
	v_lshlrev_b32_e32 v130, 16, v180
	v_and_b32_e32 v131, 0xffff0000, v180
	v_lshlrev_b32_e32 v132, 16, v181
	v_and_b32_e32 v133, 0xffff0000, v181
	s_waitcnt lgkmcnt(0)
	v_pk_fma_f32 v[132:133], v[120:121], v[140:141], v[132:133]
	v_pk_fma_f32 v[120:121], v[118:119], v[138:139], v[130:131]
	v_cvt_pk_bf16_f32 v118, v122, v123
	v_cvt_pk_bf16_f32 v119, v124, v125
	s_nop 0
	v_cvt_pk_bf16_f32 v120, v120, v121
	v_cvt_pk_bf16_f32 v121, v132, v133
	v_and_b32_e32 v131, 0xffff0000, v118
	v_and_b32_e32 v133, 0xffff0000, v119
	global_store_dwordx4 v[150:151], v[118:121], off offset:256 sc1
	v_lshlrev_b32_e32 v130, 16, v118
	v_lshlrev_b32_e32 v132, 16, v119
	v_mul_f32_e32 v118, v131, v131
	v_mul_f32_e32 v119, v133, v133
	v_and_b32_e32 v139, 0xffff0000, v120
	v_and_b32_e32 v141, 0xffff0000, v121
	v_fmac_f32_e32 v118, v130, v130
	v_fmac_f32_e32 v119, v132, v132
	v_lshlrev_b32_e32 v138, 16, v120
	v_lshlrev_b32_e32 v140, 16, v121
	v_add_f32_e32 v150, v118, v119
	v_mul_f32_e32 v122, v139, v139
	v_mul_f32_e32 v123, v141, v141
	ds_read_b128 v[118:121], v238 offset:1536
	v_fmac_f32_e32 v122, v138, v138
	v_fmac_f32_e32 v123, v140, v140
	v_add_f32_e32 v151, v122, v123
	v_add_f32_e32 v150, v150, v151
	v_add_f32_e32 v150, v176, v150
	ds_read_b128 v[122:125], v238 offset:1552
	s_waitcnt lgkmcnt(1)
	v_pk_mul_f32 v[118:119], v[118:119], v[130:131]
	ds_swizzle_b32 v130, v150 offset:swizzle(SWAP,16)
	v_pk_mul_f32 v[120:121], v[120:121], v[132:133]
	v_cvt_pk_bf16_f32 v118, v118, v119
	s_waitcnt lgkmcnt(1)
	v_pk_mul_f32 v[124:125], v[124:125], v[140:141]
	v_pk_mul_f32 v[122:123], v[122:123], v[138:139]
	v_cvt_pk_bf16_f32 v119, v120, v121
	s_nop 0
	v_cvt_pk_bf16_f32 v120, v122, v123
	v_cvt_pk_bf16_f32 v121, v124, v125
	global_store_dwordx4 v[148:149], v[118:121], off offset:256 sc1
	s_waitcnt lgkmcnt(0)
	s_nop 0
	v_add_f32_e32 v118, v150, v130
	v_mov_b32_e32 v119, v118
	s_nop 1
	v_permlane32_swap_b32_e32 v118, v119
	s_and_saveexec_b64 s[22:23], vcc
	s_cbranch_execz .LBB0_518
	v_add_f32_e32 v118, v118, v119
	v_fma_f32 v118, v118, s74, 0.5
	v_cvt_u32_f32_e32 v118, v118
	global_atomic_add v[146:147], v118, off offset:64
.LBB0_518:
	s_or_b64 exec, exec, s[22:23]
	v_lshlrev_b64 v[118:119], 11, v[226:227]
	v_lshl_add_u64 v[130:131], v[118:119], 0, v[214:215]
	ds_read_b128 v[118:121], v238
	ds_read_b128 v[122:125], v238 offset:16
	v_lshlrev_b32_e32 v132, 16, v166
	v_and_b32_e32 v133, 0xffff0000, v166
	v_lshlrev_b32_e32 v138, 16, v167
	v_and_b32_e32 v139, 0xffff0000, v167
	s_waitcnt lgkmcnt(1)
	v_pk_fma_f32 v[112:113], v[112:113], v[120:121], v[138:139]
	v_pk_fma_f32 v[110:111], v[110:111], v[118:119], v[132:133]
	v_lshlrev_b32_e32 v118, 16, v168
	v_and_b32_e32 v119, 0xffff0000, v168
	v_lshlrev_b32_e32 v120, 16, v169
	v_and_b32_e32 v121, 0xffff0000, v169
	s_waitcnt lgkmcnt(0)
	v_pk_fma_f32 v[120:121], v[108:109], v[124:125], v[120:121]
	v_pk_fma_f32 v[108:109], v[106:107], v[122:123], v[118:119]
	v_lshlrev_b64 v[118:119], 1, v[130:131]
	v_cvt_pk_bf16_f32 v106, v110, v111
	v_cvt_pk_bf16_f32 v107, v112, v113
	v_cvt_pk_bf16_f32 v108, v108, v109
	v_cvt_pk_bf16_f32 v109, v120, v121
	v_lshl_add_u64 v[120:121], s[12:13], 0, v[118:119]
	v_and_b32_e32 v123, 0xffff0000, v106
	v_and_b32_e32 v125, 0xffff0000, v107
	global_store_dwordx4 v[120:121], v[106:109], off sc1
	v_lshlrev_b32_e32 v122, 16, v106
	v_lshlrev_b32_e32 v124, 16, v107
	v_and_b32_e32 v131, 0xffff0000, v108
	v_and_b32_e32 v133, 0xffff0000, v109
	v_mul_f32_e32 v106, v123, v123
	v_mul_f32_e32 v107, v125, v125
	v_lshlrev_b32_e32 v130, 16, v108
	v_lshlrev_b32_e32 v132, 16, v109
	v_fmac_f32_e32 v106, v122, v122
	v_fmac_f32_e32 v107, v124, v124
	v_mul_f32_e32 v110, v131, v131
	v_mul_f32_e32 v111, v133, v133
	v_add_f32_e32 v138, v106, v107
	v_fmac_f32_e32 v110, v130, v130
	v_fmac_f32_e32 v111, v132, v132
	ds_read_b128 v[106:109], v238 offset:1024
	v_add_f32_e32 v139, v110, v111
	ds_read_b128 v[110:113], v238 offset:1040
	v_lshl_add_u64 v[118:119], s[36:37], 0, v[118:119]
	v_add_f32_e32 v138, v138, v139
	s_waitcnt lgkmcnt(1)
	v_pk_mul_f32 v[108:109], v[108:109], v[124:125]
	v_pk_mul_f32 v[106:107], v[106:107], v[122:123]
	s_waitcnt lgkmcnt(0)
	v_pk_mul_f32 v[112:113], v[112:113], v[132:133]
	v_pk_mul_f32 v[110:111], v[110:111], v[130:131]
	v_cvt_pk_bf16_f32 v106, v106, v107
	v_cvt_pk_bf16_f32 v107, v108, v109
	v_lshlrev_b32_e32 v122, 16, v162
	v_cvt_pk_bf16_f32 v108, v110, v111
	v_cvt_pk_bf16_f32 v109, v112, v113
	global_store_dwordx4 v[118:119], v[106:109], off sc1
	ds_read_b128 v[106:109], v238 offset:512
	ds_read_b128 v[110:113], v238 offset:528
	v_and_b32_e32 v123, 0xffff0000, v162
	v_lshlrev_b32_e32 v124, 16, v163
	v_and_b32_e32 v125, 0xffff0000, v163
	s_waitcnt lgkmcnt(1)
	v_pk_fma_f32 v[100:101], v[100:101], v[108:109], v[124:125]
	v_pk_fma_f32 v[98:99], v[98:99], v[106:107], v[122:123]
	v_lshlrev_b32_e32 v106, 16, v164
	v_and_b32_e32 v107, 0xffff0000, v164
	v_lshlrev_b32_e32 v108, 16, v165
	v_and_b32_e32 v109, 0xffff0000, v165
	s_waitcnt lgkmcnt(0)
	v_pk_fma_f32 v[108:109], v[96:97], v[112:113], v[108:109]
	v_pk_fma_f32 v[96:97], v[94:95], v[110:111], v[106:107]
	v_cvt_pk_bf16_f32 v94, v98, v99
	v_cvt_pk_bf16_f32 v95, v100, v101
	s_nop 0
	v_cvt_pk_bf16_f32 v96, v96, v97
	v_cvt_pk_bf16_f32 v97, v108, v109
	v_and_b32_e32 v107, 0xffff0000, v94
	v_and_b32_e32 v109, 0xffff0000, v95
	global_store_dwordx4 v[120:121], v[94:97], off offset:256 sc1
	v_lshlrev_b32_e32 v106, 16, v94
	v_lshlrev_b32_e32 v108, 16, v95
	v_mul_f32_e32 v94, v107, v107
	v_mul_f32_e32 v95, v109, v109
	v_and_b32_e32 v111, 0xffff0000, v96
	v_and_b32_e32 v113, 0xffff0000, v97
	v_fmac_f32_e32 v94, v106, v106
	v_fmac_f32_e32 v95, v108, v108
	v_lshlrev_b32_e32 v110, 16, v96
	v_lshlrev_b32_e32 v112, 16, v97
	v_add_f32_e32 v120, v94, v95
	v_mul_f32_e32 v98, v111, v111
	v_mul_f32_e32 v99, v113, v113
	ds_read_b128 v[94:97], v238 offset:1536
	v_fmac_f32_e32 v98, v110, v110
	v_fmac_f32_e32 v99, v112, v112
	v_add_f32_e32 v121, v98, v99
	v_add_f32_e32 v120, v120, v121
	v_add_f32_e32 v120, v138, v120
	ds_read_b128 v[98:101], v238 offset:1552
	s_waitcnt lgkmcnt(1)
	v_pk_mul_f32 v[94:95], v[94:95], v[106:107]
	ds_swizzle_b32 v106, v120 offset:swizzle(SWAP,16)
	v_pk_mul_f32 v[96:97], v[96:97], v[108:109]
	v_cvt_pk_bf16_f32 v94, v94, v95
	s_waitcnt lgkmcnt(1)
	v_pk_mul_f32 v[100:101], v[100:101], v[112:113]
	v_pk_mul_f32 v[98:99], v[98:99], v[110:111]
	v_cvt_pk_bf16_f32 v95, v96, v97
	s_nop 0
	v_cvt_pk_bf16_f32 v96, v98, v99
	v_cvt_pk_bf16_f32 v97, v100, v101
	global_store_dwordx4 v[118:119], v[94:97], off offset:256 sc1
	s_waitcnt lgkmcnt(0)
	s_nop 0
	v_add_f32_e32 v94, v120, v106
	v_mov_b32_e32 v95, v94
	s_nop 1
	v_permlane32_swap_b32_e32 v94, v95
	s_and_saveexec_b64 s[22:23], vcc
	s_cbranch_execz .LBB0_520
	v_add_f32_e32 v94, v94, v95
	v_fma_f32 v94, v94, s74, 0.5
	v_cvt_u32_f32_e32 v94, v94
	global_atomic_add v[146:147], v94, off offset:128
.LBB0_520:
	s_or_b64 exec, exec, s[22:23]
	v_lshlrev_b64 v[94:95], 11, v[224:225]
	v_lshl_add_u64 v[106:107], v[94:95], 0, v[214:215]
	ds_read_b128 v[94:97], v238
	ds_read_b128 v[98:101], v238 offset:16
	v_lshlrev_b32_e32 v108, 16, v158
	v_and_b32_e32 v109, 0xffff0000, v158
	v_lshlrev_b32_e32 v110, 16, v159
	v_and_b32_e32 v111, 0xffff0000, v159
	s_waitcnt lgkmcnt(1)
	v_pk_fma_f32 v[88:89], v[88:89], v[96:97], v[110:111]
	v_pk_fma_f32 v[86:87], v[86:87], v[94:95], v[108:109]
	v_lshlrev_b32_e32 v94, 16, v160
	v_and_b32_e32 v95, 0xffff0000, v160
	v_lshlrev_b32_e32 v96, 16, v161
	v_and_b32_e32 v97, 0xffff0000, v161
	s_waitcnt lgkmcnt(0)
	v_pk_fma_f32 v[96:97], v[84:85], v[100:101], v[96:97]
	v_pk_fma_f32 v[84:85], v[82:83], v[98:99], v[94:95]
	v_lshlrev_b64 v[94:95], 1, v[106:107]
	v_cvt_pk_bf16_f32 v82, v86, v87
	v_cvt_pk_bf16_f32 v83, v88, v89
	v_cvt_pk_bf16_f32 v84, v84, v85
	v_cvt_pk_bf16_f32 v85, v96, v97
	v_lshl_add_u64 v[96:97], s[12:13], 0, v[94:95]
	v_and_b32_e32 v99, 0xffff0000, v82
	v_and_b32_e32 v101, 0xffff0000, v83
	global_store_dwordx4 v[96:97], v[82:85], off sc1
	v_lshlrev_b32_e32 v98, 16, v82
	v_lshlrev_b32_e32 v100, 16, v83
	v_and_b32_e32 v107, 0xffff0000, v84
	v_and_b32_e32 v109, 0xffff0000, v85
	v_mul_f32_e32 v82, v99, v99
	v_mul_f32_e32 v83, v101, v101
	v_lshlrev_b32_e32 v106, 16, v84
	v_lshlrev_b32_e32 v108, 16, v85
	v_fmac_f32_e32 v82, v98, v98
	v_fmac_f32_e32 v83, v100, v100
	v_mul_f32_e32 v86, v107, v107
	v_mul_f32_e32 v87, v109, v109
	v_add_f32_e32 v110, v82, v83
	v_fmac_f32_e32 v86, v106, v106
	v_fmac_f32_e32 v87, v108, v108
	ds_read_b128 v[82:85], v238 offset:1024
	v_add_f32_e32 v111, v86, v87
	ds_read_b128 v[86:89], v238 offset:1040
	v_lshl_add_u64 v[94:95], s[36:37], 0, v[94:95]
	v_add_f32_e32 v110, v110, v111
	s_waitcnt lgkmcnt(1)
	v_pk_mul_f32 v[84:85], v[84:85], v[100:101]
	v_pk_mul_f32 v[82:83], v[82:83], v[98:99]
	s_waitcnt lgkmcnt(0)
	v_pk_mul_f32 v[88:89], v[88:89], v[108:109]
	v_pk_mul_f32 v[86:87], v[86:87], v[106:107]
	v_cvt_pk_bf16_f32 v82, v82, v83
	v_cvt_pk_bf16_f32 v83, v84, v85
	v_lshlrev_b32_e32 v98, 16, v154
	v_cvt_pk_bf16_f32 v84, v86, v87
	v_cvt_pk_bf16_f32 v85, v88, v89
	global_store_dwordx4 v[94:95], v[82:85], off sc1
	ds_read_b128 v[82:85], v238 offset:512
	ds_read_b128 v[86:89], v238 offset:528
	v_and_b32_e32 v99, 0xffff0000, v154
	v_lshlrev_b32_e32 v100, 16, v155
	v_and_b32_e32 v101, 0xffff0000, v155
	s_waitcnt lgkmcnt(1)
	v_pk_fma_f32 v[76:77], v[76:77], v[84:85], v[100:101]
	v_pk_fma_f32 v[74:75], v[74:75], v[82:83], v[98:99]
	v_lshlrev_b32_e32 v82, 16, v156
	v_and_b32_e32 v83, 0xffff0000, v156
	v_lshlrev_b32_e32 v84, 16, v157
	v_and_b32_e32 v85, 0xffff0000, v157
	s_waitcnt lgkmcnt(0)
	v_pk_fma_f32 v[84:85], v[68:69], v[88:89], v[84:85]
	v_pk_fma_f32 v[68:69], v[66:67], v[86:87], v[82:83]
	v_cvt_pk_bf16_f32 v66, v74, v75
	v_cvt_pk_bf16_f32 v67, v76, v77
	s_nop 0
	v_cvt_pk_bf16_f32 v68, v68, v69
	v_cvt_pk_bf16_f32 v69, v84, v85
	v_and_b32_e32 v83, 0xffff0000, v66
	v_and_b32_e32 v85, 0xffff0000, v67
	global_store_dwordx4 v[96:97], v[66:69], off offset:256 sc1
	v_lshlrev_b32_e32 v82, 16, v66
	v_lshlrev_b32_e32 v84, 16, v67
	v_mul_f32_e32 v66, v83, v83
	v_mul_f32_e32 v67, v85, v85
	v_and_b32_e32 v87, 0xffff0000, v68
	v_and_b32_e32 v89, 0xffff0000, v69
	v_fmac_f32_e32 v66, v82, v82
	v_fmac_f32_e32 v67, v84, v84
	v_lshlrev_b32_e32 v86, 16, v68
	v_lshlrev_b32_e32 v88, 16, v69
	v_add_f32_e32 v96, v66, v67
	v_mul_f32_e32 v74, v87, v87
	v_mul_f32_e32 v75, v89, v89
	ds_read_b128 v[66:69], v238 offset:1536
	v_fmac_f32_e32 v74, v86, v86
	v_fmac_f32_e32 v75, v88, v88
	v_add_f32_e32 v97, v74, v75
	v_add_f32_e32 v96, v96, v97
	v_add_f32_e32 v96, v110, v96
	ds_read_b128 v[74:77], v238 offset:1552
	s_waitcnt lgkmcnt(1)
	v_pk_mul_f32 v[66:67], v[66:67], v[82:83]
	ds_swizzle_b32 v82, v96 offset:swizzle(SWAP,16)
	v_pk_mul_f32 v[68:69], v[68:69], v[84:85]
	v_cvt_pk_bf16_f32 v66, v66, v67
	s_waitcnt lgkmcnt(1)
	v_pk_mul_f32 v[76:77], v[76:77], v[88:89]
	v_pk_mul_f32 v[74:75], v[74:75], v[86:87]
	v_cvt_pk_bf16_f32 v67, v68, v69
	s_nop 0
	v_cvt_pk_bf16_f32 v68, v74, v75
	v_cvt_pk_bf16_f32 v69, v76, v77
	global_store_dwordx4 v[94:95], v[66:69], off offset:256 sc1
	s_waitcnt lgkmcnt(0)
	s_nop 0
	v_add_f32_e32 v66, v96, v82
	v_mov_b32_e32 v67, v66
	s_nop 1
	v_permlane32_swap_b32_e32 v66, v67
	s_and_saveexec_b64 s[22:23], vcc
	s_cbranch_execz .LBB0_522
	v_add_f32_e32 v66, v66, v67
	v_fma_f32 v66, v66, s74, 0.5
	v_cvt_u32_f32_e32 v66, v66
	global_atomic_add v[146:147], v66, off offset:192
.LBB0_522:
	s_or_b64 exec, exec, s[22:23]
	v_lshlrev_b64 v[66:67], 11, v[222:223]
	v_lshl_add_u64 v[82:83], v[66:67], 0, v[214:215]
	ds_read_b128 v[66:69], v238
	ds_read_b128 v[74:77], v238 offset:16
	v_lshlrev_b32_e32 v84, 16, v142
	v_and_b32_e32 v85, 0xffff0000, v142
	v_lshlrev_b32_e32 v86, 16, v143
	v_and_b32_e32 v87, 0xffff0000, v143
	s_waitcnt lgkmcnt(1)
	v_pk_fma_f32 v[64:65], v[64:65], v[68:69], v[86:87]
	v_pk_fma_f32 v[62:63], v[62:63], v[66:67], v[84:85]
	v_lshlrev_b32_e32 v66, 16, v144
	v_and_b32_e32 v67, 0xffff0000, v144
	v_lshlrev_b32_e32 v68, 16, v145
	v_and_b32_e32 v69, 0xffff0000, v145
	s_waitcnt lgkmcnt(0)
	v_pk_fma_f32 v[68:69], v[60:61], v[76:77], v[68:69]
	v_pk_fma_f32 v[60:61], v[58:59], v[74:75], v[66:67]
	v_lshlrev_b64 v[66:67], 1, v[82:83]
	v_cvt_pk_bf16_f32 v58, v62, v63
	v_cvt_pk_bf16_f32 v59, v64, v65
	v_cvt_pk_bf16_f32 v60, v60, v61
	v_cvt_pk_bf16_f32 v61, v68, v69
	v_lshl_add_u64 v[68:69], s[12:13], 0, v[66:67]
	v_and_b32_e32 v75, 0xffff0000, v58
	v_and_b32_e32 v77, 0xffff0000, v59
	global_store_dwordx4 v[68:69], v[58:61], off sc1
	v_lshlrev_b32_e32 v74, 16, v58
	v_lshlrev_b32_e32 v76, 16, v59
	v_and_b32_e32 v83, 0xffff0000, v60
	v_and_b32_e32 v85, 0xffff0000, v61
	v_mul_f32_e32 v58, v75, v75
	v_mul_f32_e32 v59, v77, v77
	v_lshlrev_b32_e32 v82, 16, v60
	v_lshlrev_b32_e32 v84, 16, v61
	v_fmac_f32_e32 v58, v74, v74
	v_fmac_f32_e32 v59, v76, v76
	v_mul_f32_e32 v62, v83, v83
	v_mul_f32_e32 v63, v85, v85
	v_add_f32_e32 v86, v58, v59
	v_fmac_f32_e32 v62, v82, v82
	v_fmac_f32_e32 v63, v84, v84
	ds_read_b128 v[58:61], v238 offset:1024
	v_add_f32_e32 v87, v62, v63
	ds_read_b128 v[62:65], v238 offset:1040
	v_lshl_add_u64 v[66:67], s[36:37], 0, v[66:67]
	v_add_f32_e32 v86, v86, v87
	s_waitcnt lgkmcnt(1)
	v_pk_mul_f32 v[60:61], v[60:61], v[76:77]
	v_pk_mul_f32 v[58:59], v[58:59], v[74:75]
	s_waitcnt lgkmcnt(0)
	v_pk_mul_f32 v[64:65], v[64:65], v[84:85]
	v_pk_mul_f32 v[62:63], v[62:63], v[82:83]
	v_cvt_pk_bf16_f32 v58, v58, v59
	v_cvt_pk_bf16_f32 v59, v60, v61
	v_lshlrev_b32_e32 v74, 16, v134
	v_cvt_pk_bf16_f32 v60, v62, v63
	v_cvt_pk_bf16_f32 v61, v64, v65
	global_store_dwordx4 v[66:67], v[58:61], off sc1
	ds_read_b128 v[58:61], v238 offset:512
	ds_read_b128 v[62:65], v238 offset:528
	v_and_b32_e32 v75, 0xffff0000, v134
	v_lshlrev_b32_e32 v76, 16, v135
	v_and_b32_e32 v77, 0xffff0000, v135
	s_waitcnt lgkmcnt(1)
	v_pk_fma_f32 v[56:57], v[56:57], v[60:61], v[76:77]
	v_pk_fma_f32 v[54:55], v[54:55], v[58:59], v[74:75]
	v_lshlrev_b32_e32 v58, 16, v136
	v_and_b32_e32 v59, 0xffff0000, v136
	v_lshlrev_b32_e32 v60, 16, v137
	v_and_b32_e32 v61, 0xffff0000, v137
	s_waitcnt lgkmcnt(0)
	v_pk_fma_f32 v[60:61], v[52:53], v[64:65], v[60:61]
	v_pk_fma_f32 v[52:53], v[50:51], v[62:63], v[58:59]
	v_cvt_pk_bf16_f32 v50, v54, v55
	v_cvt_pk_bf16_f32 v51, v56, v57
	s_nop 0
	v_cvt_pk_bf16_f32 v52, v52, v53
	v_cvt_pk_bf16_f32 v53, v60, v61
	v_and_b32_e32 v59, 0xffff0000, v50
	v_and_b32_e32 v61, 0xffff0000, v51
	global_store_dwordx4 v[68:69], v[50:53], off offset:256 sc1
	v_lshlrev_b32_e32 v58, 16, v50
	v_lshlrev_b32_e32 v60, 16, v51
	v_mul_f32_e32 v50, v59, v59
	v_mul_f32_e32 v51, v61, v61
	v_and_b32_e32 v63, 0xffff0000, v52
	v_and_b32_e32 v65, 0xffff0000, v53
	v_fmac_f32_e32 v50, v58, v58
	v_fmac_f32_e32 v51, v60, v60
	v_lshlrev_b32_e32 v62, 16, v52
	v_lshlrev_b32_e32 v64, 16, v53
	v_add_f32_e32 v68, v50, v51
	v_mul_f32_e32 v54, v63, v63
	v_mul_f32_e32 v55, v65, v65
	ds_read_b128 v[50:53], v238 offset:1536
	v_fmac_f32_e32 v54, v62, v62
	v_fmac_f32_e32 v55, v64, v64
	v_add_f32_e32 v69, v54, v55
	v_add_f32_e32 v68, v68, v69
	v_add_f32_e32 v68, v86, v68
	ds_read_b128 v[54:57], v238 offset:1552
	s_waitcnt lgkmcnt(1)
	v_pk_mul_f32 v[50:51], v[50:51], v[58:59]
	ds_swizzle_b32 v58, v68 offset:swizzle(SWAP,16)
	v_pk_mul_f32 v[52:53], v[52:53], v[60:61]
	v_cvt_pk_bf16_f32 v50, v50, v51
	s_waitcnt lgkmcnt(1)
	v_pk_mul_f32 v[56:57], v[56:57], v[64:65]
	v_pk_mul_f32 v[54:55], v[54:55], v[62:63]
	v_cvt_pk_bf16_f32 v51, v52, v53
	s_nop 0
	v_cvt_pk_bf16_f32 v52, v54, v55
	v_cvt_pk_bf16_f32 v53, v56, v57
	global_store_dwordx4 v[66:67], v[50:53], off offset:256 sc1
	s_waitcnt lgkmcnt(0)
	s_nop 0
	v_add_f32_e32 v50, v68, v58
	v_mov_b32_e32 v51, v50
	s_nop 1
	v_permlane32_swap_b32_e32 v50, v51
	s_and_saveexec_b64 s[22:23], vcc
	s_cbranch_execz .LBB0_524
	v_add_f32_e32 v50, v50, v51
	v_fma_f32 v50, v50, s74, 0.5
	v_cvt_u32_f32_e32 v50, v50
	global_atomic_add v[146:147], v50, off offset:512
.LBB0_524:
	s_or_b64 exec, exec, s[22:23]
	v_lshlrev_b64 v[50:51], 11, v[220:221]
	v_lshl_add_u64 v[58:59], v[50:51], 0, v[214:215]
	ds_read_b128 v[50:53], v238
	ds_read_b128 v[54:57], v238 offset:16
	v_lshlrev_b32_e32 v60, 16, v126
	v_and_b32_e32 v61, 0xffff0000, v126
	v_lshlrev_b32_e32 v62, 16, v127
	v_and_b32_e32 v63, 0xffff0000, v127
	s_waitcnt lgkmcnt(1)
	v_pk_fma_f32 v[48:49], v[48:49], v[52:53], v[62:63]
	v_pk_fma_f32 v[46:47], v[46:47], v[50:51], v[60:61]
	v_lshlrev_b32_e32 v50, 16, v128
	v_and_b32_e32 v51, 0xffff0000, v128
	v_lshlrev_b32_e32 v52, 16, v129
	v_and_b32_e32 v53, 0xffff0000, v129
	s_waitcnt lgkmcnt(0)
	v_pk_fma_f32 v[52:53], v[44:45], v[56:57], v[52:53]
	v_pk_fma_f32 v[44:45], v[42:43], v[54:55], v[50:51]
	v_lshlrev_b64 v[50:51], 1, v[58:59]
	v_cvt_pk_bf16_f32 v42, v46, v47
	v_cvt_pk_bf16_f32 v43, v48, v49
	v_cvt_pk_bf16_f32 v44, v44, v45
	v_cvt_pk_bf16_f32 v45, v52, v53
	v_lshl_add_u64 v[52:53], s[12:13], 0, v[50:51]
	v_and_b32_e32 v55, 0xffff0000, v42
	v_and_b32_e32 v57, 0xffff0000, v43
	global_store_dwordx4 v[52:53], v[42:45], off sc1
	v_lshlrev_b32_e32 v54, 16, v42
	v_lshlrev_b32_e32 v56, 16, v43
	v_and_b32_e32 v59, 0xffff0000, v44
	v_and_b32_e32 v61, 0xffff0000, v45
	v_mul_f32_e32 v42, v55, v55
	v_mul_f32_e32 v43, v57, v57
	v_lshlrev_b32_e32 v58, 16, v44
	v_lshlrev_b32_e32 v60, 16, v45
	v_fmac_f32_e32 v42, v54, v54
	v_fmac_f32_e32 v43, v56, v56
	v_mul_f32_e32 v46, v59, v59
	v_mul_f32_e32 v47, v61, v61
	v_add_f32_e32 v62, v42, v43
	v_fmac_f32_e32 v46, v58, v58
	v_fmac_f32_e32 v47, v60, v60
	ds_read_b128 v[42:45], v238 offset:1024
	v_add_f32_e32 v63, v46, v47
	ds_read_b128 v[46:49], v238 offset:1040
	v_lshl_add_u64 v[50:51], s[36:37], 0, v[50:51]
	v_add_f32_e32 v62, v62, v63
	s_waitcnt lgkmcnt(1)
	v_pk_mul_f32 v[44:45], v[44:45], v[56:57]
	v_pk_mul_f32 v[42:43], v[42:43], v[54:55]
	s_waitcnt lgkmcnt(0)
	v_pk_mul_f32 v[48:49], v[48:49], v[60:61]
	v_pk_mul_f32 v[46:47], v[46:47], v[58:59]
	v_cvt_pk_bf16_f32 v42, v42, v43
	v_cvt_pk_bf16_f32 v43, v44, v45
	v_lshlrev_b32_e32 v54, 16, v114
	v_cvt_pk_bf16_f32 v44, v46, v47
	v_cvt_pk_bf16_f32 v45, v48, v49
	global_store_dwordx4 v[50:51], v[42:45], off sc1
	ds_read_b128 v[42:45], v238 offset:512
	ds_read_b128 v[46:49], v238 offset:528
	v_and_b32_e32 v55, 0xffff0000, v114
	v_lshlrev_b32_e32 v56, 16, v115
	v_and_b32_e32 v57, 0xffff0000, v115
	s_waitcnt lgkmcnt(1)
	v_pk_fma_f32 v[40:41], v[40:41], v[44:45], v[56:57]
	v_pk_fma_f32 v[38:39], v[38:39], v[42:43], v[54:55]
	v_lshlrev_b32_e32 v42, 16, v116
	v_and_b32_e32 v43, 0xffff0000, v116
	v_lshlrev_b32_e32 v44, 16, v117
	v_and_b32_e32 v45, 0xffff0000, v117
	s_waitcnt lgkmcnt(0)
	v_pk_fma_f32 v[44:45], v[36:37], v[48:49], v[44:45]
	v_pk_fma_f32 v[36:37], v[34:35], v[46:47], v[42:43]
	v_cvt_pk_bf16_f32 v34, v38, v39
	v_cvt_pk_bf16_f32 v35, v40, v41
	s_nop 0
	v_cvt_pk_bf16_f32 v36, v36, v37
	v_cvt_pk_bf16_f32 v37, v44, v45
	v_and_b32_e32 v43, 0xffff0000, v34
	v_and_b32_e32 v45, 0xffff0000, v35
	global_store_dwordx4 v[52:53], v[34:37], off offset:256 sc1
	v_lshlrev_b32_e32 v42, 16, v34
	v_lshlrev_b32_e32 v44, 16, v35
	v_mul_f32_e32 v34, v43, v43
	v_mul_f32_e32 v35, v45, v45
	v_and_b32_e32 v47, 0xffff0000, v36
	v_and_b32_e32 v49, 0xffff0000, v37
	v_fmac_f32_e32 v34, v42, v42
	v_fmac_f32_e32 v35, v44, v44
	v_lshlrev_b32_e32 v46, 16, v36
	v_lshlrev_b32_e32 v48, 16, v37
	v_add_f32_e32 v52, v34, v35
	v_mul_f32_e32 v38, v47, v47
	v_mul_f32_e32 v39, v49, v49
	ds_read_b128 v[34:37], v238 offset:1536
	v_fmac_f32_e32 v38, v46, v46
	v_fmac_f32_e32 v39, v48, v48
	v_add_f32_e32 v53, v38, v39
	v_add_f32_e32 v52, v52, v53
	v_add_f32_e32 v52, v62, v52
	ds_read_b128 v[38:41], v238 offset:1552
	s_waitcnt lgkmcnt(1)
	v_pk_mul_f32 v[34:35], v[34:35], v[42:43]
	ds_swizzle_b32 v42, v52 offset:swizzle(SWAP,16)
	v_pk_mul_f32 v[36:37], v[36:37], v[44:45]
	v_cvt_pk_bf16_f32 v34, v34, v35
	s_waitcnt lgkmcnt(1)
	v_pk_mul_f32 v[40:41], v[40:41], v[48:49]
	v_pk_mul_f32 v[38:39], v[38:39], v[46:47]
	v_cvt_pk_bf16_f32 v35, v36, v37
	s_nop 0
	v_cvt_pk_bf16_f32 v36, v38, v39
	v_cvt_pk_bf16_f32 v37, v40, v41
	global_store_dwordx4 v[50:51], v[34:37], off offset:256 sc1
	s_waitcnt lgkmcnt(0)
	s_nop 0
	v_add_f32_e32 v34, v52, v42
	v_mov_b32_e32 v35, v34
	s_nop 1
	v_permlane32_swap_b32_e32 v34, v35
	s_and_saveexec_b64 s[22:23], vcc
	s_cbranch_execz .LBB0_526
	v_add_f32_e32 v34, v34, v35
	v_fma_f32 v34, v34, s74, 0.5
	v_cvt_u32_f32_e32 v34, v34
	global_atomic_add v[146:147], v34, off offset:576
.LBB0_526:
	s_or_b64 exec, exec, s[22:23]
	v_lshlrev_b64 v[34:35], 11, v[218:219]
	v_lshl_add_u64 v[42:43], v[34:35], 0, v[214:215]
	ds_read_b128 v[34:37], v238
	ds_read_b128 v[38:41], v238 offset:16
	v_lshlrev_b32_e32 v44, 16, v102
	v_and_b32_e32 v45, 0xffff0000, v102
	v_lshlrev_b32_e32 v46, 16, v103
	v_and_b32_e32 v47, 0xffff0000, v103
	s_waitcnt lgkmcnt(1)
	v_pk_fma_f32 v[32:33], v[32:33], v[36:37], v[46:47]
	v_pk_fma_f32 v[30:31], v[30:31], v[34:35], v[44:45]
	v_lshlrev_b32_e32 v34, 16, v104
	v_and_b32_e32 v35, 0xffff0000, v104
	v_lshlrev_b32_e32 v36, 16, v105
	v_and_b32_e32 v37, 0xffff0000, v105
	s_waitcnt lgkmcnt(0)
	v_pk_fma_f32 v[36:37], v[28:29], v[40:41], v[36:37]
	v_pk_fma_f32 v[28:29], v[26:27], v[38:39], v[34:35]
	v_lshlrev_b64 v[34:35], 1, v[42:43]
	v_cvt_pk_bf16_f32 v26, v30, v31
	v_cvt_pk_bf16_f32 v27, v32, v33
	v_cvt_pk_bf16_f32 v28, v28, v29
	v_cvt_pk_bf16_f32 v29, v36, v37
	v_lshl_add_u64 v[36:37], s[12:13], 0, v[34:35]
	v_and_b32_e32 v39, 0xffff0000, v26
	v_and_b32_e32 v41, 0xffff0000, v27
	global_store_dwordx4 v[36:37], v[26:29], off sc1
	v_lshlrev_b32_e32 v38, 16, v26
	v_lshlrev_b32_e32 v40, 16, v27
	v_and_b32_e32 v43, 0xffff0000, v28
	v_and_b32_e32 v45, 0xffff0000, v29
	v_mul_f32_e32 v26, v39, v39
	v_mul_f32_e32 v27, v41, v41
	v_lshlrev_b32_e32 v42, 16, v28
	v_lshlrev_b32_e32 v44, 16, v29
	v_fmac_f32_e32 v26, v38, v38
	v_fmac_f32_e32 v27, v40, v40
	v_mul_f32_e32 v30, v43, v43
	v_mul_f32_e32 v31, v45, v45
	v_add_f32_e32 v46, v26, v27
	v_fmac_f32_e32 v30, v42, v42
	v_fmac_f32_e32 v31, v44, v44
	ds_read_b128 v[26:29], v238 offset:1024
	v_add_f32_e32 v47, v30, v31
	ds_read_b128 v[30:33], v238 offset:1040
	v_lshl_add_u64 v[34:35], s[36:37], 0, v[34:35]
	v_add_f32_e32 v46, v46, v47
	s_waitcnt lgkmcnt(1)
	v_pk_mul_f32 v[28:29], v[28:29], v[40:41]
	v_pk_mul_f32 v[26:27], v[26:27], v[38:39]
	s_waitcnt lgkmcnt(0)
	v_pk_mul_f32 v[32:33], v[32:33], v[44:45]
	v_pk_mul_f32 v[30:31], v[30:31], v[42:43]
	v_cvt_pk_bf16_f32 v26, v26, v27
	v_cvt_pk_bf16_f32 v27, v28, v29
	v_lshlrev_b32_e32 v38, 16, v90
	v_cvt_pk_bf16_f32 v28, v30, v31
	v_cvt_pk_bf16_f32 v29, v32, v33
	global_store_dwordx4 v[34:35], v[26:29], off sc1
	ds_read_b128 v[26:29], v238 offset:512
	ds_read_b128 v[30:33], v238 offset:528
	v_and_b32_e32 v39, 0xffff0000, v90
	v_lshlrev_b32_e32 v40, 16, v91
	v_and_b32_e32 v41, 0xffff0000, v91
	s_waitcnt lgkmcnt(1)
	v_pk_fma_f32 v[24:25], v[24:25], v[28:29], v[40:41]
	v_pk_fma_f32 v[22:23], v[22:23], v[26:27], v[38:39]
	v_lshlrev_b32_e32 v26, 16, v92
	v_and_b32_e32 v27, 0xffff0000, v92
	v_lshlrev_b32_e32 v28, 16, v93
	v_and_b32_e32 v29, 0xffff0000, v93
	s_waitcnt lgkmcnt(0)
	v_pk_fma_f32 v[28:29], v[20:21], v[32:33], v[28:29]
	v_pk_fma_f32 v[20:21], v[18:19], v[30:31], v[26:27]
	v_cvt_pk_bf16_f32 v18, v22, v23
	v_cvt_pk_bf16_f32 v19, v24, v25
	s_nop 0
	v_cvt_pk_bf16_f32 v20, v20, v21
	v_cvt_pk_bf16_f32 v21, v28, v29
	v_and_b32_e32 v27, 0xffff0000, v18
	v_and_b32_e32 v29, 0xffff0000, v19
	global_store_dwordx4 v[36:37], v[18:21], off offset:256 sc1
	v_lshlrev_b32_e32 v26, 16, v18
	v_lshlrev_b32_e32 v28, 16, v19
	v_mul_f32_e32 v18, v27, v27
	v_mul_f32_e32 v19, v29, v29
	v_and_b32_e32 v31, 0xffff0000, v20
	v_and_b32_e32 v33, 0xffff0000, v21
	v_fmac_f32_e32 v18, v26, v26
	v_fmac_f32_e32 v19, v28, v28
	v_lshlrev_b32_e32 v30, 16, v20
	v_lshlrev_b32_e32 v32, 16, v21
	v_add_f32_e32 v36, v18, v19
	v_mul_f32_e32 v22, v31, v31
	v_mul_f32_e32 v23, v33, v33
	ds_read_b128 v[18:21], v238 offset:1536
	v_fmac_f32_e32 v22, v30, v30
	v_fmac_f32_e32 v23, v32, v32
	v_add_f32_e32 v37, v22, v23
	v_add_f32_e32 v36, v36, v37
	v_add_f32_e32 v36, v46, v36
	ds_read_b128 v[22:25], v238 offset:1552
	s_waitcnt lgkmcnt(1)
	v_pk_mul_f32 v[18:19], v[18:19], v[26:27]
	ds_swizzle_b32 v26, v36 offset:swizzle(SWAP,16)
	v_pk_mul_f32 v[20:21], v[20:21], v[28:29]
	v_cvt_pk_bf16_f32 v18, v18, v19
	s_waitcnt lgkmcnt(1)
	v_pk_mul_f32 v[24:25], v[24:25], v[32:33]
	v_pk_mul_f32 v[22:23], v[22:23], v[30:31]
	v_cvt_pk_bf16_f32 v19, v20, v21
	s_nop 0
	v_cvt_pk_bf16_f32 v20, v22, v23
	v_cvt_pk_bf16_f32 v21, v24, v25
	global_store_dwordx4 v[34:35], v[18:21], off offset:256 sc1
	s_waitcnt lgkmcnt(0)
	s_nop 0
	v_add_f32_e32 v18, v36, v26
	v_mov_b32_e32 v19, v18
	s_nop 1
	v_permlane32_swap_b32_e32 v18, v19
	s_and_saveexec_b64 s[22:23], vcc
	s_cbranch_execz .LBB0_528
	v_add_f32_e32 v18, v18, v19
	v_fma_f32 v18, v18, s74, 0.5
	v_cvt_u32_f32_e32 v18, v18
	global_atomic_add v[146:147], v18, off offset:640
.LBB0_528:
	s_or_b64 exec, exec, s[22:23]
	v_lshlrev_b64 v[18:19], 11, v[216:217]
	v_lshl_add_u64 v[26:27], v[18:19], 0, v[214:215]
	ds_read_b128 v[18:21], v238
	ds_read_b128 v[22:25], v238 offset:16
	v_lshlrev_b32_e32 v28, 16, v78
	v_and_b32_e32 v29, 0xffff0000, v78
	v_lshlrev_b32_e32 v30, 16, v79
	v_and_b32_e32 v31, 0xffff0000, v79
	s_waitcnt lgkmcnt(1)
	v_pk_fma_f32 v[16:17], v[16:17], v[20:21], v[30:31]
	v_pk_fma_f32 v[14:15], v[14:15], v[18:19], v[28:29]
	v_lshlrev_b32_e32 v18, 16, v80
	v_and_b32_e32 v19, 0xffff0000, v80
	v_lshlrev_b32_e32 v20, 16, v81
	v_and_b32_e32 v21, 0xffff0000, v81
	s_waitcnt lgkmcnt(0)
	v_pk_fma_f32 v[20:21], v[12:13], v[24:25], v[20:21]
	v_pk_fma_f32 v[12:13], v[10:11], v[22:23], v[18:19]
	v_lshlrev_b64 v[18:19], 1, v[26:27]
	v_cvt_pk_bf16_f32 v10, v14, v15
	v_cvt_pk_bf16_f32 v11, v16, v17
	v_cvt_pk_bf16_f32 v12, v12, v13
	v_cvt_pk_bf16_f32 v13, v20, v21
	v_lshl_add_u64 v[20:21], s[12:13], 0, v[18:19]
	v_and_b32_e32 v23, 0xffff0000, v10
	v_and_b32_e32 v25, 0xffff0000, v11
	global_store_dwordx4 v[20:21], v[10:13], off sc1
	v_lshlrev_b32_e32 v22, 16, v10
	v_lshlrev_b32_e32 v24, 16, v11
	v_and_b32_e32 v27, 0xffff0000, v12
	v_and_b32_e32 v29, 0xffff0000, v13
	v_mul_f32_e32 v10, v23, v23
	v_mul_f32_e32 v11, v25, v25
	v_lshlrev_b32_e32 v26, 16, v12
	v_lshlrev_b32_e32 v28, 16, v13
	v_fmac_f32_e32 v10, v22, v22
	v_fmac_f32_e32 v11, v24, v24
	v_mul_f32_e32 v14, v27, v27
	v_mul_f32_e32 v15, v29, v29
	v_add_f32_e32 v30, v10, v11
	v_fmac_f32_e32 v14, v26, v26
	v_fmac_f32_e32 v15, v28, v28
	ds_read_b128 v[10:13], v238 offset:1024
	v_add_f32_e32 v31, v14, v15
	ds_read_b128 v[14:17], v238 offset:1040
	v_lshl_add_u64 v[18:19], s[36:37], 0, v[18:19]
	v_add_f32_e32 v30, v30, v31
	s_waitcnt lgkmcnt(1)
	v_pk_mul_f32 v[12:13], v[12:13], v[24:25]
	v_pk_mul_f32 v[10:11], v[10:11], v[22:23]
	s_waitcnt lgkmcnt(0)
	v_pk_mul_f32 v[16:17], v[16:17], v[28:29]
	v_pk_mul_f32 v[14:15], v[14:15], v[26:27]
	v_cvt_pk_bf16_f32 v10, v10, v11
	v_cvt_pk_bf16_f32 v11, v12, v13
	v_lshlrev_b32_e32 v22, 16, v70
	v_cvt_pk_bf16_f32 v12, v14, v15
	v_cvt_pk_bf16_f32 v13, v16, v17
	global_store_dwordx4 v[18:19], v[10:13], off sc1
	ds_read_b128 v[10:13], v238 offset:512
	ds_read_b128 v[14:17], v238 offset:528
	v_and_b32_e32 v23, 0xffff0000, v70
	v_lshlrev_b32_e32 v24, 16, v71
	v_and_b32_e32 v25, 0xffff0000, v71
	s_waitcnt lgkmcnt(1)
	v_pk_fma_f32 v[8:9], v[8:9], v[12:13], v[24:25]
	v_pk_fma_f32 v[6:7], v[6:7], v[10:11], v[22:23]
	v_lshlrev_b32_e32 v10, 16, v72
	v_and_b32_e32 v11, 0xffff0000, v72
	v_lshlrev_b32_e32 v12, 16, v73
	v_and_b32_e32 v13, 0xffff0000, v73
	s_waitcnt lgkmcnt(0)
	v_pk_fma_f32 v[12:13], v[4:5], v[16:17], v[12:13]
	v_pk_fma_f32 v[4:5], v[2:3], v[14:15], v[10:11]
	v_cvt_pk_bf16_f32 v2, v6, v7
	v_cvt_pk_bf16_f32 v3, v8, v9
	s_nop 0
	v_cvt_pk_bf16_f32 v4, v4, v5
	v_cvt_pk_bf16_f32 v5, v12, v13
	v_and_b32_e32 v11, 0xffff0000, v2
	v_and_b32_e32 v13, 0xffff0000, v3
	global_store_dwordx4 v[20:21], v[2:5], off offset:256 sc1
	v_lshlrev_b32_e32 v10, 16, v2
	v_lshlrev_b32_e32 v12, 16, v3
	v_mul_f32_e32 v2, v11, v11
	v_mul_f32_e32 v3, v13, v13
	v_and_b32_e32 v15, 0xffff0000, v4
	v_and_b32_e32 v17, 0xffff0000, v5
	v_fmac_f32_e32 v2, v10, v10
	v_fmac_f32_e32 v3, v12, v12
	v_lshlrev_b32_e32 v14, 16, v4
	v_lshlrev_b32_e32 v16, 16, v5
	v_add_f32_e32 v20, v2, v3
	v_mul_f32_e32 v6, v15, v15
	v_mul_f32_e32 v7, v17, v17
	ds_read_b128 v[2:5], v238 offset:1536
	v_fmac_f32_e32 v6, v14, v14
	v_fmac_f32_e32 v7, v16, v16
	v_add_f32_e32 v21, v6, v7
	v_add_f32_e32 v20, v20, v21
	v_add_f32_e32 v20, v30, v20
	ds_read_b128 v[6:9], v238 offset:1552
	s_waitcnt lgkmcnt(1)
	v_pk_mul_f32 v[2:3], v[2:3], v[10:11]
	ds_swizzle_b32 v10, v20 offset:swizzle(SWAP,16)
	v_pk_mul_f32 v[4:5], v[4:5], v[12:13]
	v_cvt_pk_bf16_f32 v2, v2, v3
	s_waitcnt lgkmcnt(1)
	v_pk_mul_f32 v[8:9], v[8:9], v[16:17]
	v_pk_mul_f32 v[6:7], v[6:7], v[14:15]
	v_cvt_pk_bf16_f32 v3, v4, v5
	s_nop 0
	v_cvt_pk_bf16_f32 v4, v6, v7
	v_cvt_pk_bf16_f32 v5, v8, v9
	global_store_dwordx4 v[18:19], v[2:5], off offset:256 sc1
	s_waitcnt lgkmcnt(0)
	s_nop 0
	v_add_f32_e32 v2, v20, v10
	v_mov_b32_e32 v3, v2
	s_nop 1
	v_permlane32_swap_b32_e32 v2, v3
	s_and_saveexec_b64 s[22:23], vcc
	s_cbranch_execz .LBB0_530
	v_add_f32_e32 v2, v2, v3
	v_fma_f32 v2, v2, s74, 0.5
	v_cvt_u32_f32_e32 v2, v2
	global_atomic_add v[146:147], v2, off offset:704

.LBB0_586:
	v_mov_b32_e32 v153, v0
	s_lshl_b32 s22, s52, 8
	v_bfe_u32 v163, v153, 4, 2
	v_lshl_or_b32 v150, v163, 4, s67
	v_add_u32_e32 v140, s60, v150
	ds_read_b128 v[140:143], v140
	v_add_u32_e32 v144, s61, v150
	ds_read_b128 v[146:149], v144
	s_add_i32 s0, s22, s41
	v_and_or_b32 v153, v153, 15, s0
	s_waitcnt lgkmcnt(0)
	v_cvt_f32_i32_e32 v143, v143
	v_cvt_f32_i32_e32 v142, v142
	v_or_b32_e32 v154, 0x200, v150
	v_subrev_u32_e32 v158, s22, v153
	v_cvt_f32_i32_e32 v145, v141
	v_cvt_f32_i32_e32 v144, v140
	v_pk_mul_f32 v[140:141], v[142:143], s[88:89] op_sel_hi:[1,0]
	v_cvt_f32_i32_e32 v142, v148
	v_add_u32_e32 v148, s60, v154
	v_lshl_add_u32 v158, v158, 2, s59
	v_cvt_f32_i32_e32 v143, v149
	ds_read_b128 v[148:151], v148
	ds_read_b32 v160, v158
	v_add_u32_e32 v154, s61, v154
	ds_read_b128 v[154:157], v154
	v_pk_mul_f32 v[144:145], v[144:145], s[88:89] op_sel_hi:[1,0]
	s_waitcnt lgkmcnt(0)
	v_cvt_f32_i32_e32 v149, v149
	v_cvt_f32_i32_e32 v151, v151
	v_cvt_f32_i32_e32 v150, v150
	v_cvt_f32_i32_e32 v148, v148
	v_cvt_f32_u32_e32 v162, v160
	v_cvt_f32_i32_e32 v147, v147
	v_pk_mul_f32 v[158:159], v[150:151], s[88:89] op_sel_hi:[1,0]
	v_cvt_f32_i32_e32 v151, v155
	v_cvt_f32_i32_e32 v150, v154
	v_pk_mul_f32 v[154:155], v[148:149], s[88:89] op_sel_hi:[1,0]
	v_fmamk_f32 v148, v162, 0x35000000, v232
	v_rsq_f32_e32 v162, v148
	v_pk_mul_f32 v[160:161], v[150:151], s[88:89] op_sel_hi:[1,0]
	v_mov_b32_e32 v150, v118
	v_mov_b32_e32 v151, v126
	v_mov_b32_e32 v148, v154
	v_mov_b32_e32 v149, v144
	v_pk_fma_f32 v[164:165], v[150:151], v[162:163], v[148:149] op_sel_hi:[1,0,1]
	v_cvt_f32_i32_e32 v146, v146
	v_mul_f32_e32 v118, 0xbfb8aa3b, v165
	v_exp_f32_e32 v118, v118
	v_mov_b32_e32 v166, v114
	v_pk_mul_f32 v[146:147], v[146:147], s[88:89] op_sel_hi:[1,0]
	v_mov_b32_e32 v167, v122
	v_add_f32_e32 v118, 1.0, v118
	v_mov_b32_e32 v150, v160
	v_mov_b32_e32 v151, v146
	v_rcp_f32_e32 v118, v118
	v_pk_fma_f32 v[166:167], v[166:167], v[162:163], v[150:151] op_sel_hi:[1,0,1]
	v_mov_b32_e32 v126, v119
	v_mul_f32_e32 v114, 0xbfb8aa3b, v167
	v_exp_f32_e32 v114, v114
	v_mul_f32_e32 v118, v165, v118
	v_mov_b32_e32 v144, v155
	v_mul_f32_e32 v160, v164, v118
	v_pk_fma_f32 v[118:119], v[126:127], v[162:163], v[144:145] op_sel_hi:[1,0,1]
	v_add_f32_e32 v114, 1.0, v114
	v_mul_f32_e32 v122, 0xbfb8aa3b, v119
	v_exp_f32_e32 v126, v122
	v_mov_b32_e32 v122, v115
	v_mov_b32_e32 v146, v161
	v_rcp_f32_e32 v114, v114
	v_pk_fma_f32 v[122:123], v[122:123], v[162:163], v[146:147] op_sel_hi:[1,0,1]
	v_mov_b32_e32 v127, v128
	v_mul_f32_e32 v115, 0xbfb8aa3b, v123
	v_exp_f32_e32 v115, v115
	v_mul_f32_e32 v114, v167, v114
	v_mul_f32_e32 v161, v166, v114
	v_add_f32_e32 v114, 1.0, v126
	v_rcp_f32_e32 v154, v114
	v_add_f32_e32 v114, 1.0, v115
	v_rcp_f32_e32 v155, v114
	v_mov_b32_e32 v126, v120
	v_mov_b32_e32 v114, v158
	v_mov_b32_e32 v115, v140
	v_pk_fma_f32 v[126:127], v[126:127], v[162:163], v[114:115] op_sel_hi:[1,0,1]
	v_cvt_f32_i32_e32 v157, v157
	v_mul_f32_e32 v120, 0xbfb8aa3b, v127
	v_cvt_f32_i32_e32 v156, v156
	v_exp_f32_e32 v120, v120
	v_mul_f32_e32 v119, v119, v154
	v_pk_mul_f32 v[142:143], v[142:143], s[88:89] op_sel_hi:[1,0]
	v_pk_mul_f32 v[156:157], v[156:157], s[88:89] op_sel_hi:[1,0]
	v_mul_f32_e32 v158, v118, v119
	v_add_f32_e32 v118, 1.0, v120
	v_mul_f32_e32 v123, v123, v155
	v_rcp_f32_e32 v120, v118
	v_mov_b32_e32 v154, v116
	v_mov_b32_e32 v155, v124
	v_mov_b32_e32 v118, v156
	v_mov_b32_e32 v119, v142
	v_pk_fma_f32 v[154:155], v[154:155], v[162:163], v[118:119] op_sel_hi:[1,0,1]
	v_mul_f32_e32 v120, v127, v120
	v_mul_f32_e32 v116, 0xbfb8aa3b, v155
	v_exp_f32_e32 v116, v116
	v_mov_b32_e32 v128, v121
	v_mov_b32_e32 v140, v159
	v_mul_f32_e32 v156, v122, v123
	v_mul_f32_e32 v123, v126, v120
	v_add_f32_e32 v116, 1.0, v116
	v_pk_fma_f32 v[120:121], v[128:129], v[162:163], v[140:141] op_sel_hi:[1,0,1]
	v_rcp_f32_e32 v122, v116
	v_mul_f32_e32 v116, 0xbfb8aa3b, v121
	v_mov_b32_e32 v124, v117
	v_mov_b32_e32 v142, v157
	v_exp_f32_e32 v126, v116
	v_pk_fma_f32 v[116:117], v[124:125], v[162:163], v[142:143] op_sel_hi:[1,0,1]
	v_mul_f32_e32 v122, v155, v122
	v_mul_f32_e32 v124, 0xbfb8aa3b, v117
	v_exp_f32_e32 v124, v124
	v_add_f32_e32 v125, 1.0, v126
	v_rcp_f32_e32 v125, v125
	v_or_b32_e32 v129, 16, v153
	v_add_f32_e32 v124, 1.0, v124
	v_rcp_f32_e32 v124, v124
	v_mul_f32_e32 v121, v121, v125
	v_mul_f32_e32 v126, v154, v122
	v_mul_f32_e32 v120, v120, v121
	v_mul_f32_e32 v117, v117, v124
	v_mul_f32_e32 v116, v116, v117
	v_cvt_pk_bf16_f32 v122, v160, v158
	v_cvt_pk_bf16_f32 v123, v123, v120
	v_cvt_pk_bf16_f32 v124, v161, v156
	v_cvt_pk_bf16_f32 v125, v126, v116
	v_subrev_u32_e32 v116, s22, v129
	v_lshl_add_u32 v116, v116, 2, s59
	ds_read_b32 v116, v116
	v_mov_b32_e32 v154, v102
	v_mov_b32_e32 v155, v110
	v_mov_b32_e32 v156, v98
	v_mov_b32_e32 v157, v106
	s_waitcnt lgkmcnt(0)
	v_cvt_f32_u32_e32 v128, v116
	s_lshl_b32 s0, s44, 7
	v_lshl_or_b32 v117, v163, 3, s0
	v_or_b32_e32 v120, s43, v117
	v_fmamk_f32 v128, v128, 0x35000000, v232
	v_rsq_f32_e32 v128, v128
	v_ashrrev_i32_e32 v121, 31, v120
	v_mov_b64_e32 v[116:117], s[10:11]
	v_mad_i64_i32 v[126:127], s[0:1], v153, s66, v[116:117]
	v_pk_fma_f32 v[154:155], v[154:155], v[128:129], v[148:149] op_sel_hi:[1,0,1]
	v_pk_fma_f32 v[156:157], v[156:157], v[128:129], v[150:151] op_sel_hi:[1,0,1]
	v_mul_f32_e32 v102, 0xbfb8aa3b, v155
	v_exp_f32_e32 v102, v102
	v_mul_f32_e32 v98, 0xbfb8aa3b, v157
	v_exp_f32_e32 v98, v98
	v_lshlrev_b64 v[120:121], 1, v[120:121]
	v_add_f32_e32 v102, 1.0, v102
	v_rcp_f32_e32 v102, v102
	v_add_f32_e32 v98, 1.0, v98
	v_rcp_f32_e32 v98, v98
	v_lshl_add_u64 v[126:127], v[126:127], 0, v[120:121]
	v_mul_f32_e32 v102, v155, v102
	v_mov_b32_e32 v110, v103
	global_store_dwordx4 v[126:127], v[122:125], off sc1
	v_mov_b32_e32 v106, v99
	s_andn2_b64 vcc, exec, s[6:7]
	v_mul_f32_e32 v122, v154, v102
	v_pk_fma_f32 v[102:103], v[110:111], v[128:129], v[144:145] op_sel_hi:[1,0,1]
	v_mul_f32_e32 v123, v157, v98
	v_mul_f32_e32 v98, 0xbfb8aa3b, v103
	v_exp_f32_e32 v110, v98
	v_pk_fma_f32 v[98:99], v[106:107], v[128:129], v[146:147] op_sel_hi:[1,0,1]
	v_mul_f32_e32 v111, v156, v123
	v_mul_f32_e32 v106, 0xbfb8aa3b, v99
	v_exp_f32_e32 v106, v106
	v_add_f32_e32 v107, 1.0, v110
	v_rcp_f32_e32 v110, v107
	v_mov_b32_e32 v107, v112
	v_add_f32_e32 v106, 1.0, v106
	v_rcp_f32_e32 v123, v106
	v_mov_b32_e32 v106, v104
	v_pk_fma_f32 v[106:107], v[106:107], v[128:129], v[114:115] op_sel_hi:[1,0,1]
	v_mul_f32_e32 v103, v103, v110
	v_mul_f32_e32 v104, 0xbfb8aa3b, v107
	v_exp_f32_e32 v104, v104
	v_mul_f32_e32 v110, v102, v103
	v_mov_b32_e32 v103, v108
	v_mul_f32_e32 v99, v99, v123
	v_add_f32_e32 v102, 1.0, v104
	v_rcp_f32_e32 v104, v102
	v_mov_b32_e32 v102, v100
	v_pk_fma_f32 v[102:103], v[102:103], v[128:129], v[118:119] op_sel_hi:[1,0,1]
	v_mul_f32_e32 v123, v98, v99
	v_mul_f32_e32 v100, 0xbfb8aa3b, v103
	v_exp_f32_e32 v100, v100
	v_mul_f32_e32 v98, v107, v104
	v_mul_f32_e32 v104, v106, v98
	v_mov_b32_e32 v112, v105
	v_add_f32_e32 v98, 1.0, v100
	v_rcp_f32_e32 v106, v98
	v_pk_fma_f32 v[98:99], v[112:113], v[128:129], v[140:141] op_sel_hi:[1,0,1]
	v_mov_b32_e32 v108, v101
	v_mul_f32_e32 v100, 0xbfb8aa3b, v99
	v_exp_f32_e32 v105, v100
	v_pk_fma_f32 v[100:101], v[108:109], v[128:129], v[142:143] op_sel_hi:[1,0,1]
	v_mul_f32_e32 v103, v103, v106
	v_mul_f32_e32 v107, 0xbfb8aa3b, v101
	v_exp_f32_e32 v107, v107
	v_add_f32_e32 v105, 1.0, v105
	v_rcp_f32_e32 v105, v105
	v_mul_f32_e32 v102, v102, v103
	v_add_f32_e32 v106, 1.0, v107
	v_rcp_f32_e32 v106, v106
	v_mul_f32_e32 v99, v99, v105
	v_mul_f32_e32 v99, v98, v99
	v_or_b32_e32 v103, 32, v153
	v_mul_f32_e32 v98, v101, v106
	v_mul_f32_e32 v101, v100, v98
	v_cvt_pk_bf16_f32 v98, v122, v110
	v_cvt_pk_bf16_f32 v99, v104, v99
	v_cvt_pk_bf16_f32 v100, v111, v123
	v_cvt_pk_bf16_f32 v101, v102, v101
	v_subrev_u32_e32 v102, s22, v103
	v_lshl_add_u32 v102, v102, 2, s59
	ds_read_b32 v102, v102
	v_mov_b32_e32 v106, v86
	v_mov_b32_e32 v107, v94
	v_mov_b32_e32 v108, v82
	v_mov_b32_e32 v109, v90
	s_waitcnt lgkmcnt(0)
	v_cvt_f32_u32_e32 v102, v102
	v_mad_i64_i32 v[104:105], s[0:1], v129, s66, v[116:117]
	v_lshl_add_u64 v[104:105], v[104:105], 0, v[120:121]
	v_fmamk_f32 v102, v102, 0x35000000, v232
	v_rsq_f32_e32 v102, v102
	v_mov_b32_e32 v94, v87
	global_store_dwordx4 v[104:105], v[98:101], off sc1
	v_mov_b32_e32 v90, v83
	v_pk_fma_f32 v[106:107], v[106:107], v[102:103], v[148:149] op_sel_hi:[1,0,1]
	v_pk_fma_f32 v[108:109], v[108:109], v[102:103], v[150:151] op_sel_hi:[1,0,1]
	v_mul_f32_e32 v86, 0xbfb8aa3b, v107
	v_exp_f32_e32 v86, v86
	v_mul_f32_e32 v82, 0xbfb8aa3b, v109
	v_exp_f32_e32 v82, v82
	s_mov_b64 s[6:7], -1
	v_add_f32_e32 v86, 1.0, v86
	v_rcp_f32_e32 v86, v86
	v_add_f32_e32 v82, 1.0, v82
	v_rcp_f32_e32 v82, v82
	v_mul_f32_e32 v86, v107, v86
	v_mul_f32_e32 v98, v106, v86
	v_pk_fma_f32 v[86:87], v[94:95], v[102:103], v[144:145] op_sel_hi:[1,0,1]
	v_mul_f32_e32 v99, v109, v82
	v_mul_f32_e32 v82, 0xbfb8aa3b, v87
	v_exp_f32_e32 v94, v82
	v_pk_fma_f32 v[82:83], v[90:91], v[102:103], v[146:147] op_sel_hi:[1,0,1]
	v_mul_f32_e32 v95, v108, v99
	v_mul_f32_e32 v90, 0xbfb8aa3b, v83
	v_exp_f32_e32 v90, v90
	v_add_f32_e32 v91, 1.0, v94
	v_rcp_f32_e32 v94, v91
	v_mov_b32_e32 v91, v96
	v_add_f32_e32 v90, 1.0, v90
	v_rcp_f32_e32 v99, v90
	v_mov_b32_e32 v90, v88
	v_pk_fma_f32 v[90:91], v[90:91], v[102:103], v[114:115] op_sel_hi:[1,0,1]
	v_mul_f32_e32 v87, v87, v94
	v_mul_f32_e32 v88, 0xbfb8aa3b, v91
	v_exp_f32_e32 v88, v88
	v_mul_f32_e32 v94, v86, v87
	v_mov_b32_e32 v87, v92
	v_mul_f32_e32 v83, v83, v99
	v_add_f32_e32 v86, 1.0, v88
	v_rcp_f32_e32 v88, v86
	v_mov_b32_e32 v86, v84
	v_pk_fma_f32 v[86:87], v[86:87], v[102:103], v[118:119] op_sel_hi:[1,0,1]
	v_mul_f32_e32 v99, v82, v83
	v_mul_f32_e32 v84, 0xbfb8aa3b, v87
	v_exp_f32_e32 v84, v84
	v_mul_f32_e32 v82, v91, v88
	v_mul_f32_e32 v88, v90, v82
	v_mov_b32_e32 v96, v89
	v_add_f32_e32 v82, 1.0, v84
	v_rcp_f32_e32 v90, v82
	v_pk_fma_f32 v[82:83], v[96:97], v[102:103], v[140:141] op_sel_hi:[1,0,1]
	v_mov_b32_e32 v92, v85
	v_mul_f32_e32 v84, 0xbfb8aa3b, v83
	v_exp_f32_e32 v89, v84
	v_pk_fma_f32 v[84:85], v[92:93], v[102:103], v[142:143] op_sel_hi:[1,0,1]
	v_mul_f32_e32 v87, v87, v90
	v_mul_f32_e32 v91, 0xbfb8aa3b, v85
	v_exp_f32_e32 v91, v91
	v_add_f32_e32 v89, 1.0, v89
	v_rcp_f32_e32 v89, v89
	v_mul_f32_e32 v86, v86, v87
	v_add_f32_e32 v90, 1.0, v91
	v_rcp_f32_e32 v90, v90
	v_mul_f32_e32 v83, v83, v89
	v_mul_f32_e32 v83, v82, v83
	v_or_b32_e32 v87, 48, v153
	v_mul_f32_e32 v82, v85, v90
	v_mul_f32_e32 v85, v84, v82
	v_cvt_pk_bf16_f32 v82, v98, v94
	v_cvt_pk_bf16_f32 v83, v88, v83
	v_cvt_pk_bf16_f32 v84, v95, v99
	v_cvt_pk_bf16_f32 v85, v86, v85
	v_subrev_u32_e32 v86, s22, v87
	v_lshl_add_u32 v86, v86, 2, s59
	ds_read_b32 v86, v86
	v_mov_b32_e32 v90, v70
	v_mov_b32_e32 v91, v78
	v_mov_b32_e32 v92, v66
	v_mov_b32_e32 v93, v74
	s_waitcnt lgkmcnt(0)
	v_cvt_f32_u32_e32 v86, v86
	v_mad_i64_i32 v[88:89], s[0:1], v103, s66, v[116:117]
	v_lshl_add_u64 v[88:89], v[88:89], 0, v[120:121]
	v_fmamk_f32 v86, v86, 0x35000000, v232
	v_rsq_f32_e32 v86, v86
	v_mov_b32_e32 v78, v71
	global_store_dwordx4 v[88:89], v[82:85], off sc1
	v_mov_b32_e32 v74, v67
	v_pk_fma_f32 v[90:91], v[90:91], v[86:87], v[148:149] op_sel_hi:[1,0,1]
	v_pk_fma_f32 v[92:93], v[92:93], v[86:87], v[150:151] op_sel_hi:[1,0,1]
	v_mul_f32_e32 v70, 0xbfb8aa3b, v91
	v_exp_f32_e32 v70, v70
	v_mul_f32_e32 v66, 0xbfb8aa3b, v93
	v_exp_f32_e32 v66, v66
	v_add_f32_e32 v70, 1.0, v70
	v_rcp_f32_e32 v70, v70
	v_add_f32_e32 v66, 1.0, v66
	v_rcp_f32_e32 v66, v66
	v_mul_f32_e32 v70, v91, v70
	v_mul_f32_e32 v82, v90, v70
	v_pk_fma_f32 v[70:71], v[78:79], v[86:87], v[144:145] op_sel_hi:[1,0,1]
	v_mul_f32_e32 v83, v93, v66
	v_mul_f32_e32 v66, 0xbfb8aa3b, v71
	v_exp_f32_e32 v78, v66
	v_pk_fma_f32 v[66:67], v[74:75], v[86:87], v[146:147] op_sel_hi:[1,0,1]
	v_mul_f32_e32 v79, v92, v83
	v_mul_f32_e32 v74, 0xbfb8aa3b, v67
	v_exp_f32_e32 v74, v74
	v_add_f32_e32 v75, 1.0, v78
	v_rcp_f32_e32 v78, v75
	v_mov_b32_e32 v75, v80
	v_add_f32_e32 v74, 1.0, v74
	v_rcp_f32_e32 v83, v74
	v_mov_b32_e32 v74, v72
	v_pk_fma_f32 v[74:75], v[74:75], v[86:87], v[114:115] op_sel_hi:[1,0,1]
	v_mul_f32_e32 v71, v71, v78
	v_mul_f32_e32 v72, 0xbfb8aa3b, v75
	v_exp_f32_e32 v72, v72
	v_mul_f32_e32 v78, v70, v71
	v_mov_b32_e32 v71, v76
	v_mul_f32_e32 v67, v67, v83
	v_add_f32_e32 v70, 1.0, v72
	v_rcp_f32_e32 v72, v70
	v_mov_b32_e32 v70, v68
	v_pk_fma_f32 v[70:71], v[70:71], v[86:87], v[118:119] op_sel_hi:[1,0,1]
	v_mul_f32_e32 v83, v66, v67
	v_mul_f32_e32 v68, 0xbfb8aa3b, v71
	v_exp_f32_e32 v68, v68
	v_mul_f32_e32 v66, v75, v72
	v_mul_f32_e32 v72, v74, v66
	v_mov_b32_e32 v80, v73
	v_add_f32_e32 v66, 1.0, v68
	v_rcp_f32_e32 v74, v66
	v_pk_fma_f32 v[66:67], v[80:81], v[86:87], v[140:141] op_sel_hi:[1,0,1]
	v_mov_b32_e32 v76, v69
	v_mul_f32_e32 v68, 0xbfb8aa3b, v67
	v_exp_f32_e32 v73, v68
	v_pk_fma_f32 v[68:69], v[76:77], v[86:87], v[142:143] op_sel_hi:[1,0,1]
	v_mul_f32_e32 v71, v71, v74
	v_mul_f32_e32 v75, 0xbfb8aa3b, v69
	v_exp_f32_e32 v75, v75
	v_add_f32_e32 v73, 1.0, v73
	v_rcp_f32_e32 v73, v73
	v_mul_f32_e32 v70, v70, v71
	v_add_f32_e32 v74, 1.0, v75
	v_rcp_f32_e32 v74, v74
	v_mul_f32_e32 v67, v67, v73
	v_mul_f32_e32 v67, v66, v67
	v_add_u32_e32 v71, 0x80, v153
	v_mul_f32_e32 v66, v69, v74
	v_mul_f32_e32 v69, v68, v66
	v_cvt_pk_bf16_f32 v66, v82, v78
	v_cvt_pk_bf16_f32 v67, v72, v67
	v_cvt_pk_bf16_f32 v68, v79, v83
	v_cvt_pk_bf16_f32 v69, v70, v69
	v_subrev_u32_e32 v70, s22, v71
	v_lshl_add_u32 v70, v70, 2, s59
	ds_read_b32 v70, v70
	v_mov_b32_e32 v74, v54
	v_mov_b32_e32 v75, v62
	v_mov_b32_e32 v76, v50
	v_mov_b32_e32 v77, v58
	s_waitcnt lgkmcnt(0)
	v_cvt_f32_u32_e32 v70, v70
	v_mad_i64_i32 v[72:73], s[0:1], v87, s66, v[116:117]
	v_lshl_add_u64 v[72:73], v[72:73], 0, v[120:121]
	v_fmamk_f32 v70, v70, 0x35000000, v232
	v_rsq_f32_e32 v70, v70
	v_mov_b32_e32 v62, v55
	global_store_dwordx4 v[72:73], v[66:69], off sc1
	v_mov_b32_e32 v58, v51
	v_pk_fma_f32 v[74:75], v[74:75], v[70:71], v[148:149] op_sel_hi:[1,0,1]
	v_pk_fma_f32 v[76:77], v[76:77], v[70:71], v[150:151] op_sel_hi:[1,0,1]
	v_mul_f32_e32 v54, 0xbfb8aa3b, v75
	v_exp_f32_e32 v54, v54
	v_mul_f32_e32 v50, 0xbfb8aa3b, v77
	v_exp_f32_e32 v50, v50
	v_add_f32_e32 v54, 1.0, v54
	v_rcp_f32_e32 v54, v54
	v_add_f32_e32 v50, 1.0, v50
	v_rcp_f32_e32 v50, v50
	v_mul_f32_e32 v54, v75, v54
	v_mul_f32_e32 v66, v74, v54
	v_pk_fma_f32 v[54:55], v[62:63], v[70:71], v[144:145] op_sel_hi:[1,0,1]
	v_mul_f32_e32 v67, v77, v50
	v_mul_f32_e32 v50, 0xbfb8aa3b, v55
	v_exp_f32_e32 v62, v50
	v_pk_fma_f32 v[50:51], v[58:59], v[70:71], v[146:147] op_sel_hi:[1,0,1]
	v_mul_f32_e32 v63, v76, v67
	v_mul_f32_e32 v58, 0xbfb8aa3b, v51
	v_exp_f32_e32 v58, v58
	v_add_f32_e32 v59, 1.0, v62
	v_rcp_f32_e32 v62, v59
	v_mov_b32_e32 v59, v64
	v_add_f32_e32 v58, 1.0, v58
	v_rcp_f32_e32 v67, v58
	v_mov_b32_e32 v58, v56
	v_pk_fma_f32 v[58:59], v[58:59], v[70:71], v[114:115] op_sel_hi:[1,0,1]
	v_mul_f32_e32 v55, v55, v62
	v_mul_f32_e32 v56, 0xbfb8aa3b, v59
	v_exp_f32_e32 v56, v56
	v_mul_f32_e32 v62, v54, v55
	v_mov_b32_e32 v55, v60
	v_mul_f32_e32 v51, v51, v67
	v_add_f32_e32 v54, 1.0, v56
	v_rcp_f32_e32 v56, v54
	v_mov_b32_e32 v54, v52
	v_pk_fma_f32 v[54:55], v[54:55], v[70:71], v[118:119] op_sel_hi:[1,0,1]
	v_mul_f32_e32 v67, v50, v51
	v_mul_f32_e32 v52, 0xbfb8aa3b, v55
	v_exp_f32_e32 v52, v52
	v_mul_f32_e32 v50, v59, v56
	v_mul_f32_e32 v56, v58, v50
	v_mov_b32_e32 v64, v57
	v_add_f32_e32 v50, 1.0, v52
	v_rcp_f32_e32 v58, v50
	v_pk_fma_f32 v[50:51], v[64:65], v[70:71], v[140:141] op_sel_hi:[1,0,1]
	v_mov_b32_e32 v60, v53
	v_mul_f32_e32 v52, 0xbfb8aa3b, v51
	v_exp_f32_e32 v57, v52
	v_pk_fma_f32 v[52:53], v[60:61], v[70:71], v[142:143] op_sel_hi:[1,0,1]
	v_mul_f32_e32 v55, v55, v58
	v_mul_f32_e32 v59, 0xbfb8aa3b, v53
	v_exp_f32_e32 v59, v59
	v_add_f32_e32 v57, 1.0, v57
	v_rcp_f32_e32 v57, v57
	v_mul_f32_e32 v54, v54, v55
	v_add_f32_e32 v58, 1.0, v59
	v_rcp_f32_e32 v58, v58
	v_mul_f32_e32 v51, v51, v57
	v_mul_f32_e32 v51, v50, v51
	v_add_u32_e32 v55, 0x90, v153
	v_mul_f32_e32 v50, v53, v58
	v_mul_f32_e32 v53, v52, v50
	v_cvt_pk_bf16_f32 v50, v66, v62
	v_cvt_pk_bf16_f32 v51, v56, v51
	v_cvt_pk_bf16_f32 v52, v63, v67
	v_cvt_pk_bf16_f32 v53, v54, v53
	v_subrev_u32_e32 v54, s22, v55
	v_lshl_add_u32 v54, v54, 2, s59
	ds_read_b32 v54, v54
	v_mov_b32_e32 v58, v38
	v_mov_b32_e32 v59, v46
	v_mov_b32_e32 v60, v34
	v_mov_b32_e32 v61, v42
	s_waitcnt lgkmcnt(0)
	v_cvt_f32_u32_e32 v54, v54
	v_mad_i64_i32 v[56:57], s[0:1], v71, s66, v[116:117]
	v_lshl_add_u64 v[56:57], v[56:57], 0, v[120:121]
	v_fmamk_f32 v54, v54, 0x35000000, v232
	v_rsq_f32_e32 v54, v54
	v_mov_b32_e32 v46, v39
	global_store_dwordx4 v[56:57], v[50:53], off sc1
	v_mov_b32_e32 v42, v35
	v_pk_fma_f32 v[58:59], v[58:59], v[54:55], v[148:149] op_sel_hi:[1,0,1]
	v_pk_fma_f32 v[60:61], v[60:61], v[54:55], v[150:151] op_sel_hi:[1,0,1]
	v_mul_f32_e32 v38, 0xbfb8aa3b, v59
	v_exp_f32_e32 v38, v38
	v_mul_f32_e32 v34, 0xbfb8aa3b, v61
	v_exp_f32_e32 v34, v34
	v_add_f32_e32 v38, 1.0, v38
	v_rcp_f32_e32 v38, v38
	v_add_f32_e32 v34, 1.0, v34
	v_rcp_f32_e32 v34, v34
	v_mul_f32_e32 v38, v59, v38
	v_mul_f32_e32 v50, v58, v38
	v_pk_fma_f32 v[38:39], v[46:47], v[54:55], v[144:145] op_sel_hi:[1,0,1]
	v_mul_f32_e32 v51, v61, v34
	v_mul_f32_e32 v34, 0xbfb8aa3b, v39
	v_exp_f32_e32 v46, v34
	v_pk_fma_f32 v[34:35], v[42:43], v[54:55], v[146:147] op_sel_hi:[1,0,1]
	v_mul_f32_e32 v47, v60, v51
	v_mul_f32_e32 v42, 0xbfb8aa3b, v35
	v_exp_f32_e32 v42, v42
	v_add_f32_e32 v43, 1.0, v46
	v_rcp_f32_e32 v46, v43
	v_mov_b32_e32 v43, v48
	v_add_f32_e32 v42, 1.0, v42
	v_rcp_f32_e32 v51, v42
	v_mov_b32_e32 v42, v40
	v_pk_fma_f32 v[42:43], v[42:43], v[54:55], v[114:115] op_sel_hi:[1,0,1]
	v_mul_f32_e32 v39, v39, v46
	v_mul_f32_e32 v40, 0xbfb8aa3b, v43
	v_exp_f32_e32 v40, v40
	v_mul_f32_e32 v46, v38, v39
	v_mov_b32_e32 v39, v44
	v_mul_f32_e32 v35, v35, v51
	v_add_f32_e32 v38, 1.0, v40
	v_rcp_f32_e32 v40, v38
	v_mov_b32_e32 v38, v36
	v_pk_fma_f32 v[38:39], v[38:39], v[54:55], v[118:119] op_sel_hi:[1,0,1]
	v_mul_f32_e32 v51, v34, v35
	v_mul_f32_e32 v36, 0xbfb8aa3b, v39
	v_exp_f32_e32 v36, v36
	v_mul_f32_e32 v34, v43, v40
	v_mul_f32_e32 v40, v42, v34
	v_mov_b32_e32 v48, v41
	v_add_f32_e32 v34, 1.0, v36
	v_rcp_f32_e32 v42, v34
	v_pk_fma_f32 v[34:35], v[48:49], v[54:55], v[140:141] op_sel_hi:[1,0,1]
	v_mov_b32_e32 v44, v37
	v_mul_f32_e32 v36, 0xbfb8aa3b, v35
	v_exp_f32_e32 v41, v36
	v_pk_fma_f32 v[36:37], v[44:45], v[54:55], v[142:143] op_sel_hi:[1,0,1]
	v_mul_f32_e32 v39, v39, v42
	v_mul_f32_e32 v43, 0xbfb8aa3b, v37
	v_exp_f32_e32 v43, v43
	v_add_f32_e32 v41, 1.0, v41
	v_rcp_f32_e32 v41, v41
	v_mul_f32_e32 v38, v38, v39
	v_add_f32_e32 v42, 1.0, v43
	v_rcp_f32_e32 v42, v42
	v_mul_f32_e32 v35, v35, v41
	v_mul_f32_e32 v35, v34, v35
	v_add_u32_e32 v39, 0xa0, v153
	v_mul_f32_e32 v34, v37, v42
	v_mul_f32_e32 v37, v36, v34
	v_cvt_pk_bf16_f32 v34, v50, v46
	v_cvt_pk_bf16_f32 v35, v40, v35
	v_cvt_pk_bf16_f32 v36, v47, v51
	v_cvt_pk_bf16_f32 v37, v38, v37
	v_subrev_u32_e32 v38, s22, v39
	v_lshl_add_u32 v38, v38, 2, s59
	ds_read_b32 v38, v38
	v_mov_b32_e32 v42, v22
	v_mov_b32_e32 v43, v30
	v_mov_b32_e32 v44, v18
	v_mov_b32_e32 v45, v26
	s_waitcnt lgkmcnt(0)
	v_cvt_f32_u32_e32 v38, v38
	v_mad_i64_i32 v[40:41], s[0:1], v55, s66, v[116:117]
	v_lshl_add_u64 v[40:41], v[40:41], 0, v[120:121]
	v_fmamk_f32 v38, v38, 0x35000000, v232
	v_rsq_f32_e32 v38, v38
	v_mov_b32_e32 v30, v23
	global_store_dwordx4 v[40:41], v[34:37], off sc1
	v_mov_b32_e32 v26, v19
	v_pk_fma_f32 v[42:43], v[42:43], v[38:39], v[148:149] op_sel_hi:[1,0,1]
	v_pk_fma_f32 v[44:45], v[44:45], v[38:39], v[150:151] op_sel_hi:[1,0,1]
	v_mul_f32_e32 v22, 0xbfb8aa3b, v43
	v_exp_f32_e32 v22, v22
	v_mul_f32_e32 v18, 0xbfb8aa3b, v45
	v_exp_f32_e32 v18, v18
	v_add_f32_e32 v22, 1.0, v22
	v_rcp_f32_e32 v22, v22
	v_add_f32_e32 v18, 1.0, v18
	v_rcp_f32_e32 v18, v18
	v_mul_f32_e32 v22, v43, v22
	v_mul_f32_e32 v34, v42, v22
	v_pk_fma_f32 v[22:23], v[30:31], v[38:39], v[144:145] op_sel_hi:[1,0,1]
	v_mul_f32_e32 v35, v45, v18
	v_mul_f32_e32 v18, 0xbfb8aa3b, v23
	v_exp_f32_e32 v30, v18
	v_pk_fma_f32 v[18:19], v[26:27], v[38:39], v[146:147] op_sel_hi:[1,0,1]
	v_mul_f32_e32 v31, v44, v35
	v_mul_f32_e32 v26, 0xbfb8aa3b, v19
	v_exp_f32_e32 v26, v26
	v_add_f32_e32 v27, 1.0, v30
	v_rcp_f32_e32 v30, v27
	v_mov_b32_e32 v27, v32
	v_add_f32_e32 v26, 1.0, v26
	v_rcp_f32_e32 v35, v26
	v_mov_b32_e32 v26, v24
	v_pk_fma_f32 v[26:27], v[26:27], v[38:39], v[114:115] op_sel_hi:[1,0,1]
	v_mul_f32_e32 v23, v23, v30
	v_mul_f32_e32 v24, 0xbfb8aa3b, v27
	v_exp_f32_e32 v24, v24
	v_mul_f32_e32 v30, v22, v23
	v_mov_b32_e32 v23, v28
	v_mul_f32_e32 v19, v19, v35
	v_add_f32_e32 v22, 1.0, v24
	v_rcp_f32_e32 v24, v22
	v_mov_b32_e32 v22, v20
	v_pk_fma_f32 v[22:23], v[22:23], v[38:39], v[118:119] op_sel_hi:[1,0,1]
	v_mul_f32_e32 v35, v18, v19
	v_mul_f32_e32 v20, 0xbfb8aa3b, v23
	v_exp_f32_e32 v20, v20
	v_mul_f32_e32 v18, v27, v24
	v_mul_f32_e32 v24, v26, v18
	v_mov_b32_e32 v32, v25
	v_add_f32_e32 v18, 1.0, v20
	v_rcp_f32_e32 v26, v18
	v_pk_fma_f32 v[18:19], v[32:33], v[38:39], v[140:141] op_sel_hi:[1,0,1]
	v_mov_b32_e32 v28, v21
	v_mul_f32_e32 v20, 0xbfb8aa3b, v19
	v_exp_f32_e32 v25, v20
	v_pk_fma_f32 v[20:21], v[28:29], v[38:39], v[142:143] op_sel_hi:[1,0,1]
	v_mul_f32_e32 v23, v23, v26
	v_mul_f32_e32 v27, 0xbfb8aa3b, v21
	v_exp_f32_e32 v27, v27
	v_add_f32_e32 v25, 1.0, v25
	v_rcp_f32_e32 v25, v25
	v_mul_f32_e32 v22, v22, v23
	v_add_f32_e32 v26, 1.0, v27
	v_rcp_f32_e32 v26, v26
	v_mul_f32_e32 v19, v19, v25
	v_mul_f32_e32 v19, v18, v19
	v_add_u32_e32 v23, 0xb0, v153
	v_mul_f32_e32 v18, v21, v26
	v_mul_f32_e32 v21, v20, v18
	v_cvt_pk_bf16_f32 v18, v34, v30
	v_cvt_pk_bf16_f32 v19, v24, v19
	v_cvt_pk_bf16_f32 v20, v31, v35
	v_cvt_pk_bf16_f32 v21, v22, v21
	v_subrev_u32_e32 v22, s22, v23
	v_lshl_add_u32 v22, v22, 2, s59
	ds_read_b32 v22, v22
	v_mov_b32_e32 v26, v6
	v_mov_b32_e32 v27, v14
	v_mov_b32_e32 v28, v2
	v_mov_b32_e32 v29, v10
	s_waitcnt lgkmcnt(0)
	v_cvt_f32_u32_e32 v22, v22
	v_mad_i64_i32 v[24:25], s[0:1], v39, s66, v[116:117]
	v_lshl_add_u64 v[24:25], v[24:25], 0, v[120:121]
	v_fmamk_f32 v22, v22, 0x35000000, v232
	v_rsq_f32_e32 v22, v22
	v_mov_b32_e32 v14, v7
	global_store_dwordx4 v[24:25], v[18:21], off sc1
	v_mov_b32_e32 v10, v3
	v_pk_fma_f32 v[26:27], v[26:27], v[22:23], v[148:149] op_sel_hi:[1,0,1]
	v_pk_fma_f32 v[28:29], v[28:29], v[22:23], v[150:151] op_sel_hi:[1,0,1]
	v_mul_f32_e32 v6, 0xbfb8aa3b, v27
	v_exp_f32_e32 v6, v6
	v_mul_f32_e32 v2, 0xbfb8aa3b, v29
	v_exp_f32_e32 v2, v2
	v_add_f32_e32 v6, 1.0, v6
	v_rcp_f32_e32 v6, v6
	v_add_f32_e32 v2, 1.0, v2
	v_rcp_f32_e32 v2, v2
	v_mul_f32_e32 v6, v27, v6
	v_mul_f32_e32 v18, v26, v6
	v_pk_fma_f32 v[6:7], v[14:15], v[22:23], v[144:145] op_sel_hi:[1,0,1]
	v_mul_f32_e32 v19, v29, v2
	v_mul_f32_e32 v2, 0xbfb8aa3b, v7
	v_exp_f32_e32 v14, v2
	v_pk_fma_f32 v[2:3], v[10:11], v[22:23], v[146:147] op_sel_hi:[1,0,1]
	v_mul_f32_e32 v15, v28, v19
	v_mul_f32_e32 v10, 0xbfb8aa3b, v3
	v_exp_f32_e32 v10, v10
	v_add_f32_e32 v11, 1.0, v14
	v_rcp_f32_e32 v14, v11
	v_mov_b32_e32 v11, v16
	v_add_f32_e32 v10, 1.0, v10
	v_rcp_f32_e32 v19, v10
	v_mov_b32_e32 v10, v8
	v_pk_fma_f32 v[10:11], v[10:11], v[22:23], v[114:115] op_sel_hi:[1,0,1]
	v_mul_f32_e32 v7, v7, v14
	v_mul_f32_e32 v8, 0xbfb8aa3b, v11
	v_exp_f32_e32 v8, v8
	v_mul_f32_e32 v14, v6, v7
	v_mov_b32_e32 v7, v12
	v_mul_f32_e32 v3, v3, v19
	v_add_f32_e32 v6, 1.0, v8
	v_rcp_f32_e32 v8, v6
	v_mov_b32_e32 v6, v4
	v_pk_fma_f32 v[6:7], v[6:7], v[22:23], v[118:119] op_sel_hi:[1,0,1]
	v_mul_f32_e32 v19, v2, v3
	v_mul_f32_e32 v4, 0xbfb8aa3b, v7
	v_exp_f32_e32 v4, v4
	v_mul_f32_e32 v2, v11, v8
	v_mul_f32_e32 v8, v10, v2
	v_mov_b32_e32 v16, v9
	v_add_f32_e32 v2, 1.0, v4
	v_rcp_f32_e32 v10, v2
	v_pk_fma_f32 v[2:3], v[16:17], v[22:23], v[140:141] op_sel_hi:[1,0,1]
	v_mov_b32_e32 v12, v5
	v_mul_f32_e32 v4, 0xbfb8aa3b, v3
	v_exp_f32_e32 v9, v4
	v_pk_fma_f32 v[4:5], v[12:13], v[22:23], v[142:143] op_sel_hi:[1,0,1]
	v_mul_f32_e32 v7, v7, v10
	v_mul_f32_e32 v11, 0xbfb8aa3b, v5
	v_exp_f32_e32 v11, v11
	v_add_f32_e32 v9, 1.0, v9
	v_rcp_f32_e32 v9, v9
	v_add_f32_e32 v10, 1.0, v11
	v_rcp_f32_e32 v10, v10
	v_mul_f32_e32 v3, v3, v9
	v_mul_f32_e32 v9, v2, v3
	v_mul_f32_e32 v11, v6, v7
	v_mul_f32_e32 v2, v5, v10
	v_mul_f32_e32 v5, v4, v2
	v_mad_i64_i32 v[2:3], s[0:1], v23, s66, v[116:117]
	v_lshl_add_u64 v[6:7], v[2:3], 0, v[120:121]
	v_cvt_pk_bf16_f32 v2, v18, v14
	v_cvt_pk_bf16_f32 v3, v8, v9
	v_cvt_pk_bf16_f32 v4, v15, v19
	v_cvt_pk_bf16_f32 v5, v11, v5
	global_store_dwordx4 v[6:7], v[2:5], off sc1
	s_cbranch_vccnz .LBB0_577
	s_andn2_b64 vcc, exec, s[8:9]
	s_cbranch_vccnz .LBB0_576
	s_barrier
	s_branch .LBB0_576

.LBB0_650:
	v_mov_b32_e32 v66, v0
	s_lshl_b32 s0, s22, 8
	s_add_i32 s0, s0, s54
	v_bfe_u32 v240, v66, 4, 2
	v_and_or_b32 v226, v66, 15, s0
	s_or_b32 s0, s6, s67
	v_lshlrev_b32_e32 v66, 3, v240
	v_or_b32_e32 v212, s0, v66
	v_or_b32_e32 v66, s67, v66
	v_ashrrev_i32_e32 v213, 31, v212
	v_ashrrev_i32_e32 v227, 31, v226
	v_lshlrev_b32_e32 v239, 2, v66
	v_lshl_add_u64 v[66:67], v[212:213], 1, s[12:13]
	v_lshlrev_b64 v[68:69], 12, v[226:227]
	v_or_b32_e32 v224, 16, v226
	v_lshl_add_u64 v[68:69], v[66:67], 0, v[68:69]
	v_ashrrev_i32_e32 v225, 31, v224
	global_load_dwordx4 v[228:231], v[68:69], off
	global_load_dwordx4 v[186:189], v[68:69], off offset:256
	v_lshlrev_b64 v[68:69], 12, v[224:225]
	v_or_b32_e32 v222, 32, v226
	v_lshl_add_u64 v[68:69], v[66:67], 0, v[68:69]
	v_ashrrev_i32_e32 v223, 31, v222
	global_load_dwordx4 v[182:185], v[68:69], off
	global_load_dwordx4 v[178:181], v[68:69], off offset:256
	v_lshlrev_b64 v[68:69], 12, v[222:223]
	v_or_b32_e32 v220, 48, v226
	v_lshl_add_u64 v[68:69], v[66:67], 0, v[68:69]
	v_ashrrev_i32_e32 v221, 31, v220
	global_load_dwordx4 v[174:177], v[68:69], off
	global_load_dwordx4 v[170:173], v[68:69], off offset:256
	v_lshlrev_b64 v[68:69], 12, v[220:221]
	v_add_u32_e32 v218, 0x80, v226
	v_lshl_add_u64 v[68:69], v[66:67], 0, v[68:69]
	v_ashrrev_i32_e32 v219, 31, v218
	global_load_dwordx4 v[158:161], v[68:69], off
	global_load_dwordx4 v[154:157], v[68:69], off offset:256
	v_lshlrev_b64 v[68:69], 12, v[218:219]
	v_add_u32_e32 v216, 0x90, v226
	v_lshl_add_u64 v[68:69], v[66:67], 0, v[68:69]
	v_ashrrev_i32_e32 v217, 31, v216
	global_load_dwordx4 v[142:145], v[68:69], off
	global_load_dwordx4 v[130:133], v[68:69], off offset:256
	v_lshlrev_b64 v[68:69], 12, v[216:217]
	v_add_u32_e32 v214, 0xa0, v226
	v_lshl_add_u64 v[68:69], v[66:67], 0, v[68:69]
	v_ashrrev_i32_e32 v215, 31, v214
	global_load_dwordx4 v[118:121], v[68:69], off
	global_load_dwordx4 v[106:109], v[68:69], off offset:256
	v_lshlrev_b64 v[68:69], 12, v[214:215]
	v_add_u32_e32 v210, 0xb0, v226
	v_lshl_add_u64 v[68:69], v[66:67], 0, v[68:69]
	v_ashrrev_i32_e32 v211, 31, v210
	global_load_dwordx4 v[94:97], v[68:69], off
	global_load_dwordx4 v[82:85], v[68:69], off offset:256
	v_lshlrev_b64 v[68:69], 12, v[210:211]
	v_lshl_add_u64 v[66:67], v[66:67], 0, v[68:69]
	global_load_dwordx4 v[70:73], v[66:67], off
	s_nop 0
	global_load_dwordx4 v[66:69], v[66:67], off offset:256
	v_add_u32_e32 v238, 0, v239
	v_add_u32_e32 v238, 0x24400, v238
	v_lshlrev_b64 v[242:243], 11, v[226:227]
	v_lshl_add_u64 v[250:251], v[242:243], 0, v[212:213]
	ds_read_b128 v[242:245], v238
	ds_read_b128 v[246:249], v238 offset:16
	s_andn2_b64 vcc, exec, s[38:39]
	v_add_u32_e32 v239, s59, v239
	s_waitcnt vmcnt(0)
	v_lshlrev_b32_e32 v252, 16, v228
	v_and_b32_e32 v253, 0xffff0000, v228
	v_lshlrev_b32_e32 v228, 16, v229
	v_and_b32_e32 v229, 0xffff0000, v229
	s_waitcnt lgkmcnt(1)
	v_pk_fma_f32 v[168:169], v[168:169], v[244:245], v[228:229]
	v_lshlrev_b32_e32 v228, 16, v230
	v_and_b32_e32 v229, 0xffff0000, v230
	v_lshlrev_b32_e32 v230, 16, v231
	v_and_b32_e32 v231, 0xffff0000, v231
	v_pk_fma_f32 v[166:167], v[166:167], v[242:243], v[252:253]
	s_waitcnt lgkmcnt(0)
	v_pk_fma_f32 v[164:165], v[164:165], v[248:249], v[230:231]
	v_pk_fma_f32 v[162:163], v[162:163], v[246:247], v[228:229]
	v_cndmask_b32_e64 v230, 0, 1, s[38:39]
	v_cvt_pk_bf16_f32 v242, v166, v167
	v_cvt_pk_bf16_f32 v243, v168, v169
	v_cvt_pk_bf16_f32 v244, v162, v163
	v_cvt_pk_bf16_f32 v245, v164, v165
	v_lshl_add_u64 v[162:163], v[250:251], 1, s[36:37]
	v_lshlrev_b32_e32 v228, 16, v242
	v_and_b32_e32 v229, 0xffff0000, v242
	v_lshlrev_b32_e32 v168, 16, v243
	v_and_b32_e32 v169, 0xffff0000, v243
	v_lshlrev_b32_e32 v166, 16, v244
	v_and_b32_e32 v167, 0xffff0000, v244
	v_lshlrev_b32_e32 v164, 16, v245
	v_and_b32_e32 v165, 0xffff0000, v245
	v_cmp_ne_u32_e64 s[6:7], 1, v230
	v_lshl_add_u64 v[230:231], v[250:251], 1, s[46:47]
	global_store_dwordx4 v[162:163], v[242:245], off sc1
	s_cbranch_vccnz .LBB0_652
	ds_read_b128 v[242:245], v239 offset:1024
	ds_read_b128 v[246:249], v239 offset:1040
	s_waitcnt lgkmcnt(1)
	v_pk_mul_f32 v[244:245], v[168:169], v[244:245]
	v_pk_mul_f32 v[242:243], v[228:229], v[242:243]
	s_waitcnt lgkmcnt(0)
	v_pk_mul_f32 v[248:249], v[164:165], v[248:249]
	v_pk_mul_f32 v[246:247], v[166:167], v[246:247]
	v_cvt_pk_bf16_f32 v242, v242, v243
	v_cvt_pk_bf16_f32 v243, v244, v245
	s_nop 0
	v_cvt_pk_bf16_f32 v244, v246, v247
	v_cvt_pk_bf16_f32 v245, v248, v249
	global_store_dwordx4 v[230:231], v[242:245], off sc1
.LBB0_652:
	ds_read_b128 v[242:245], v239 offset:512
	ds_read_b128 v[246:249], v239 offset:528
	v_lshlrev_b32_e32 v250, 16, v186
	v_and_b32_e32 v251, 0xffff0000, v186
	v_lshlrev_b32_e32 v186, 16, v187
	v_and_b32_e32 v187, 0xffff0000, v187
	s_waitcnt lgkmcnt(1)
	v_pk_fma_f32 v[152:153], v[152:153], v[244:245], v[186:187]
	v_lshlrev_b32_e32 v186, 16, v188
	v_and_b32_e32 v187, 0xffff0000, v188
	v_lshlrev_b32_e32 v188, 16, v189
	v_and_b32_e32 v189, 0xffff0000, v189
	v_pk_fma_f32 v[150:151], v[150:151], v[242:243], v[250:251]
	s_waitcnt lgkmcnt(0)
	v_pk_fma_f32 v[148:149], v[148:149], v[248:249], v[188:189]
	v_pk_fma_f32 v[146:147], v[146:147], v[246:247], v[186:187]
	v_cvt_pk_bf16_f32 v186, v150, v151
	v_cvt_pk_bf16_f32 v187, v152, v153
	s_and_b64 vcc, exec, s[6:7]
	v_cvt_pk_bf16_f32 v188, v146, v147
	v_cvt_pk_bf16_f32 v189, v148, v149
	v_lshlrev_b32_e32 v152, 16, v186
	v_and_b32_e32 v153, 0xffff0000, v186
	v_lshlrev_b32_e32 v150, 16, v187
	v_and_b32_e32 v151, 0xffff0000, v187
	v_lshlrev_b32_e32 v148, 16, v188
	v_and_b32_e32 v149, 0xffff0000, v188
	v_lshlrev_b32_e32 v146, 16, v189
	v_and_b32_e32 v147, 0xffff0000, v189
	global_store_dwordx4 v[162:163], v[186:189], off offset:256 sc1
	s_cbranch_vccnz .LBB0_654
	ds_read_b128 v[186:189], v239 offset:1536
	ds_read_b128 v[242:245], v239 offset:1552
	s_waitcnt lgkmcnt(1)
	v_pk_mul_f32 v[162:163], v[150:151], v[188:189]
	v_pk_mul_f32 v[186:187], v[152:153], v[186:187]
	s_waitcnt lgkmcnt(0)
	v_pk_mul_f32 v[188:189], v[148:149], v[242:243]
	v_pk_mul_f32 v[244:245], v[146:147], v[244:245]
	v_cvt_pk_bf16_f32 v186, v186, v187
	v_cvt_pk_bf16_f32 v187, v162, v163
	v_cvt_pk_bf16_f32 v188, v188, v189
	s_nop 0
	v_cvt_pk_bf16_f32 v189, v244, v245
	global_store_dwordx4 v[230:231], v[186:189], off offset:256 sc1

.LBB0_656:
	s_or_b64 exec, exec, s[22:23]
	v_lshlrev_b64 v[146:147], 11, v[224:225]
	v_lshl_add_u64 v[162:163], v[146:147], 0, v[212:213]
	ds_read_b128 v[146:149], v238
	ds_read_b128 v[150:153], v238 offset:16
	v_lshlrev_b32_e32 v164, 16, v182
	v_and_b32_e32 v165, 0xffff0000, v182
	v_lshlrev_b32_e32 v166, 16, v183
	v_and_b32_e32 v167, 0xffff0000, v183
	s_waitcnt lgkmcnt(1)
	v_pk_fma_f32 v[140:141], v[140:141], v[148:149], v[166:167]
	v_pk_fma_f32 v[138:139], v[138:139], v[146:147], v[164:165]
	v_lshlrev_b32_e32 v146, 16, v184
	v_and_b32_e32 v147, 0xffff0000, v184
	v_lshlrev_b32_e32 v148, 16, v185
	v_and_b32_e32 v149, 0xffff0000, v185
	s_waitcnt lgkmcnt(0)
	v_pk_fma_f32 v[136:137], v[136:137], v[152:153], v[148:149]
	v_pk_fma_f32 v[134:135], v[134:135], v[150:151], v[146:147]
	v_cvt_pk_bf16_f32 v150, v138, v139
	v_cvt_pk_bf16_f32 v151, v140, v141
	v_lshl_add_u64 v[148:149], v[162:163], 1, s[36:37]
	v_cvt_pk_bf16_f32 v152, v134, v135
	v_cvt_pk_bf16_f32 v153, v136, v137
	v_lshlrev_b32_e32 v140, 16, v150
	v_and_b32_e32 v141, 0xffff0000, v150
	v_lshlrev_b32_e32 v138, 16, v151
	v_and_b32_e32 v139, 0xffff0000, v151
	v_lshlrev_b32_e32 v136, 16, v152
	v_and_b32_e32 v137, 0xffff0000, v152
	v_lshlrev_b32_e32 v134, 16, v153
	v_and_b32_e32 v135, 0xffff0000, v153
	s_and_b64 vcc, exec, s[6:7]
	v_lshl_add_u64 v[146:147], v[162:163], 1, s[46:47]
	global_store_dwordx4 v[148:149], v[150:153], off sc1
	s_cbranch_vccnz .LBB0_658
	ds_read_b128 v[150:153], v239 offset:1024
	ds_read_b128 v[162:165], v239 offset:1040
	s_waitcnt lgkmcnt(1)
	v_pk_mul_f32 v[152:153], v[138:139], v[152:153]
	v_pk_mul_f32 v[150:151], v[140:141], v[150:151]
	s_waitcnt lgkmcnt(0)
	v_pk_mul_f32 v[164:165], v[134:135], v[164:165]
	v_pk_mul_f32 v[162:163], v[136:137], v[162:163]
	v_cvt_pk_bf16_f32 v150, v150, v151
	v_cvt_pk_bf16_f32 v151, v152, v153
	s_nop 0
	v_cvt_pk_bf16_f32 v152, v162, v163
	v_cvt_pk_bf16_f32 v153, v164, v165
	global_store_dwordx4 v[146:147], v[150:153], off sc1
.LBB0_658:
	ds_read_b128 v[150:153], v239 offset:512
	ds_read_b128 v[162:165], v239 offset:528
	v_lshlrev_b32_e32 v166, 16, v178
	v_and_b32_e32 v167, 0xffff0000, v178
	v_lshlrev_b32_e32 v168, 16, v179
	v_and_b32_e32 v169, 0xffff0000, v179
	s_waitcnt lgkmcnt(1)
	v_pk_fma_f32 v[128:129], v[128:129], v[152:153], v[168:169]
	v_pk_fma_f32 v[126:127], v[126:127], v[150:151], v[166:167]
	v_lshlrev_b32_e32 v150, 16, v180
	v_and_b32_e32 v151, 0xffff0000, v180
	v_lshlrev_b32_e32 v152, 16, v181
	v_and_b32_e32 v153, 0xffff0000, v181
	s_waitcnt lgkmcnt(0)
	v_pk_fma_f32 v[124:125], v[124:125], v[164:165], v[152:153]
	v_pk_fma_f32 v[122:123], v[122:123], v[162:163], v[150:151]
	v_cvt_pk_bf16_f32 v150, v126, v127
	v_cvt_pk_bf16_f32 v151, v128, v129
	s_and_b64 vcc, exec, s[6:7]
	v_cvt_pk_bf16_f32 v152, v122, v123
	v_cvt_pk_bf16_f32 v153, v124, v125
	v_lshlrev_b32_e32 v128, 16, v150
	v_and_b32_e32 v129, 0xffff0000, v150
	v_lshlrev_b32_e32 v126, 16, v151
	v_and_b32_e32 v127, 0xffff0000, v151
	v_lshlrev_b32_e32 v124, 16, v152
	v_and_b32_e32 v125, 0xffff0000, v152
	v_lshlrev_b32_e32 v122, 16, v153
	v_and_b32_e32 v123, 0xffff0000, v153
	global_store_dwordx4 v[148:149], v[150:153], off offset:256 sc1
	s_cbranch_vccnz .LBB0_660
	ds_read_b128 v[148:151], v239 offset:1536
	ds_read_b128 v[162:165], v239 offset:1552
	s_waitcnt lgkmcnt(1)
	v_pk_mul_f32 v[150:151], v[126:127], v[150:151]
	v_pk_mul_f32 v[148:149], v[128:129], v[148:149]
	s_waitcnt lgkmcnt(0)
	v_pk_mul_f32 v[152:153], v[122:123], v[164:165]
	v_pk_mul_f32 v[162:163], v[124:125], v[162:163]
	v_cvt_pk_bf16_f32 v148, v148, v149
	v_cvt_pk_bf16_f32 v149, v150, v151
	s_nop 0
	v_cvt_pk_bf16_f32 v150, v162, v163
	v_cvt_pk_bf16_f32 v151, v152, v153
	global_store_dwordx4 v[146:147], v[148:151], off offset:256 sc1

.LBB0_662:
	s_or_b64 exec, exec, s[22:23]
	v_lshlrev_b64 v[122:123], 11, v[222:223]
	v_lshl_add_u64 v[134:135], v[122:123], 0, v[212:213]
	ds_read_b128 v[122:125], v238
	ds_read_b128 v[126:129], v238 offset:16
	v_lshlrev_b32_e32 v136, 16, v174
	v_and_b32_e32 v137, 0xffff0000, v174
	v_lshlrev_b32_e32 v138, 16, v175
	v_and_b32_e32 v139, 0xffff0000, v175
	s_waitcnt lgkmcnt(1)
	v_pk_fma_f32 v[116:117], v[116:117], v[124:125], v[138:139]
	v_pk_fma_f32 v[114:115], v[114:115], v[122:123], v[136:137]
	v_lshlrev_b32_e32 v122, 16, v176
	v_and_b32_e32 v123, 0xffff0000, v176
	v_lshlrev_b32_e32 v124, 16, v177
	v_and_b32_e32 v125, 0xffff0000, v177
	s_waitcnt lgkmcnt(0)
	v_pk_fma_f32 v[112:113], v[112:113], v[128:129], v[124:125]
	v_pk_fma_f32 v[110:111], v[110:111], v[126:127], v[122:123]
	v_cvt_pk_bf16_f32 v126, v114, v115
	v_cvt_pk_bf16_f32 v127, v116, v117
	v_lshl_add_u64 v[124:125], v[134:135], 1, s[36:37]
	v_cvt_pk_bf16_f32 v128, v110, v111
	v_cvt_pk_bf16_f32 v129, v112, v113
	v_lshlrev_b32_e32 v116, 16, v126
	v_and_b32_e32 v117, 0xffff0000, v126
	v_lshlrev_b32_e32 v114, 16, v127
	v_and_b32_e32 v115, 0xffff0000, v127
	v_lshlrev_b32_e32 v112, 16, v128
	v_and_b32_e32 v113, 0xffff0000, v128
	v_lshlrev_b32_e32 v110, 16, v129
	v_and_b32_e32 v111, 0xffff0000, v129
	s_and_b64 vcc, exec, s[6:7]
	v_lshl_add_u64 v[122:123], v[134:135], 1, s[46:47]
	global_store_dwordx4 v[124:125], v[126:129], off sc1
	s_cbranch_vccnz .LBB0_664
	ds_read_b128 v[126:129], v239 offset:1024
	ds_read_b128 v[134:137], v239 offset:1040
	s_waitcnt lgkmcnt(1)
	v_pk_mul_f32 v[128:129], v[114:115], v[128:129]
	v_pk_mul_f32 v[126:127], v[116:117], v[126:127]
	s_waitcnt lgkmcnt(0)
	v_pk_mul_f32 v[136:137], v[110:111], v[136:137]
	v_pk_mul_f32 v[134:135], v[112:113], v[134:135]
	v_cvt_pk_bf16_f32 v126, v126, v127
	v_cvt_pk_bf16_f32 v127, v128, v129
	s_nop 0
	v_cvt_pk_bf16_f32 v128, v134, v135
	v_cvt_pk_bf16_f32 v129, v136, v137
	global_store_dwordx4 v[122:123], v[126:129], off sc1
.LBB0_664:
	ds_read_b128 v[126:129], v239 offset:512
	ds_read_b128 v[134:137], v239 offset:528
	v_lshlrev_b32_e32 v138, 16, v170
	v_and_b32_e32 v139, 0xffff0000, v170
	v_lshlrev_b32_e32 v140, 16, v171
	v_and_b32_e32 v141, 0xffff0000, v171
	s_waitcnt lgkmcnt(1)
	v_pk_fma_f32 v[104:105], v[104:105], v[128:129], v[140:141]
	v_pk_fma_f32 v[102:103], v[102:103], v[126:127], v[138:139]
	v_lshlrev_b32_e32 v126, 16, v172
	v_and_b32_e32 v127, 0xffff0000, v172
	v_lshlrev_b32_e32 v128, 16, v173
	v_and_b32_e32 v129, 0xffff0000, v173
	s_waitcnt lgkmcnt(0)
	v_pk_fma_f32 v[100:101], v[100:101], v[136:137], v[128:129]
	v_pk_fma_f32 v[98:99], v[98:99], v[134:135], v[126:127]
	v_cvt_pk_bf16_f32 v126, v102, v103
	v_cvt_pk_bf16_f32 v127, v104, v105
	s_and_b64 vcc, exec, s[6:7]
	v_cvt_pk_bf16_f32 v128, v98, v99
	v_cvt_pk_bf16_f32 v129, v100, v101
	v_lshlrev_b32_e32 v104, 16, v126
	v_and_b32_e32 v105, 0xffff0000, v126
	v_lshlrev_b32_e32 v102, 16, v127
	v_and_b32_e32 v103, 0xffff0000, v127
	v_lshlrev_b32_e32 v100, 16, v128
	v_and_b32_e32 v101, 0xffff0000, v128
	v_lshlrev_b32_e32 v98, 16, v129
	v_and_b32_e32 v99, 0xffff0000, v129
	global_store_dwordx4 v[124:125], v[126:129], off offset:256 sc1
	s_cbranch_vccnz .LBB0_666
	ds_read_b128 v[124:127], v239 offset:1536
	ds_read_b128 v[134:137], v239 offset:1552
	s_waitcnt lgkmcnt(1)
	v_pk_mul_f32 v[126:127], v[102:103], v[126:127]
	v_pk_mul_f32 v[124:125], v[104:105], v[124:125]
	s_waitcnt lgkmcnt(0)
	v_pk_mul_f32 v[128:129], v[98:99], v[136:137]
	v_pk_mul_f32 v[134:135], v[100:101], v[134:135]
	v_cvt_pk_bf16_f32 v124, v124, v125
	v_cvt_pk_bf16_f32 v125, v126, v127
	s_nop 0
	v_cvt_pk_bf16_f32 v126, v134, v135
	v_cvt_pk_bf16_f32 v127, v128, v129
	global_store_dwordx4 v[122:123], v[124:127], off offset:256 sc1

.LBB0_668:
	s_or_b64 exec, exec, s[22:23]
	v_lshlrev_b64 v[98:99], 11, v[220:221]
	v_lshl_add_u64 v[110:111], v[98:99], 0, v[212:213]
	ds_read_b128 v[98:101], v238
	ds_read_b128 v[102:105], v238 offset:16
	v_lshlrev_b32_e32 v112, 16, v158
	v_and_b32_e32 v113, 0xffff0000, v158
	v_lshlrev_b32_e32 v114, 16, v159
	v_and_b32_e32 v115, 0xffff0000, v159
	s_waitcnt lgkmcnt(1)
	v_pk_fma_f32 v[92:93], v[92:93], v[100:101], v[114:115]
	v_pk_fma_f32 v[90:91], v[90:91], v[98:99], v[112:113]
	v_lshlrev_b32_e32 v98, 16, v160
	v_and_b32_e32 v99, 0xffff0000, v160
	v_lshlrev_b32_e32 v100, 16, v161
	v_and_b32_e32 v101, 0xffff0000, v161
	s_waitcnt lgkmcnt(0)
	v_pk_fma_f32 v[88:89], v[88:89], v[104:105], v[100:101]
	v_pk_fma_f32 v[86:87], v[86:87], v[102:103], v[98:99]
	v_cvt_pk_bf16_f32 v102, v90, v91
	v_cvt_pk_bf16_f32 v103, v92, v93
	v_lshl_add_u64 v[100:101], v[110:111], 1, s[36:37]
	v_cvt_pk_bf16_f32 v104, v86, v87
	v_cvt_pk_bf16_f32 v105, v88, v89
	v_lshlrev_b32_e32 v92, 16, v102
	v_and_b32_e32 v93, 0xffff0000, v102
	v_lshlrev_b32_e32 v90, 16, v103
	v_and_b32_e32 v91, 0xffff0000, v103
	v_lshlrev_b32_e32 v88, 16, v104
	v_and_b32_e32 v89, 0xffff0000, v104
	v_lshlrev_b32_e32 v86, 16, v105
	v_and_b32_e32 v87, 0xffff0000, v105
	s_and_b64 vcc, exec, s[6:7]
	v_lshl_add_u64 v[98:99], v[110:111], 1, s[46:47]
	global_store_dwordx4 v[100:101], v[102:105], off sc1
	s_cbranch_vccnz .LBB0_670
	ds_read_b128 v[102:105], v239 offset:1024
	ds_read_b128 v[110:113], v239 offset:1040
	s_waitcnt lgkmcnt(1)
	v_pk_mul_f32 v[104:105], v[90:91], v[104:105]
	v_pk_mul_f32 v[102:103], v[92:93], v[102:103]
	s_waitcnt lgkmcnt(0)
	v_pk_mul_f32 v[112:113], v[86:87], v[112:113]
	v_pk_mul_f32 v[110:111], v[88:89], v[110:111]
	v_cvt_pk_bf16_f32 v102, v102, v103
	v_cvt_pk_bf16_f32 v103, v104, v105
	s_nop 0
	v_cvt_pk_bf16_f32 v104, v110, v111
	v_cvt_pk_bf16_f32 v105, v112, v113
	global_store_dwordx4 v[98:99], v[102:105], off sc1
.LBB0_670:
	ds_read_b128 v[102:105], v239 offset:512
	ds_read_b128 v[110:113], v239 offset:528
	v_lshlrev_b32_e32 v114, 16, v154
	v_and_b32_e32 v115, 0xffff0000, v154
	v_lshlrev_b32_e32 v116, 16, v155
	v_and_b32_e32 v117, 0xffff0000, v155
	s_waitcnt lgkmcnt(1)
	v_pk_fma_f32 v[80:81], v[80:81], v[104:105], v[116:117]
	v_pk_fma_f32 v[78:79], v[78:79], v[102:103], v[114:115]
	v_lshlrev_b32_e32 v102, 16, v156
	v_and_b32_e32 v103, 0xffff0000, v156
	v_lshlrev_b32_e32 v104, 16, v157
	v_and_b32_e32 v105, 0xffff0000, v157
	s_waitcnt lgkmcnt(0)
	v_pk_fma_f32 v[76:77], v[76:77], v[112:113], v[104:105]
	v_pk_fma_f32 v[74:75], v[74:75], v[110:111], v[102:103]
	v_cvt_pk_bf16_f32 v102, v78, v79
	v_cvt_pk_bf16_f32 v103, v80, v81
	s_and_b64 vcc, exec, s[6:7]
	v_cvt_pk_bf16_f32 v104, v74, v75
	v_cvt_pk_bf16_f32 v105, v76, v77
	v_lshlrev_b32_e32 v80, 16, v102
	v_and_b32_e32 v81, 0xffff0000, v102
	v_lshlrev_b32_e32 v78, 16, v103
	v_and_b32_e32 v79, 0xffff0000, v103
	v_lshlrev_b32_e32 v76, 16, v104
	v_and_b32_e32 v77, 0xffff0000, v104
	v_lshlrev_b32_e32 v74, 16, v105
	v_and_b32_e32 v75, 0xffff0000, v105
	global_store_dwordx4 v[100:101], v[102:105], off offset:256 sc1
	s_cbranch_vccnz .LBB0_672
	ds_read_b128 v[100:103], v239 offset:1536
	ds_read_b128 v[110:113], v239 offset:1552
	s_waitcnt lgkmcnt(1)
	v_pk_mul_f32 v[102:103], v[78:79], v[102:103]
	v_pk_mul_f32 v[100:101], v[80:81], v[100:101]
	s_waitcnt lgkmcnt(0)
	v_pk_mul_f32 v[104:105], v[74:75], v[112:113]
	v_pk_mul_f32 v[110:111], v[76:77], v[110:111]
	v_cvt_pk_bf16_f32 v100, v100, v101
	v_cvt_pk_bf16_f32 v101, v102, v103
	s_nop 0
	v_cvt_pk_bf16_f32 v102, v110, v111
	v_cvt_pk_bf16_f32 v103, v104, v105
	global_store_dwordx4 v[98:99], v[100:103], off offset:256 sc1

.LBB0_674:
	s_or_b64 exec, exec, s[22:23]
	v_lshlrev_b64 v[74:75], 11, v[218:219]
	v_lshl_add_u64 v[86:87], v[74:75], 0, v[212:213]
	ds_read_b128 v[74:77], v238
	ds_read_b128 v[78:81], v238 offset:16
	v_lshlrev_b32_e32 v88, 16, v142
	v_and_b32_e32 v89, 0xffff0000, v142
	v_lshlrev_b32_e32 v90, 16, v143
	v_and_b32_e32 v91, 0xffff0000, v143
	s_waitcnt lgkmcnt(1)
	v_pk_fma_f32 v[64:65], v[64:65], v[76:77], v[90:91]
	v_pk_fma_f32 v[62:63], v[62:63], v[74:75], v[88:89]
	v_lshlrev_b32_e32 v74, 16, v144
	v_and_b32_e32 v75, 0xffff0000, v144
	v_lshlrev_b32_e32 v76, 16, v145
	v_and_b32_e32 v77, 0xffff0000, v145
	s_waitcnt lgkmcnt(0)
	v_pk_fma_f32 v[60:61], v[60:61], v[80:81], v[76:77]
	v_pk_fma_f32 v[58:59], v[58:59], v[78:79], v[74:75]
	v_cvt_pk_bf16_f32 v78, v62, v63
	v_cvt_pk_bf16_f32 v79, v64, v65
	v_lshl_add_u64 v[76:77], v[86:87], 1, s[36:37]
	v_cvt_pk_bf16_f32 v80, v58, v59
	v_cvt_pk_bf16_f32 v81, v60, v61
	v_lshlrev_b32_e32 v64, 16, v78
	v_and_b32_e32 v65, 0xffff0000, v78
	v_lshlrev_b32_e32 v62, 16, v79
	v_and_b32_e32 v63, 0xffff0000, v79
	v_lshlrev_b32_e32 v60, 16, v80
	v_and_b32_e32 v61, 0xffff0000, v80
	v_lshlrev_b32_e32 v58, 16, v81
	v_and_b32_e32 v59, 0xffff0000, v81
	s_and_b64 vcc, exec, s[6:7]
	v_lshl_add_u64 v[74:75], v[86:87], 1, s[46:47]
	global_store_dwordx4 v[76:77], v[78:81], off sc1
	s_cbranch_vccnz .LBB0_676
	ds_read_b128 v[78:81], v239 offset:1024
	ds_read_b128 v[86:89], v239 offset:1040
	s_waitcnt lgkmcnt(1)
	v_pk_mul_f32 v[80:81], v[62:63], v[80:81]
	v_pk_mul_f32 v[78:79], v[64:65], v[78:79]
	s_waitcnt lgkmcnt(0)
	v_pk_mul_f32 v[88:89], v[58:59], v[88:89]
	v_pk_mul_f32 v[86:87], v[60:61], v[86:87]
	v_cvt_pk_bf16_f32 v78, v78, v79
	v_cvt_pk_bf16_f32 v79, v80, v81
	s_nop 0
	v_cvt_pk_bf16_f32 v80, v86, v87
	v_cvt_pk_bf16_f32 v81, v88, v89
	global_store_dwordx4 v[74:75], v[78:81], off sc1
.LBB0_676:
	ds_read_b128 v[78:81], v239 offset:512
	ds_read_b128 v[86:89], v239 offset:528
	v_lshlrev_b32_e32 v90, 16, v130
	v_and_b32_e32 v91, 0xffff0000, v130
	v_lshlrev_b32_e32 v92, 16, v131
	v_and_b32_e32 v93, 0xffff0000, v131
	s_waitcnt lgkmcnt(1)
	v_pk_fma_f32 v[56:57], v[56:57], v[80:81], v[92:93]
	v_pk_fma_f32 v[54:55], v[54:55], v[78:79], v[90:91]
	v_lshlrev_b32_e32 v78, 16, v132
	v_and_b32_e32 v79, 0xffff0000, v132
	v_lshlrev_b32_e32 v80, 16, v133
	v_and_b32_e32 v81, 0xffff0000, v133
	s_waitcnt lgkmcnt(0)
	v_pk_fma_f32 v[52:53], v[52:53], v[88:89], v[80:81]
	v_pk_fma_f32 v[50:51], v[50:51], v[86:87], v[78:79]
	v_cvt_pk_bf16_f32 v78, v54, v55
	v_cvt_pk_bf16_f32 v79, v56, v57
	s_and_b64 vcc, exec, s[6:7]
	v_cvt_pk_bf16_f32 v80, v50, v51
	v_cvt_pk_bf16_f32 v81, v52, v53
	v_lshlrev_b32_e32 v56, 16, v78
	v_and_b32_e32 v57, 0xffff0000, v78
	v_lshlrev_b32_e32 v54, 16, v79
	v_and_b32_e32 v55, 0xffff0000, v79
	v_lshlrev_b32_e32 v52, 16, v80
	v_and_b32_e32 v53, 0xffff0000, v80
	v_lshlrev_b32_e32 v50, 16, v81
	v_and_b32_e32 v51, 0xffff0000, v81
	global_store_dwordx4 v[76:77], v[78:81], off offset:256 sc1
	s_cbranch_vccnz .LBB0_678
	ds_read_b128 v[76:79], v239 offset:1536
	ds_read_b128 v[86:89], v239 offset:1552
	s_waitcnt lgkmcnt(1)
	v_pk_mul_f32 v[78:79], v[54:55], v[78:79]
	v_pk_mul_f32 v[76:77], v[56:57], v[76:77]
	s_waitcnt lgkmcnt(0)
	v_pk_mul_f32 v[80:81], v[50:51], v[88:89]
	v_pk_mul_f32 v[86:87], v[52:53], v[86:87]
	v_cvt_pk_bf16_f32 v76, v76, v77
	v_cvt_pk_bf16_f32 v77, v78, v79
	s_nop 0
	v_cvt_pk_bf16_f32 v78, v86, v87
	v_cvt_pk_bf16_f32 v79, v80, v81
	global_store_dwordx4 v[74:75], v[76:79], off offset:256 sc1

.LBB0_680:
	s_or_b64 exec, exec, s[22:23]
	v_lshlrev_b64 v[50:51], 11, v[216:217]
	v_lshl_add_u64 v[58:59], v[50:51], 0, v[212:213]
	ds_read_b128 v[50:53], v238
	ds_read_b128 v[54:57], v238 offset:16
	v_lshlrev_b32_e32 v60, 16, v118
	v_and_b32_e32 v61, 0xffff0000, v118
	v_lshlrev_b32_e32 v62, 16, v119
	v_and_b32_e32 v63, 0xffff0000, v119
	s_waitcnt lgkmcnt(1)
	v_pk_fma_f32 v[48:49], v[48:49], v[52:53], v[62:63]
	v_pk_fma_f32 v[46:47], v[46:47], v[50:51], v[60:61]
	v_lshlrev_b32_e32 v50, 16, v120
	v_and_b32_e32 v51, 0xffff0000, v120
	v_lshlrev_b32_e32 v52, 16, v121
	v_and_b32_e32 v53, 0xffff0000, v121
	s_waitcnt lgkmcnt(0)
	v_pk_fma_f32 v[44:45], v[44:45], v[56:57], v[52:53]
	v_pk_fma_f32 v[42:43], v[42:43], v[54:55], v[50:51]
	v_cvt_pk_bf16_f32 v54, v46, v47
	v_cvt_pk_bf16_f32 v55, v48, v49
	v_lshl_add_u64 v[52:53], v[58:59], 1, s[36:37]
	v_cvt_pk_bf16_f32 v56, v42, v43
	v_cvt_pk_bf16_f32 v57, v44, v45
	v_lshlrev_b32_e32 v48, 16, v54
	v_and_b32_e32 v49, 0xffff0000, v54
	v_lshlrev_b32_e32 v46, 16, v55
	v_and_b32_e32 v47, 0xffff0000, v55
	v_lshlrev_b32_e32 v44, 16, v56
	v_and_b32_e32 v45, 0xffff0000, v56
	v_lshlrev_b32_e32 v42, 16, v57
	v_and_b32_e32 v43, 0xffff0000, v57
	s_and_b64 vcc, exec, s[6:7]
	v_lshl_add_u64 v[50:51], v[58:59], 1, s[46:47]
	global_store_dwordx4 v[52:53], v[54:57], off sc1
	s_cbranch_vccnz .LBB0_682
	ds_read_b128 v[54:57], v239 offset:1024
	ds_read_b128 v[58:61], v239 offset:1040
	s_waitcnt lgkmcnt(1)
	v_pk_mul_f32 v[56:57], v[46:47], v[56:57]
	v_pk_mul_f32 v[54:55], v[48:49], v[54:55]
	s_waitcnt lgkmcnt(0)
	v_pk_mul_f32 v[60:61], v[42:43], v[60:61]
	v_pk_mul_f32 v[58:59], v[44:45], v[58:59]
	v_cvt_pk_bf16_f32 v54, v54, v55
	v_cvt_pk_bf16_f32 v55, v56, v57
	s_nop 0
	v_cvt_pk_bf16_f32 v56, v58, v59
	v_cvt_pk_bf16_f32 v57, v60, v61
	global_store_dwordx4 v[50:51], v[54:57], off sc1
.LBB0_682:
	ds_read_b128 v[54:57], v239 offset:512
	ds_read_b128 v[58:61], v239 offset:528
	v_lshlrev_b32_e32 v62, 16, v106
	v_and_b32_e32 v63, 0xffff0000, v106
	v_lshlrev_b32_e32 v64, 16, v107
	v_and_b32_e32 v65, 0xffff0000, v107
	s_waitcnt lgkmcnt(1)
	v_pk_fma_f32 v[40:41], v[40:41], v[56:57], v[64:65]
	v_pk_fma_f32 v[38:39], v[38:39], v[54:55], v[62:63]
	v_lshlrev_b32_e32 v54, 16, v108
	v_and_b32_e32 v55, 0xffff0000, v108
	v_lshlrev_b32_e32 v56, 16, v109
	v_and_b32_e32 v57, 0xffff0000, v109
	s_waitcnt lgkmcnt(0)
	v_pk_fma_f32 v[36:37], v[36:37], v[60:61], v[56:57]
	v_pk_fma_f32 v[34:35], v[34:35], v[58:59], v[54:55]
	v_cvt_pk_bf16_f32 v54, v38, v39
	v_cvt_pk_bf16_f32 v55, v40, v41
	s_and_b64 vcc, exec, s[6:7]
	v_cvt_pk_bf16_f32 v56, v34, v35
	v_cvt_pk_bf16_f32 v57, v36, v37
	v_lshlrev_b32_e32 v40, 16, v54
	v_and_b32_e32 v41, 0xffff0000, v54
	v_lshlrev_b32_e32 v38, 16, v55
	v_and_b32_e32 v39, 0xffff0000, v55
	v_lshlrev_b32_e32 v36, 16, v56
	v_and_b32_e32 v37, 0xffff0000, v56
	v_lshlrev_b32_e32 v34, 16, v57
	v_and_b32_e32 v35, 0xffff0000, v57
	global_store_dwordx4 v[52:53], v[54:57], off offset:256 sc1
	s_cbranch_vccnz .LBB0_684
	ds_read_b128 v[52:55], v239 offset:1536
	ds_read_b128 v[56:59], v239 offset:1552
	s_waitcnt lgkmcnt(1)
	v_pk_mul_f32 v[54:55], v[38:39], v[54:55]
	v_pk_mul_f32 v[52:53], v[40:41], v[52:53]
	s_waitcnt lgkmcnt(0)
	v_pk_mul_f32 v[58:59], v[34:35], v[58:59]
	v_pk_mul_f32 v[56:57], v[36:37], v[56:57]
	v_cvt_pk_bf16_f32 v52, v52, v53
	v_cvt_pk_bf16_f32 v53, v54, v55
	s_nop 0
	v_cvt_pk_bf16_f32 v54, v56, v57
	v_cvt_pk_bf16_f32 v55, v58, v59
	global_store_dwordx4 v[50:51], v[52:55], off offset:256 sc1

.LBB0_686:
	s_or_b64 exec, exec, s[22:23]
	v_lshlrev_b64 v[34:35], 11, v[214:215]
	v_lshl_add_u64 v[42:43], v[34:35], 0, v[212:213]
	ds_read_b128 v[34:37], v238
	ds_read_b128 v[38:41], v238 offset:16
	v_lshlrev_b32_e32 v44, 16, v94
	v_and_b32_e32 v45, 0xffff0000, v94
	v_lshlrev_b32_e32 v46, 16, v95
	v_and_b32_e32 v47, 0xffff0000, v95
	s_waitcnt lgkmcnt(1)
	v_pk_fma_f32 v[32:33], v[32:33], v[36:37], v[46:47]
	v_pk_fma_f32 v[30:31], v[30:31], v[34:35], v[44:45]
	v_lshlrev_b32_e32 v34, 16, v96
	v_and_b32_e32 v35, 0xffff0000, v96
	v_lshlrev_b32_e32 v36, 16, v97
	v_and_b32_e32 v37, 0xffff0000, v97
	s_waitcnt lgkmcnt(0)
	v_pk_fma_f32 v[28:29], v[28:29], v[40:41], v[36:37]
	v_pk_fma_f32 v[26:27], v[26:27], v[38:39], v[34:35]
	v_cvt_pk_bf16_f32 v38, v30, v31
	v_cvt_pk_bf16_f32 v39, v32, v33
	v_lshl_add_u64 v[36:37], v[42:43], 1, s[36:37]
	v_cvt_pk_bf16_f32 v40, v26, v27
	v_cvt_pk_bf16_f32 v41, v28, v29
	v_lshlrev_b32_e32 v32, 16, v38
	v_and_b32_e32 v33, 0xffff0000, v38
	v_lshlrev_b32_e32 v30, 16, v39
	v_and_b32_e32 v31, 0xffff0000, v39
	v_lshlrev_b32_e32 v28, 16, v40
	v_and_b32_e32 v29, 0xffff0000, v40
	v_lshlrev_b32_e32 v26, 16, v41
	v_and_b32_e32 v27, 0xffff0000, v41
	s_and_b64 vcc, exec, s[6:7]
	v_lshl_add_u64 v[34:35], v[42:43], 1, s[46:47]
	global_store_dwordx4 v[36:37], v[38:41], off sc1
	s_cbranch_vccnz .LBB0_688
	ds_read_b128 v[38:41], v239 offset:1024
	ds_read_b128 v[42:45], v239 offset:1040
	s_waitcnt lgkmcnt(1)
	v_pk_mul_f32 v[40:41], v[30:31], v[40:41]
	v_pk_mul_f32 v[38:39], v[32:33], v[38:39]
	s_waitcnt lgkmcnt(0)
	v_pk_mul_f32 v[44:45], v[26:27], v[44:45]
	v_pk_mul_f32 v[42:43], v[28:29], v[42:43]
	v_cvt_pk_bf16_f32 v38, v38, v39
	v_cvt_pk_bf16_f32 v39, v40, v41
	s_nop 0
	v_cvt_pk_bf16_f32 v40, v42, v43
	v_cvt_pk_bf16_f32 v41, v44, v45
	global_store_dwordx4 v[34:35], v[38:41], off sc1
.LBB0_688:
	ds_read_b128 v[38:41], v239 offset:512
	ds_read_b128 v[42:45], v239 offset:528
	v_lshlrev_b32_e32 v46, 16, v82
	v_and_b32_e32 v47, 0xffff0000, v82
	v_lshlrev_b32_e32 v48, 16, v83
	v_and_b32_e32 v49, 0xffff0000, v83
	s_waitcnt lgkmcnt(1)
	v_pk_fma_f32 v[24:25], v[24:25], v[40:41], v[48:49]
	v_pk_fma_f32 v[22:23], v[22:23], v[38:39], v[46:47]
	v_lshlrev_b32_e32 v38, 16, v84
	v_and_b32_e32 v39, 0xffff0000, v84
	v_lshlrev_b32_e32 v40, 16, v85
	v_and_b32_e32 v41, 0xffff0000, v85
	s_waitcnt lgkmcnt(0)
	v_pk_fma_f32 v[20:21], v[20:21], v[44:45], v[40:41]
	v_pk_fma_f32 v[18:19], v[18:19], v[42:43], v[38:39]
	v_cvt_pk_bf16_f32 v38, v22, v23
	v_cvt_pk_bf16_f32 v39, v24, v25
	s_and_b64 vcc, exec, s[6:7]
	v_cvt_pk_bf16_f32 v40, v18, v19
	v_cvt_pk_bf16_f32 v41, v20, v21
	v_lshlrev_b32_e32 v24, 16, v38
	v_and_b32_e32 v25, 0xffff0000, v38
	v_lshlrev_b32_e32 v22, 16, v39
	v_and_b32_e32 v23, 0xffff0000, v39
	v_lshlrev_b32_e32 v20, 16, v40
	v_and_b32_e32 v21, 0xffff0000, v40
	v_lshlrev_b32_e32 v18, 16, v41
	v_and_b32_e32 v19, 0xffff0000, v41
	global_store_dwordx4 v[36:37], v[38:41], off offset:256 sc1
	s_cbranch_vccnz .LBB0_690
	ds_read_b128 v[36:39], v239 offset:1536
	ds_read_b128 v[40:43], v239 offset:1552
	s_waitcnt lgkmcnt(1)
	v_pk_mul_f32 v[38:39], v[22:23], v[38:39]
	v_pk_mul_f32 v[36:37], v[24:25], v[36:37]
	s_waitcnt lgkmcnt(0)
	v_pk_mul_f32 v[42:43], v[18:19], v[42:43]
	v_pk_mul_f32 v[40:41], v[20:21], v[40:41]
	v_cvt_pk_bf16_f32 v36, v36, v37
	v_cvt_pk_bf16_f32 v37, v38, v39
	s_nop 0
	v_cvt_pk_bf16_f32 v38, v40, v41
	v_cvt_pk_bf16_f32 v39, v42, v43
	global_store_dwordx4 v[34:35], v[36:39], off offset:256 sc1

.LBB0_692:
	s_or_b64 exec, exec, s[22:23]
	v_lshlrev_b64 v[18:19], 11, v[210:211]
	v_lshl_add_u64 v[26:27], v[18:19], 0, v[212:213]
	ds_read_b128 v[18:21], v238
	ds_read_b128 v[22:25], v238 offset:16
	v_lshlrev_b32_e32 v28, 16, v70
	v_and_b32_e32 v29, 0xffff0000, v70
	v_lshlrev_b32_e32 v30, 16, v71
	v_and_b32_e32 v31, 0xffff0000, v71
	s_waitcnt lgkmcnt(1)
	v_pk_fma_f32 v[16:17], v[16:17], v[20:21], v[30:31]
	v_pk_fma_f32 v[14:15], v[14:15], v[18:19], v[28:29]
	v_lshlrev_b32_e32 v18, 16, v72
	v_and_b32_e32 v19, 0xffff0000, v72
	v_lshlrev_b32_e32 v20, 16, v73
	v_and_b32_e32 v21, 0xffff0000, v73
	s_waitcnt lgkmcnt(0)
	v_pk_fma_f32 v[12:13], v[12:13], v[24:25], v[20:21]
	v_pk_fma_f32 v[10:11], v[10:11], v[22:23], v[18:19]
	v_cvt_pk_bf16_f32 v22, v14, v15
	v_cvt_pk_bf16_f32 v23, v16, v17
	v_lshl_add_u64 v[20:21], v[26:27], 1, s[36:37]
	v_cvt_pk_bf16_f32 v24, v10, v11
	v_cvt_pk_bf16_f32 v25, v12, v13
	v_lshlrev_b32_e32 v16, 16, v22
	v_and_b32_e32 v17, 0xffff0000, v22
	v_lshlrev_b32_e32 v14, 16, v23
	v_and_b32_e32 v15, 0xffff0000, v23
	v_lshlrev_b32_e32 v12, 16, v24
	v_and_b32_e32 v13, 0xffff0000, v24
	v_lshlrev_b32_e32 v10, 16, v25
	v_and_b32_e32 v11, 0xffff0000, v25
	s_and_b64 vcc, exec, s[6:7]
	v_lshl_add_u64 v[18:19], v[26:27], 1, s[46:47]
	global_store_dwordx4 v[20:21], v[22:25], off sc1
	s_cbranch_vccnz .LBB0_694
	ds_read_b128 v[22:25], v239 offset:1024
	ds_read_b128 v[26:29], v239 offset:1040
	s_waitcnt lgkmcnt(1)
	v_pk_mul_f32 v[24:25], v[14:15], v[24:25]
	v_pk_mul_f32 v[22:23], v[16:17], v[22:23]
	s_waitcnt lgkmcnt(0)
	v_pk_mul_f32 v[28:29], v[10:11], v[28:29]
	v_pk_mul_f32 v[26:27], v[12:13], v[26:27]
	v_cvt_pk_bf16_f32 v22, v22, v23
	v_cvt_pk_bf16_f32 v23, v24, v25
	s_nop 0
	v_cvt_pk_bf16_f32 v24, v26, v27
	v_cvt_pk_bf16_f32 v25, v28, v29
	global_store_dwordx4 v[18:19], v[22:25], off sc1
.LBB0_694:
	ds_read_b128 v[22:25], v239 offset:512
	ds_read_b128 v[26:29], v239 offset:528
	v_lshlrev_b32_e32 v30, 16, v66
	v_and_b32_e32 v31, 0xffff0000, v66
	v_lshlrev_b32_e32 v32, 16, v67
	v_and_b32_e32 v33, 0xffff0000, v67
	s_waitcnt lgkmcnt(1)
	v_pk_fma_f32 v[8:9], v[8:9], v[24:25], v[32:33]
	v_pk_fma_f32 v[6:7], v[6:7], v[22:23], v[30:31]
	v_lshlrev_b32_e32 v22, 16, v68
	v_and_b32_e32 v23, 0xffff0000, v68
	v_lshlrev_b32_e32 v24, 16, v69
	v_and_b32_e32 v25, 0xffff0000, v69
	s_waitcnt lgkmcnt(0)
	v_pk_fma_f32 v[4:5], v[4:5], v[28:29], v[24:25]
	v_pk_fma_f32 v[2:3], v[2:3], v[26:27], v[22:23]
	v_cvt_pk_bf16_f32 v22, v6, v7
	v_cvt_pk_bf16_f32 v23, v8, v9
	s_and_b64 vcc, exec, s[6:7]
	v_cvt_pk_bf16_f32 v24, v2, v3
	v_cvt_pk_bf16_f32 v25, v4, v5
	v_lshlrev_b32_e32 v8, 16, v22
	v_and_b32_e32 v9, 0xffff0000, v22
	v_lshlrev_b32_e32 v6, 16, v23
	v_and_b32_e32 v7, 0xffff0000, v23
	v_lshlrev_b32_e32 v4, 16, v24
	v_and_b32_e32 v5, 0xffff0000, v24
	v_lshlrev_b32_e32 v2, 16, v25
	v_and_b32_e32 v3, 0xffff0000, v25
	global_store_dwordx4 v[20:21], v[22:25], off offset:256 sc1
	s_cbranch_vccnz .LBB0_696
	ds_read_b128 v[20:23], v239 offset:1536
	ds_read_b128 v[24:27], v239 offset:1552
	s_waitcnt lgkmcnt(1)
	v_pk_mul_f32 v[22:23], v[6:7], v[22:23]
	v_pk_mul_f32 v[20:21], v[8:9], v[20:21]
	s_waitcnt lgkmcnt(0)
	v_pk_mul_f32 v[26:27], v[2:3], v[26:27]
	v_pk_mul_f32 v[24:25], v[4:5], v[24:25]
	v_cvt_pk_bf16_f32 v20, v20, v21
	v_cvt_pk_bf16_f32 v21, v22, v23
	s_nop 0
	v_cvt_pk_bf16_f32 v22, v24, v25
	v_cvt_pk_bf16_f32 v23, v26, v27
	global_store_dwordx4 v[18:19], v[20:23], off offset:256 sc1
